# all 14 seams XCD-local (runtime mapping check + fallback), batch-aligned mixer work mapping, batch-contiguous PROJ/YMIX scratch layout, plain loads in conf/mix2
# speedup vs baseline: 1.0154x; 1.0076x over previous
.LBB0_252:
	s_mov_b64 s[14:15], 0x80
	s_add_i32 m0, s31, 0x18000
	v_lshl_add_u64 v[6:7], v[6:7], 0, s[14:15]
	s_waitcnt vmcnt(2)
	s_barrier
	global_load_lds_dwordx4 v[6:7], off
	v_lshl_add_u64 v[6:7], v[8:9], 0, s[14:15]
	s_add_i32 m0, s31, 0x1a000
	s_add_i32 s37, s31, 0x8000
	global_load_lds_dwordx4 v[6:7], off
	v_lshl_add_u64 v[6:7], v[10:11], 0, s[14:15]
	s_mov_b32 m0, s37
	s_add_i32 s38, s31, 0xa000
	global_load_lds_dwordx4 v[6:7], off
	v_lshl_add_u64 v[6:7], v[12:13], 0, s[14:15]
	s_mov_b32 m0, s38
	s_mov_b64 s[16:17], 0x40080
	global_load_lds_dwordx4 v[6:7], off
	v_lshl_add_u64 v[6:7], v[2:3], 0, s[16:17]
	s_add_i32 m0, s31, 0x1c000
	v_lshl_add_u64 v[8:9], v[6:7], 0, v[134:135]
	global_load_lds_dwordx4 v[8:9], off
	v_lshl_add_u64 v[6:7], v[6:7], 0, v[140:141]
	s_add_i32 m0, s31, 0x1e000
	s_and_b32 s18, s2, 7
	s_lshl_b32 s18, s18, 23
	s_add_u32 s18, s18, 0xd000000
	s_mov_b32 s19, 0
	global_load_lds_dwordx4 v[6:7], off
	v_lshl_add_u64 v[142:143], v[4:5], 0, s[18:19]
	v_lshrrev_b32_e32 v5, 1, v14
	v_and_b32_e32 v5, 24, v5
	v_and_b32_e32 v4, 15, v14
	v_lshlrev_b32_e32 v6, 1, v5
	v_lshl_or_b32 v166, s9, 6, v4
	v_lshl_or_b32 v4, v4, 6, v6
	v_lshlrev_b32_e32 v6, 2, v14
	s_sext_i32_i8 s54, s7
	s_lshl_b32 s7, s9, 13
	v_and_b32_e32 v6, 32, v6
	v_bitop3_b32 v7, v4, s7, v6 bitop3:0xde
	s_lshl_b32 s7, s8, 5
	s_and_b32 s7, s7, 0x60
	s_lshl_b32 s8, s7, 7
	v_bitop3_b32 v167, v4, s8, v6 bitop3:0xde
	v_lshlrev_b32_e32 v4, 14, v18
	v_and_b32_e32 v4, 0xffff8000, v4
	v_or_b32_e32 v169, s7, v5
	v_lshl_add_u32 v4, v19, 11, v4
	v_and_b32_e32 v5, 1, v18
	v_lshl_or_b32 v4, v5, 6, v4
	v_lshl_add_u32 v144, v20, 1, v4
	v_lshlrev_b32_e32 v4, 14, v15
	v_and_b32_e32 v4, 0xffff8000, v4
	s_waitcnt vmcnt(6)
	s_cmpk_lt_u32 s6, 0x100
	v_lshl_add_u32 v4, v16, 11, v4
	v_and_b32_e32 v5, 1, v15
	s_cselect_b64 s[18:19], -1, 0
	s_add_i32 s6, 0, 0x21c00
	v_lshl_or_b32 v4, v5, 6, v4
	s_mov_b32 s22, 0xfffc0080
	s_mov_b32 s55, 0
	v_lshl_add_u32 v168, v166, 4, s6
	v_mov_b32_e32 v145, v135
	v_lshl_add_u32 v146, v17, 1, v4
	v_mov_b32_e32 v147, v135
	v_mov_b64_e32 v[148:149], 0x380
	v_mov_b64_e32 v[150:151], 0x37f
	s_movk_i32 s39, 0x71
	s_mov_b64 s[20:21], 0x100
	s_mov_b32 s23, -1
	s_add_i32 s42, 0, 0x10000
	s_add_i32 s43, 0, 0x14000
	v_add_u32_e32 v170, 0, v7
	s_add_i32 s44, s31, 0xc000
	s_add_i32 s45, s31, 0xe000
	s_movk_i32 s50, 0xe00
	v_mov_b32_e32 v171, 0x358637bd
	s_mov_b32 s51, 0x800000
	s_mov_b32 s52, 0
	s_barrier
	s_branch .LBB0_255

.LBB0_312:
	s_or_b64 exec, exec, s[50:51]
	v_mov_b32_e32 v0, v176
	s_and_b32 s3, s2, 7
	s_lshl_b32 s3, s3, 5
	s_lshr_b32 s98, s2, 3
	s_add_i32 s3, s3, s98
	s_mov_b32 s10, s68
	s_waitcnt lgkmcnt(0)
	s_barrier
	s_lshl_b32 s3, s3, 3
	v_readfirstlane_b32 s6, v0
	s_ashr_i32 s7, s6, 6
	s_add_i32 s3, s3, s7
	s_mov_b64 s[8:9], s[0:1]
	s_cmpk_gt_i32 s3, 0x7ff
	s_cbranch_scc1 .LBB0_321
	v_bfe_u32 v3, v0, 4, 2
	s_mulk_i32 s7, 0x4400
	v_lshlrev_b32_e32 v77, 2, v3
	v_and_b32_e32 v1, 63, v0
	s_add_i32 s7, s7, 0
	v_and_b32_e32 v72, 15, v0
	v_and_b32_e32 v0, 48, v0
	v_or_b32_e32 v102, 1, v77
	v_or_b32_e32 v104, 2, v77
	v_or_b32_e32 v106, 3, v77
	v_lshlrev_b32_e32 v2, 9, v3
	v_add_u32_e32 v76, s7, v0
	v_lshl_add_u32 v0, v3, 11, s7
	v_lshlrev_b32_e32 v3, 3, v72
	v_lshl_add_u32 v4, v102, 9, s7
	v_lshl_add_u32 v5, v104, 9, s7
	v_lshl_add_u32 v6, v106, 9, s7
	v_add_u32_e32 v79, v0, v3
	v_add_u32_e32 v103, v4, v3
	v_add_u32_e32 v105, v5, v3
	v_add_u32_e32 v107, v6, v3
	v_or_b32_e32 v7, 0x80, v3
	v_or_b32_e32 v3, 0x100, v3
	s_bfe_u32 s6, s6, 0x20006
	s_lshl_b32 s20, s10, 3
	v_add_u32_e32 v112, v0, v3
	v_add_u32_e32 v113, v4, v3
	v_add_u32_e32 v114, v5, v3
	v_add_u32_e32 v115, v6, v3
	v_or_b32_e32 v3, 48, v1
	s_lshl_b32 s10, s6, 6
	v_lshl_add_u32 v73, v1, 1, s7
	v_add_u32_e32 v108, v0, v7
	v_add_u32_e32 v109, v4, v7
	v_add_u32_e32 v110, v5, v7
	v_add_u32_e32 v111, v6, v7
	v_lshlrev_b32_e32 v7, 3, v3
	v_or_b32_e32 v78, s10, v1
	v_lshl_add_u32 v1, v1, 3, s7
	v_mov_b32_e32 v75, 0
	v_add_u32_e32 v116, v0, v7
	s_lshl_b32 s6, s6, 12
	v_or_b32_e32 v0, s10, v72
	v_add_u32_e32 v122, 0x2400, v1
	v_mov_b32_e32 v1, 0x18000800
	s_mov_b32 s11, 0
	v_add_u32_e32 v117, v4, v7
	v_add_u32_e32 v118, v5, v7
	v_add_u32_e32 v119, v6, v7
	v_lshl_add_u32 v120, v72, 1, s7
	v_lshl_add_u32 v121, v3, 1, s7
	v_lshlrev_b32_e32 v80, 3, v78
	v_mov_b32_e32 v81, v75
	v_lshl_or_b32 v82, v78, 2, v1
	v_mov_b32_e32 v83, v75
	v_mov_b64_e32 v[84:85], s[8:9]
	v_lshlrev_b32_e32 v86, 2, v78
	v_mov_b32_e32 v87, v75
	s_and_b32 s12, s2, 7
	s_lshl_b32 s12, s12, 23
	s_add_u32 s12, s12, 0xd000000
	s_mov_b32 s13, 0
	s_lshl_b32 s10, s6, 2
	v_lshlrev_b32_e32 v88, 2, v2
	v_lshlrev_b32_e32 v90, 2, v72
	s_movk_i32 s21, 0x2000
	s_movk_i32 s22, 0x1000
	s_movk_i32 s23, 0x3000
	s_movk_i32 s26, 0x4000
	s_movk_i32 s27, 0x5000
	s_movk_i32 s28, 0x6000
	s_movk_i32 s29, 0x7000
	s_mov_b32 s30, 0x8000
	s_mov_b32 s31, 0x9000
	s_mov_b32 s34, 0xa000
	s_mov_b32 s35, 0xb000
	s_mov_b32 s36, 0xc000
	s_mov_b32 s37, 0xd000
	s_mov_b32 s38, 0xe000
	s_mov_b32 s39, 0xf000
	s_mov_b32 s42, 0x10000
	s_mov_b32 s43, 0x11000
	s_mov_b32 s44, 0x12000
	s_mov_b32 s45, 0x13000
	s_mov_b32 s50, 0x14000
	s_mov_b32 s51, 0x15000
	s_mov_b32 s52, 0x16000
	s_mov_b32 s53, 0x17000
	s_mov_b32 s54, 0x18000
	s_mov_b32 s55, 0x19000
	s_mov_b32 s56, 0x1a000
	s_mov_b32 s57, 0x1b000
	s_mov_b32 s58, 0x1c000
	s_mov_b32 s59, 0x1d000
	s_mov_b32 s60, 0x1e000
	s_mov_b32 s61, 0x1f000
	s_mov_b32 s62, 0x20000
	s_mov_b32 s63, 0x21000
	s_mov_b32 s64, 0x22000
	s_mov_b32 s65, 0x23000
	s_mov_b32 s66, 0x24000
	s_mov_b32 s67, 0x25000
	s_mov_b32 s70, 0x26000
	s_mov_b32 s71, 0x27000
	s_mov_b32 s72, 0x28000
	s_mov_b32 s73, 0x29000
	s_mov_b32 s74, 0x2a000
	s_mov_b32 s75, 0x2b000
	s_mov_b32 s76, 0x2c000
	s_mov_b32 s77, 0x2d000
	s_mov_b32 s78, 0x2e000
	s_mov_b32 s79, 0x2f000
	s_mov_b32 s80, 0x30000
	s_mov_b32 s81, 0x31000
	s_mov_b32 s82, 0x32000
	s_mov_b32 s83, 0x33000
	s_mov_b32 s84, 0x34000
	s_mov_b32 s85, 0x35000
	s_mov_b32 s86, 0x36000
	s_mov_b32 s87, 0x37000
	v_lshlrev_b32_e32 v92, 2, v0
	s_mov_b32 s88, 0x3f2aaaab
	v_mov_b32_e32 v123, 0x3ecc95a3
	s_mov_b32 s89, 0x3f317218
	s_mov_b32 s90, 0x7f800000
	s_mov_b32 s91, 0x33800000
	s_movk_i32 s92, 0x90
	s_mov_b32 s93, 0xf800000
	v_mov_b32_e32 v124, 0x260
	s_mov_b64 s[14:15], 0x1000
	s_mov_b64 s[16:17], 0x4000
	v_mov_b32_e32 v125, 0xe00
	v_mov_b32_e32 v126, 0x7f800000
	v_mov_b32_e32 v127, 0x7fc00000
	v_mov_b32_e32 v128, 0xff800000

.LBB0_321:
	v_mov_b32_e32 v0, v176
	s_and_b32 s3, s2, 7
	s_lshl_b32 s3, s3, 6
	s_lshr_b32 s98, s2, 3
	s_add_i32 s3, s3, s98
	s_add_i32 s99, s3, 32
	s_mov_b32 s42, 32
	s_mov_b64 s[22:23], s[0:1]
	s_barrier
	s_load_dwordx2 s[86:87], s[0:1], 0xe0
	v_readfirstlane_b32 s6, v0
	s_cmpk_gt_i32 s3, 0x1ff
	v_mbcnt_lo_u32_b32 v216, -1, 0
	s_cbranch_scc1 .LBB0_334
	v_mbcnt_hi_u32_b32 v10, -1, v216
	v_and_b32_e32 v12, 64, v10
	v_xor_b32_e32 v11, 16, v10
	v_add_u32_e32 v12, 64, v12
	v_cmp_lt_i32_e32 vcc, v11, v12
	v_and_b32_e32 v1, 7, v0
	v_add_u32_e32 v6, 0x400, v0
	v_cndmask_b32_e32 v11, v10, v11, vcc
	s_ashr_i32 s26, s6, 6
	v_lshl_add_u32 v3, v1, 4, 0
	s_movk_i32 s6, 0x1070
	v_add_u32_e32 v5, 0x200, v0
	v_ashrrev_i32_e32 v90, 3, v6
	v_add_u32_e32 v6, 0x600, v0
	v_lshlrev_b32_e32 v111, 2, v11
	v_xor_b32_e32 v11, 32, v10
	v_mad_u32_u24 v4, v1, s6, v3
	v_ashrrev_i32_e32 v86, 3, v0
	v_ashrrev_i32_e32 v88, 3, v5
	v_ashrrev_i32_e32 v92, 3, v6
	v_bfe_u32 v6, v0, 4, 2
	v_cmp_lt_i32_e32 vcc, v11, v12
	v_lshl_add_u32 v85, v86, 1, v4
	v_lshl_add_u32 v108, v88, 1, v4
	v_lshl_add_u32 v109, v90, 1, v4
	v_lshl_add_u32 v110, v92, 1, v4
	v_lshlrev_b32_e32 v4, 3, v6
	v_lshlrev_b32_e32 v6, 2, v6
	v_cndmask_b32_e32 v10, v10, v11, vcc
	s_and_b32 s43, s26, 3
	s_lshl_b32 s14, s26, 4
	v_and_b32_e32 v9, 15, v0
	v_lshlrev_b32_e32 v112, 2, v10
	v_or_b32_e32 v10, 2, v6
	s_lshr_b32 s26, s26, 2
	v_cmp_gt_u32_e64 s[18:19], v10, v9
	v_or_b32_e32 v10, 3, v6
	s_lshl_b32 s29, s26, 7
	v_cmp_gt_u32_e64 s[20:21], v10, v9
	v_and_or_b32 v10, v0, 63, 48
	s_movk_i32 s30, 0x210
	v_mov_b32_e32 v11, s29
	v_mad_u32_u24 v10, v10, s30, v11
	v_add3_u32 v10, v10, v4, 0
	v_add_u32_e32 v113, 0x9000, v10
	v_mad_u32_u24 v10, v9, s30, v11
	v_add3_u32 v10, v10, v4, 0
	s_lshl_b32 s44, s26, 6
	s_mulk_i32 s26, 0x2400
	s_movk_i32 s28, 0x90
	s_andn2_b32 s14, s14, 63
	v_add_u32_e32 v114, 0x9000, v10
	v_mov_b32_e32 v10, s26
	v_lshlrev_b32_e32 v84, 3, v1
	s_movk_i32 s12, 0x7f
	v_mul_lo_u32 v1, v86, s28
	v_mul_lo_u32 v5, v88, s28
	v_mul_lo_u32 v7, v90, s28
	v_mul_lo_u32 v8, v92, s28
	s_ashr_i32 s15, s14, 31
	v_mad_u32_u24 v10, v9, s28, v10
	v_and_b32_e32 v0, 48, v0
	s_mov_b32 s27, 0
	v_mov_b32_e32 v2, 0
	v_cmp_lt_i32_e64 s[6:7], s12, v86
	v_ashrrev_i32_e32 v87, 31, v86
	v_cmp_lt_i32_e64 s[8:9], s12, v88
	v_ashrrev_i32_e32 v89, 31, v88
	v_cmp_lt_i32_e64 s[10:11], s12, v90
	v_ashrrev_i32_e32 v91, 31, v90
	v_cmp_lt_i32_e64 s[12:13], s12, v92
	v_ashrrev_i32_e32 v93, 31, v92
	v_or_b32_e32 v94, s14, v9
	v_mov_b32_e32 v95, s15
	v_cmp_gt_u32_e64 s[14:15], v6, v9
	v_cmp_lt_u32_e64 s[16:17], v6, v9
	v_add3_u32 v115, v10, v0, 0
	v_or_b32_e32 v116, s44, v9
	v_mov_b64_e32 v[96:97], s[22:23]
	s_and_b32 s28, s2, 7
	s_lshl_b32 s28, s28, 23
	s_add_u32 s28, s28, 0xd000000
	s_mov_b32 s29, 0
	s_movk_i32 s45, 0xe00
	v_add_u32_e32 v117, v3, v1
	v_add_u32_e32 v118, v3, v5
	v_add_u32_e32 v119, v3, v7
	v_add_u32_e32 v120, v3, v8
	v_lshlrev_b32_e32 v98, 1, v4
	s_mov_b32 s50, 0xf149f2ca
	v_lshlrev_b32_e32 v100, 1, v6
	s_mov_b64 s[30:31], 0x9000200
	s_mov_b32 s51, 0x9000000
	v_mov_b32_e32 v121, 0xf149f2ca

.LBB0_332:
	ds_read_b128 v[16:19], v125
	s_nop 0
	ds_read_b128 v[12:15], v125 offset:64
	ds_read_b128 v[20:23], v125 offset:2304
	ds_read_b128 v[36:39], v125 offset:4608
	s_add_i32 s54, s44, s52
	s_add_i32 s53, s52, 16
	s_cmp_lg_u32 s52, 48
	s_cselect_b32 s26, s53, 48
	v_add_u32_e32 v0, s52, v116
	s_waitcnt vmcnt(1) lgkmcnt(3)
	v_mfma_f32_16x16x32_bf16 v[32:35], v[16:19], v[8:11], 0
	ds_read_b128 v[24:27], v125 offset:2368
	ds_read_b128 v[16:19], v125 offset:4672
	ds_read_b128 v[40:43], v125 offset:6912
	v_ashrrev_i32_e32 v1, 31, v0
	v_lshl_add_u64 v[0:1], s[34:35], 0, v[0:1]
	s_waitcnt lgkmcnt(4)
	v_mfma_f32_16x16x32_bf16 v[44:47], v[20:23], v[8:11], 0
	ds_read_b128 v[20:23], v125 offset:6976
	ds_read_b128 v[52:55], v125 offset:9216
	ds_read_b128 v[28:31], v125 offset:9280
	v_lshlrev_b64 v[0:1], 11, v[0:1]
	v_lshl_add_u64 v[0:1], v[102:103], 0, v[0:1]
	s_waitcnt lgkmcnt(6)
	v_mfma_f32_16x16x32_bf16 v[56:59], v[36:39], v[8:11], 0
	ds_read_b128 v[80:83], v125 offset:11520
	ds_read_b128 v[36:39], v125 offset:11584
	ds_read_b128 v[76:79], v125 offset:13824
	v_mov_b32_e32 v101, v2
	v_lshl_add_u64 v[0:1], v[0:1], 0, s[38:39]
	s_waitcnt lgkmcnt(6)
	v_mfma_f32_16x16x32_bf16 v[60:63], v[40:43], v[8:11], 0
	ds_read_b128 v[40:43], v125 offset:13888
	ds_read_b128 v[72:75], v125 offset:16128
	ds_read_b128 v[48:51], v125 offset:16192
	s_add_i32 s55, s54, 16
	s_add_i32 s58, s54, 32
	s_waitcnt lgkmcnt(7)
	v_mfma_f32_16x16x32_bf16 v[64:67], v[52:55], v[8:11], 0
	ds_read_b128 v[68:71], v125 offset:18432
	ds_read_b128 v[52:55], v125 offset:18496
	s_add_i32 s59, s54, 48
	s_add_i32 s60, s54, 64
	s_waitcnt lgkmcnt(7)
	v_mfma_f32_16x16x32_bf16 v[126:129], v[80:83], v[8:11], 0
	s_add_i32 s61, s54, 0x50
	s_add_i32 s62, s54, 0x60
	s_add_i32 s63, s54, 0x70
	s_waitcnt lgkmcnt(5)
	v_mfma_f32_16x16x32_bf16 v[76:79], v[76:79], v[8:11], 0
	v_lshl_add_u64 v[0:1], v[0:1], 0, v[100:101]
	s_cmpk_lt_i32 s54, 0x80
	v_add_u32_e32 v124, 0x900, v125
	s_waitcnt lgkmcnt(3)
	v_mfma_f32_16x16x32_bf16 v[72:75], v[72:75], v[8:11], 0
	v_mov_b32_e32 v125, v124
	v_mov_b32_e32 v3, v2
	v_add_u32_e32 v81, 0x2000, v99
	s_waitcnt lgkmcnt(1)
	v_mfma_f32_16x16x32_bf16 v[68:71], v[68:71], v[8:11], 0
	v_lshl_add_u64 v[8:9], v[104:105], 0, s[26:27]
	v_add_u32_e32 v82, 0x4000, v99
	v_add_u32_e32 v80, 32, v99
	s_waitcnt vmcnt(0)
	v_mfma_f32_16x16x32_bf16 v[32:35], v[12:15], v[4:7], v[32:35]
	v_mad_u64_u32 v[12:13], s[22:23], v8, s45, v[106:107]
	v_mov_b32_e32 v8, v13
	v_mad_u64_u32 v[8:9], s[56:57], v9, s45, v[8:9]
	v_mov_b32_e32 v13, v8
	global_load_dwordx4 v[8:11], v[12:13], off offset:1024
	s_nop 0
	global_load_dwordx4 v[12:15], v[12:13], off offset:1088
	v_mfma_f32_16x16x32_bf16 v[24:27], v[24:27], v[4:7], v[44:47]
	s_cselect_b64 s[22:23], -1, 0
	v_add_u32_e32 v83, 32, v123
	s_mov_b32 s52, s53
	v_mfma_f32_16x16x32_bf16 v[44:47], v[16:19], v[4:7], v[56:59]
	v_add_co_u32_e32 v18, vcc, s51, v0
	v_lshl_add_u64 v[16:17], v[0:1], 0, s[30:31]
	s_nop 0
	v_addc_co_u32_e32 v19, vcc, 0, v1, vcc
	s_and_b64 vcc, s[36:37], s[22:23]
	s_or_b64 s[22:23], s[16:17], vcc
	v_mul_f32_e32 v1, 0x3e000000, v33
	s_cmpk_lt_i32 s55, 0x80
	v_mul_f32_e32 v0, 0x3e000000, v32
	v_mul_f32_e32 v32, 0x3e000000, v34
	v_mul_f32_e32 v33, 0x3e000000, v35
	v_cndmask_b32_e64 v1, v1, v121, s[22:23]
	s_cselect_b64 s[22:23], -1, 0
	v_cndmask_b32_e32 v0, v0, v121, vcc
	v_cndmask_b32_e32 v32, v32, v121, vcc
	v_cndmask_b32_e32 v33, v33, v121, vcc
	s_and_b64 vcc, s[36:37], s[22:23]
	s_cmpk_lt_i32 s58, 0x80
	v_mul_f32_e32 v24, 0x3e000000, v24
	v_mul_f32_e32 v25, 0x3e000000, v25
	v_mul_f32_e32 v26, 0x3e000000, v26
	v_mul_f32_e32 v27, 0x3e000000, v27
	s_cselect_b64 s[22:23], -1, 0
	v_cndmask_b32_e32 v24, v24, v121, vcc
	v_cndmask_b32_e32 v25, v25, v121, vcc
	v_cndmask_b32_e32 v26, v26, v121, vcc
	v_cndmask_b32_e32 v27, v27, v121, vcc
	s_and_b64 vcc, s[36:37], s[22:23]
	v_mfma_f32_16x16x32_bf16 v[20:23], v[20:23], v[4:7], v[60:63]
	s_cmpk_lt_i32 s59, 0x80
	v_mul_f32_e32 v34, 0x3e000000, v44
	v_mul_f32_e32 v35, 0x3e000000, v45
	v_mfma_f32_16x16x32_bf16 v[48:51], v[48:51], v[4:7], v[72:75]
	v_mul_f32_e32 v44, 0x3e000000, v46
	v_mul_f32_e32 v45, 0x3e000000, v47
	s_cselect_b64 s[22:23], -1, 0
	v_cndmask_b32_e32 v34, v34, v121, vcc
	v_cndmask_b32_e32 v35, v35, v121, vcc
	v_cndmask_b32_e32 v44, v44, v121, vcc
	v_cndmask_b32_e32 v45, v45, v121, vcc
	s_and_b64 vcc, s[36:37], s[22:23]
	v_mfma_f32_16x16x32_bf16 v[28:31], v[28:31], v[4:7], v[64:67]
	v_cndmask_b32_e64 v0, v121, v0, s[14:15]
	s_cmpk_lt_i32 s60, 0x80
	v_mul_f32_e32 v20, 0x3e000000, v20
	v_mul_f32_e32 v21, 0x3e000000, v21
	v_mul_f32_e32 v22, 0x3e000000, v22
	v_mul_f32_e32 v23, 0x3e000000, v23
	v_mul_f32_e32 v46, 0x3e000000, v48
	v_mul_f32_e32 v48, 0x3e000000, v50
	v_cndmask_b32_e64 v32, v121, v32, s[18:19]
	v_cndmask_b32_e64 v33, v121, v33, s[20:21]
	v_max3_f32 v50, v0, s50, v1
	s_cselect_b64 s[22:23], -1, 0
	v_max3_f32 v50, v50, v32, v33
	v_cndmask_b32_e32 v20, v20, v121, vcc
	v_cndmask_b32_e32 v21, v21, v121, vcc
	v_cndmask_b32_e32 v22, v22, v121, vcc
	v_cndmask_b32_e32 v23, v23, v121, vcc
	s_and_b64 vcc, s[36:37], s[22:23]
	v_mfma_f32_16x16x32_bf16 v[36:39], v[36:39], v[4:7], v[126:129]
	v_max3_f32 v50, v50, v24, v25
	s_cmpk_lt_i32 s61, 0x80
	v_mul_f32_e32 v28, 0x3e000000, v28
	v_mul_f32_e32 v29, 0x3e000000, v29
	v_mul_f32_e32 v30, 0x3e000000, v30
	v_mul_f32_e32 v31, 0x3e000000, v31
	v_max3_f32 v50, v50, v26, v27
	s_cselect_b64 s[22:23], -1, 0
	v_max3_f32 v50, v50, v34, v35
	v_cndmask_b32_e32 v28, v28, v121, vcc
	v_cndmask_b32_e32 v29, v29, v121, vcc
	v_cndmask_b32_e32 v30, v30, v121, vcc
	v_cndmask_b32_e32 v31, v31, v121, vcc
	s_and_b64 vcc, s[36:37], s[22:23]
	v_mfma_f32_16x16x32_bf16 v[40:43], v[40:43], v[4:7], v[76:79]
	v_max3_f32 v50, v50, v44, v45
	s_cmpk_lt_i32 s62, 0x80
	v_mul_f32_e32 v36, 0x3e000000, v36
	v_mul_f32_e32 v37, 0x3e000000, v37
	v_mul_f32_e32 v38, 0x3e000000, v38
	v_mul_f32_e32 v39, 0x3e000000, v39
	v_max3_f32 v50, v50, v20, v21
	s_cselect_b64 s[22:23], -1, 0
	v_max3_f32 v50, v50, v22, v23
	v_cndmask_b32_e32 v36, v36, v121, vcc
	v_cndmask_b32_e32 v37, v37, v121, vcc
	v_cndmask_b32_e32 v38, v38, v121, vcc
	v_cndmask_b32_e32 v39, v39, v121, vcc
	s_and_b64 vcc, s[36:37], s[22:23]
	v_max3_f32 v50, v50, v28, v29
	s_cmpk_lt_i32 s63, 0x80
	s_waitcnt lgkmcnt(0)
	v_mfma_f32_16x16x32_bf16 v[4:7], v[52:55], v[4:7], v[68:71]
	v_mul_f32_e32 v40, 0x3e000000, v40
	v_mul_f32_e32 v41, 0x3e000000, v41
	v_mul_f32_e32 v42, 0x3e000000, v42
	v_mul_f32_e32 v43, 0x3e000000, v43
	v_max3_f32 v50, v50, v30, v31
	s_cselect_b64 s[22:23], -1, 0
	v_max3_f32 v50, v50, v36, v37
	v_cndmask_b32_e32 v40, v40, v121, vcc
	v_cndmask_b32_e32 v41, v41, v121, vcc
	v_cndmask_b32_e32 v42, v42, v121, vcc
	v_cndmask_b32_e32 v43, v43, v121, vcc
	s_and_b64 vcc, s[36:37], s[22:23]
	v_max3_f32 v50, v50, v38, v39
	s_cmp_gt_u32 s54, 0x7fffff7f
	v_mul_f32_e32 v47, 0x3e000000, v49
	v_mul_f32_e32 v49, 0x3e000000, v51
	v_max3_f32 v50, v50, v40, v41
	s_cselect_b64 s[22:23], -1, 0
	v_mul_f32_e32 v5, 0x3e000000, v5
	v_max3_f32 v50, v50, v42, v43
	v_cndmask_b32_e32 v46, v46, v121, vcc
	v_cndmask_b32_e32 v47, v47, v121, vcc
	v_cndmask_b32_e32 v48, v48, v121, vcc
	v_cndmask_b32_e32 v49, v49, v121, vcc
	s_and_b64 vcc, s[36:37], s[22:23]
	v_mul_f32_e32 v4, 0x3e000000, v4
	v_max3_f32 v50, v50, v46, v47
	v_cndmask_b32_e32 v5, v5, v121, vcc
	s_or_b64 s[22:23], s[14:15], vcc
	v_mul_f32_e32 v6, 0x3e000000, v6
	v_mul_f32_e32 v7, 0x3e000000, v7
	v_max3_f32 v50, v50, v48, v49
	v_cndmask_b32_e64 v4, v4, v121, s[22:23]
	v_cndmask_b32_e64 v5, v121, v5, s[16:17]
	s_or_b64 s[22:23], s[18:19], vcc
	s_or_b64 vcc, s[20:21], vcc
	v_cndmask_b32_e64 v6, v6, v121, s[22:23]
	v_cndmask_b32_e32 v7, v7, v121, vcc
	v_max3_f32 v50, v50, v4, v5
	v_max3_f32 v50, v50, v6, v7
	ds_bpermute_b32 v51, v111, v50
	s_cmp_lg_u32 s53, 64
	s_waitcnt lgkmcnt(0)
	v_max_f32_e32 v51, v51, v51
	v_max_f32_e32 v50, v50, v51
	ds_bpermute_b32 v51, v112, v50
	s_waitcnt lgkmcnt(0)
	v_max3_f32 v50, v50, v51, v122
	v_sub_f32_e32 v0, v0, v50
	v_sub_f32_e32 v1, v1, v50
	v_mul_f32_e32 v0, 0x3fb8aa3b, v0
	v_sub_f32_e32 v32, v32, v50
	v_mul_f32_e32 v1, 0x3fb8aa3b, v1
	v_exp_f32_e32 v0, v0
	v_sub_f32_e32 v33, v33, v50
	v_mul_f32_e32 v32, 0x3fb8aa3b, v32
	v_exp_f32_e32 v51, v1
	v_sub_f32_e32 v24, v24, v50
	v_sub_f32_e32 v25, v25, v50
	v_sub_f32_e32 v26, v26, v50
	v_sub_f32_e32 v27, v27, v50
	v_sub_f32_e32 v34, v34, v50
	v_sub_f32_e32 v35, v35, v50
	v_sub_f32_e32 v44, v44, v50
	v_sub_f32_e32 v45, v45, v50
	v_sub_f32_e32 v20, v20, v50
	v_sub_f32_e32 v21, v21, v50
	v_sub_f32_e32 v22, v22, v50
	v_sub_f32_e32 v23, v23, v50
	v_sub_f32_e32 v28, v28, v50
	v_sub_f32_e32 v29, v29, v50
	v_sub_f32_e32 v30, v30, v50
	v_sub_f32_e32 v31, v31, v50
	v_sub_f32_e32 v36, v36, v50
	v_sub_f32_e32 v37, v37, v50
	v_sub_f32_e32 v38, v38, v50
	v_sub_f32_e32 v39, v39, v50
	v_sub_f32_e32 v40, v40, v50
	v_sub_f32_e32 v41, v41, v50
	v_sub_f32_e32 v42, v42, v50
	v_sub_f32_e32 v43, v43, v50
	v_sub_f32_e32 v46, v46, v50
	v_sub_f32_e32 v47, v47, v50
	v_sub_f32_e32 v48, v48, v50
	v_sub_f32_e32 v49, v49, v50
	v_sub_f32_e32 v4, v4, v50
	v_sub_f32_e32 v5, v5, v50
	v_sub_f32_e32 v6, v6, v50
	v_sub_f32_e32 v7, v7, v50
	v_sub_f32_e32 v50, v122, v50
	v_mul_f32_e32 v33, 0x3fb8aa3b, v33
	v_exp_f32_e32 v52, v32
	v_mul_f32_e32 v24, 0x3fb8aa3b, v24
	v_mul_f32_e32 v50, 0x3fb8aa3b, v50
	v_exp_f32_e32 v53, v33
	v_mul_f32_e32 v25, 0x3fb8aa3b, v25
	v_exp_f32_e32 v54, v24
	v_exp_f32_e32 v130, v50
	v_add_f32_e32 v50, 0, v0
	v_mul_f32_e32 v26, 0x3fb8aa3b, v26
	v_exp_f32_e32 v55, v25
	v_add_f32_e32 v50, v51, v50
	v_mul_f32_e32 v27, 0x3fb8aa3b, v27
	v_exp_f32_e32 v56, v26
	v_add_f32_e32 v50, v52, v50
	v_mul_f32_e32 v34, 0x3fb8aa3b, v34
	v_exp_f32_e32 v57, v27
	v_add_f32_e32 v50, v53, v50
	v_mul_f32_e32 v35, 0x3fb8aa3b, v35
	v_mul_f32_e32 v20, 0x3fb8aa3b, v20
	v_mul_f32_e32 v21, 0x3fb8aa3b, v21
	v_exp_f32_e32 v58, v34
	v_add_f32_e32 v50, v54, v50
	v_mul_f32_e32 v44, 0x3fb8aa3b, v44
	v_exp_f32_e32 v59, v35
	v_exp_f32_e32 v62, v20
	v_exp_f32_e32 v63, v21
	v_cvt_pk_bf16_f32 v20, v0, v51
	v_cvt_pk_bf16_f32 v21, v52, v53
	v_add_f32_e32 v52, v55, v50
	v_mul_f32_e32 v45, 0x3fb8aa3b, v45
	v_exp_f32_e32 v60, v44
	v_add_f32_e32 v52, v56, v52
	v_exp_f32_e32 v61, v45
	v_add_f32_e32 v52, v57, v52
	v_mul_f32_e32 v22, 0x3fb8aa3b, v22
	v_mul_f32_e32 v23, 0x3fb8aa3b, v23
	v_mul_f32_e32 v28, 0x3fb8aa3b, v28
	v_mul_f32_e32 v29, 0x3fb8aa3b, v29
	v_mul_f32_e32 v30, 0x3fb8aa3b, v30
	v_mul_f32_e32 v31, 0x3fb8aa3b, v31
	v_mul_f32_e32 v36, 0x3fb8aa3b, v36
	v_mul_f32_e32 v37, 0x3fb8aa3b, v37
	v_mul_f32_e32 v38, 0x3fb8aa3b, v38
	v_mul_f32_e32 v39, 0x3fb8aa3b, v39
	v_mul_f32_e32 v40, 0x3fb8aa3b, v40
	v_mul_f32_e32 v41, 0x3fb8aa3b, v41
	v_mul_f32_e32 v42, 0x3fb8aa3b, v42
	v_mul_f32_e32 v43, 0x3fb8aa3b, v43
	v_mul_f32_e32 v46, 0x3fb8aa3b, v46
	v_mul_f32_e32 v47, 0x3fb8aa3b, v47
	v_mul_f32_e32 v48, 0x3fb8aa3b, v48
	v_mul_f32_e32 v49, 0x3fb8aa3b, v49
	v_mul_f32_e32 v4, 0x3fb8aa3b, v4
	v_mul_f32_e32 v5, 0x3fb8aa3b, v5
	v_mul_f32_e32 v6, 0x3fb8aa3b, v6
	v_mul_f32_e32 v7, 0x3fb8aa3b, v7
	v_add_f32_e32 v52, v58, v52
	v_exp_f32_e32 v64, v22
	v_exp_f32_e32 v65, v23
	v_exp_f32_e32 v66, v28
	v_exp_f32_e32 v67, v29
	v_exp_f32_e32 v68, v30
	v_exp_f32_e32 v69, v31
	v_exp_f32_e32 v70, v36
	v_exp_f32_e32 v71, v37
	v_exp_f32_e32 v72, v38
	v_exp_f32_e32 v73, v39
	v_exp_f32_e32 v74, v40
	v_exp_f32_e32 v75, v41
	v_exp_f32_e32 v76, v42
	v_exp_f32_e32 v77, v43
	v_exp_f32_e32 v78, v46
	v_exp_f32_e32 v79, v47
	v_exp_f32_e32 v101, v48
	v_exp_f32_e32 v124, v49
	v_exp_f32_e32 v126, v4
	v_exp_f32_e32 v127, v5
	v_exp_f32_e32 v128, v6
	v_exp_f32_e32 v129, v7
	v_cvt_pk_bf16_f32 v22, v54, v55
	v_cvt_pk_bf16_f32 v23, v56, v57
	v_cvt_pk_bf16_f32 v24, v58, v59
	v_cvt_pk_bf16_f32 v25, v60, v61
	v_cvt_pk_bf16_f32 v26, v62, v63
	v_cvt_pk_bf16_f32 v27, v64, v65
	v_cvt_pk_bf16_f32 v28, v66, v67
	v_cvt_pk_bf16_f32 v29, v68, v69
	v_cvt_pk_bf16_f32 v30, v70, v71
	v_cvt_pk_bf16_f32 v31, v72, v73
	v_cvt_pk_bf16_f32 v32, v74, v75
	v_cvt_pk_bf16_f32 v33, v76, v77
	v_cvt_pk_bf16_f32 v34, v78, v79
	v_cvt_pk_bf16_f32 v35, v101, v124
	v_cvt_pk_bf16_f32 v0, v126, v127
	v_cvt_pk_bf16_f32 v1, v128, v129
	ds_read2_b64 v[4:7], v99 offset1:4
	ds_read2_b64 v[36:39], v99 offset0:8 offset1:12
	ds_read2_b64 v[40:43], v99 offset0:16 offset1:20
	ds_read2_b64 v[44:47], v99 offset0:24 offset1:28
	ds_read_b64 v[48:49], v99 offset:256
	v_add_f32_e32 v52, v59, v52
	s_waitcnt lgkmcnt(4)
	v_mfma_f32_16x16x32_bf16 v[4:7], v[4:7], v[20:23], 0
	v_add_f32_e32 v52, v60, v52
	v_add_f32_e32 v52, v61, v52
	v_add_f32_e32 v52, v62, v52
	v_add_f32_e32 v52, v63, v52
	s_waitcnt lgkmcnt(3)
	v_mfma_f32_16x16x32_bf16 v[4:7], v[36:39], v[24:27], v[4:7]
	v_add_f32_e32 v36, v64, v52
	v_add_f32_e32 v36, v65, v36
	v_add_f32_e32 v36, v66, v36
	v_add_f32_e32 v36, v67, v36
	s_waitcnt lgkmcnt(2)
	v_mfma_f32_16x16x32_bf16 v[4:7], v[40:43], v[28:31], v[4:7]
	v_add_f32_e32 v36, v68, v36
	v_add_f32_e32 v36, v69, v36
	v_add_f32_e32 v36, v70, v36
	s_waitcnt lgkmcnt(0)
	v_mov_b32_e32 v50, v48
	v_mov_b32_e32 v51, v49
	v_add_f32_e32 v40, v71, v36
	v_mfma_f32_16x16x32_bf16 v[36:39], v[44:47], v[32:35], v[4:7]
	s_nop 2
	v_add_f32_e32 v4, v72, v40
	v_add_f32_e32 v40, v73, v4
	s_waitcnt vmcnt(0)
	v_mov_b64_e32 v[4:5], v[12:13]
	v_mov_b64_e32 v[6:7], v[14:15]
	v_add_f32_e32 v12, v74, v40
	v_add_f32_e32 v40, v75, v12
	v_mfma_f32_16x16x32_bf16 v[12:15], v[48:51], v[0:3], v[36:39]
	s_nop 2
	v_add_f32_e32 v36, v76, v40
	v_add_f32_e32 v36, v77, v36
	v_add_f32_e32 v36, v78, v36
	v_add_f32_e32 v36, v79, v36
	v_add_f32_e32 v36, v101, v36
	v_add_f32_e32 v36, v124, v36
	v_add_f32_e32 v36, v126, v36
	v_add_f32_e32 v36, v127, v36
	v_add_f32_e32 v36, v128, v36
	v_add_f32_e32 v36, v129, v36
	ds_bpermute_b32 v37, v111, v36
	s_waitcnt lgkmcnt(0)
	v_add_f32_e32 v36, v36, v37
	ds_bpermute_b32 v37, v112, v36
	s_waitcnt lgkmcnt(0)
	v_add_f32_e32 v36, v36, v37
	v_add_f32_e32 v36, v130, v36
	v_div_scale_f32 v37, s[22:23], v36, v36, 1.0
	v_rcp_f32_e32 v39, v37
	v_div_scale_f32 v38, vcc, 1.0, v36, 1.0
	v_fma_f32 v40, -v37, v39, 1.0
	v_fmac_f32_e32 v39, v40, v39
	v_mul_f32_e32 v40, v38, v39
	v_fma_f32 v41, -v37, v40, v38
	v_fmac_f32_e32 v40, v41, v39
	v_fma_f32 v37, -v37, v40, v38
	v_div_fmas_f32 v37, v37, v39, v40
	v_div_fixup_f32 v48, v37, v36, 1.0
	v_mul_f32_e32 v12, v12, v48
	v_mul_f32_e32 v13, v13, v48
	v_mul_f32_e32 v14, v14, v48
	v_mul_f32_e32 v15, v15, v48
	v_cvt_pk_bf16_f32 v44, v12, v13
	v_cvt_pk_bf16_f32 v45, v14, v15
	ds_read2_b64 v[12:15], v81 offset0:32 offset1:36
	ds_read2_b64 v[36:39], v81 offset0:40 offset1:44
	s_waitcnt lgkmcnt(1)
	v_mfma_f32_16x16x32_bf16 v[12:15], v[12:15], v[20:23], 0
	s_waitcnt lgkmcnt(0)
	v_mfma_f32_16x16x32_bf16 v[12:15], v[36:39], v[24:27], v[12:15]
	ds_read2_b64 v[36:39], v81 offset0:48 offset1:52
	ds_read2_b64 v[40:43], v81 offset0:56 offset1:60
	global_store_dwordx2 v[18:19], v[44:45], off offset:512 nt
	s_waitcnt lgkmcnt(1)
	v_mfma_f32_16x16x32_bf16 v[12:15], v[36:39], v[28:31], v[12:15]
	ds_read_b64 v[36:37], v99 offset:8704
	s_waitcnt lgkmcnt(0)
	v_mov_b32_e32 v38, v36
	v_mov_b32_e32 v39, v37
	v_mfma_f32_16x16x32_bf16 v[12:15], v[40:43], v[32:35], v[12:15]
	s_nop 0
	v_mfma_f32_16x16x32_bf16 v[12:15], v[36:39], v[0:3], v[12:15]
	s_nop 7
	v_mul_f32_e32 v12, v48, v12
	v_mul_f32_e32 v13, v48, v13
	v_mul_f32_e32 v14, v48, v14
	v_mul_f32_e32 v15, v48, v15
	v_cvt_pk_bf16_f32 v18, v12, v13
	v_cvt_pk_bf16_f32 v19, v14, v15
	ds_read2_b64 v[12:15], v82 offset0:64 offset1:68
	ds_read2_b64 v[36:39], v82 offset0:72 offset1:76
	ds_read2_b64 v[40:43], v82 offset0:80 offset1:84
	s_waitcnt lgkmcnt(2)
	v_mfma_f32_16x16x32_bf16 v[12:15], v[12:15], v[20:23], 0
	s_waitcnt lgkmcnt(1)
	v_mfma_f32_16x16x32_bf16 v[12:15], v[36:39], v[24:27], v[12:15]
	ds_read2_b64 v[36:39], v82 offset0:88 offset1:92
	ds_read_b64 v[44:45], v99 offset:17152
	global_store_dwordx2 v[16:17], v[18:19], off offset:32 nt
	v_mov_b32_e32 v99, v80
	s_waitcnt lgkmcnt(2)
	v_mfma_f32_16x16x32_bf16 v[12:15], v[40:43], v[28:31], v[12:15]
	s_waitcnt lgkmcnt(0)
	v_mov_b32_e32 v46, v44
	v_mov_b32_e32 v47, v45
	v_mfma_f32_16x16x32_bf16 v[12:15], v[36:39], v[32:35], v[12:15]
	s_nop 0
	v_mfma_f32_16x16x32_bf16 v[12:15], v[44:47], v[0:3], v[12:15]
	s_nop 7
	v_mul_f32_e32 v12, v48, v12
	v_mul_f32_e32 v13, v48, v13
	v_mul_f32_e32 v14, v48, v14
	v_mul_f32_e32 v15, v48, v15
	v_cvt_pk_bf16_f32 v40, v12, v13
	v_cvt_pk_bf16_f32 v41, v14, v15
	ds_read2_b64 v[12:15], v123 offset1:4
	ds_read2_b64 v[36:39], v123 offset0:8 offset1:12
	s_waitcnt lgkmcnt(1)
	v_mfma_f32_16x16x32_bf16 v[12:15], v[12:15], v[20:23], 0
	ds_read2_b64 v[18:21], v123 offset0:16 offset1:20
	s_waitcnt lgkmcnt(1)
	v_mfma_f32_16x16x32_bf16 v[12:15], v[36:39], v[24:27], v[12:15]
	ds_read2_b64 v[22:25], v123 offset0:24 offset1:28
	ds_read_b64 v[26:27], v123 offset:256
	v_mov_b32_e32 v123, v83
	global_store_dwordx2 v[16:17], v[40:41], off offset:64 nt
	s_waitcnt lgkmcnt(2)
	v_mfma_f32_16x16x32_bf16 v[12:15], v[18:21], v[28:31], v[12:15]
	s_waitcnt lgkmcnt(0)
	v_mov_b32_e32 v28, v26
	v_mov_b32_e32 v29, v27
	v_mfma_f32_16x16x32_bf16 v[12:15], v[22:25], v[32:35], v[12:15]
	s_nop 0
	v_mfma_f32_16x16x32_bf16 v[12:15], v[26:29], v[0:3], v[12:15]
	s_nop 7
	v_mul_f32_e32 v0, v48, v12
	v_mul_f32_e32 v1, v48, v13
	v_mul_f32_e32 v3, v48, v14
	v_mul_f32_e32 v12, v48, v15
	v_cvt_pk_bf16_f32 v0, v0, v1
	v_cvt_pk_bf16_f32 v1, v3, v12
	global_store_dwordx2 v[16:17], v[0:1], off offset:96 nt
	s_cbranch_scc1 .LBB0_332
	s_add_i32 s3, s3, s42
	s_cmp_gt_i32 s3, s99
	s_barrier
	s_cbranch_scc0 .LBB0_323
.LBB0_334:
	v_mov_b32_e32 v54, v176
	s_and_b32 s27, s2, 7
	s_lshl_b32 s27, s27, 7
	s_lshr_b32 s98, s2, 3
	s_add_i32 s27, s27, s98
	s_add_i32 s99, s27, 96
	s_mov_b32 s3, 32
	s_mov_b64 s[6:7], s[0:1]
	v_readfirstlane_b32 s18, v54
	s_cmpk_gt_i32 s27, 0x3ff
	s_cbranch_scc1 .LBB0_367
	v_mov_b64_e32 v[0:1], s[6:7]
	flat_load_dwordx4 v[2:5], v[0:1] offset:120
	flat_load_dwordx4 v[6:9], v[0:1] offset:136
	flat_load_dwordx2 v[40:41], v[0:1] offset:216
	flat_load_dwordx2 v[12:13], v[0:1] offset:152
	v_and_b32_e32 v55, 0xff, v54
	v_mov_b32_e32 v0, 0
	v_and_b32_e32 v56, 63, v54
	v_lshlrev_b32_e32 v10, 2, v55
	v_mov_b32_e32 v11, v0
	s_movk_i32 s6, 0x1000
	v_lshlrev_b32_e32 v14, 4, v56
	v_mov_b32_e32 v15, v0
	s_movk_i32 s7, 0x2000
	s_movk_i32 s8, 0x3000
	s_movk_i32 s9, 0x4000
	s_movk_i32 s10, 0x5000
	s_movk_i32 s11, 0x6000
	s_movk_i32 s12, 0x7000
	s_lshl_b32 s20, s27, 5
	v_ashrrev_i32_e32 v90, 5, v54
	v_lshlrev_b32_e32 v57, 3, v54
	v_and_b32_e32 v94, 0xf8, v57
	v_mov_b32_e32 v1, v0
	v_lshlrev_b32_e32 v52, 1, v94
	s_waitcnt vmcnt(0) lgkmcnt(0)
	v_lshl_add_u64 v[2:3], v[2:3], 0, v[10:11]
	v_lshl_add_u64 v[18:19], v[8:9], 0, v[14:15]
	v_add_co_u32_e32 v8, vcc, s6, v2
	v_lshl_add_u64 v[10:11], v[4:5], 0, v[10:11]
	s_nop 0
	v_addc_co_u32_e32 v9, vcc, 0, v3, vcc
	v_add_co_u32_e32 v20, vcc, s7, v2
	v_lshl_add_u64 v[16:17], v[6:7], 0, v[14:15]
	s_nop 0
	v_addc_co_u32_e32 v21, vcc, 0, v3, vcc
	v_add_co_u32_e32 v22, vcc, s8, v2
	s_and_b32 s6, s2, 7
	s_lshl_b32 s6, s6, 23
	s_add_u32 s6, s6, 0xd000000
	s_mov_b32 s7, 0
	s_nop 0
	v_addc_co_u32_e32 v23, vcc, 0, v3, vcc
	v_add_co_u32_e32 v24, vcc, s9, v2
	v_lshl_add_u64 v[50:51], v[40:41], 0, s[6:7]
	s_nop 0
	v_addc_co_u32_e32 v25, vcc, 0, v3, vcc
	v_add_co_u32_e32 v26, vcc, s10, v2
	s_ashr_i32 s6, s27, 7
	s_nop 0
	v_addc_co_u32_e32 v27, vcc, 0, v3, vcc
	v_add_co_u32_e32 v28, vcc, s11, v2
	s_and_b32 s7, s20, 0xfe0
	s_nop 0
	v_addc_co_u32_e32 v29, vcc, 0, v3, vcc
	v_add_co_u32_e32 v30, vcc, s12, v2
	s_sub_i32 s16, s7, 30
	s_nop 0
	v_addc_co_u32_e32 v31, vcc, 0, v3, vcc
	global_load_dword v58, v[10:11], off
	global_load_dwordx4 v[4:7], v[16:17], off
	global_load_dword v59, v[2:3], off
	global_load_dword v60, v[2:3], off offset:1024
	global_load_dword v61, v[2:3], off offset:2048
	global_load_dword v62, v[2:3], off offset:3072
	global_load_dword v63, v[8:9], off offset:1024
	global_load_dword v64, v[8:9], off offset:2048
	global_load_dword v65, v[8:9], off offset:3072
	global_load_dword v66, v[22:23], off offset:1024
	global_load_dword v67, v[20:21], off offset:-4096
	global_load_dword v68, v[20:21], off
	global_load_dword v69, v[20:21], off offset:1024
	global_load_dword v70, v[20:21], off offset:2048
	global_load_dword v71, v[20:21], off offset:3072
	global_load_dword v72, v[24:25], off offset:-4096
	global_load_dword v73, v[24:25], off
	global_load_dword v74, v[24:25], off offset:1024
	global_load_dword v75, v[24:25], off offset:2048
	global_load_dword v76, v[24:25], off offset:3072
	global_load_dword v77, v[28:29], off offset:-4096
	global_load_dword v78, v[28:29], off
	global_load_dword v79, v[28:29], off offset:1024
	global_load_dword v80, v[28:29], off offset:2048
	global_load_dword v81, v[28:29], off offset:3072
	global_load_dword v82, v[22:23], off offset:2048
	global_load_dword v83, v[22:23], off offset:3072
	global_load_dword v84, v[26:27], off offset:1024
	global_load_dword v85, v[26:27], off offset:2048
	global_load_dword v86, v[26:27], off offset:3072
	global_load_dword v87, v[30:31], off
	global_load_dword v88, v[30:31], off offset:1024
	global_load_dword v89, v[30:31], off offset:2048
	global_load_dwordx4 v[8:11], v[18:19], off
	v_lshl_add_u64 v[2:3], v[12:13], 0, v[14:15]
	global_load_dwordx4 v[12:15], v[2:3], off offset:3072
	s_ashr_i32 s7, s6, 31
	s_lshl_b64 s[14:15], s[6:7], 12
	v_add_u32_e32 v24, s16, v90
	s_movk_i32 s6, 0x7c0
	v_mov_b32_e32 v2, v0
	v_mov_b32_e32 v3, v0
	v_cmp_gt_i32_e64 s[6:7], s6, v54
	v_cmp_lt_i32_e32 vcc, -1, v24
	v_mov_b64_e32 v[22:23], v[2:3]
	v_mov_b64_e32 v[18:19], v[2:3]
	s_and_b64 s[10:11], s[6:7], vcc
	v_mov_b64_e32 v[20:21], v[0:1]
	v_mov_b64_e32 v[16:17], v[0:1]
	s_and_saveexec_b64 s[8:9], s[10:11]
	s_cbranch_execz .LBB0_337
	v_mov_b32_e32 v25, v0
	v_lshl_add_u64 v[16:17], s[14:15], 0, v[24:25]
	s_movk_i32 s12, 0xe00
	v_mad_u64_u32 v[18:19], s[10:11], v16, s12, v[50:51]
	v_mad_i32_i24 v19, v17, s12, v19
	v_mov_b32_e32 v53, v0
	v_lshl_add_u64 v[24:25], v[18:19], 0, v[52:53]
	global_load_dwordx4 v[16:19], v[24:25], off offset:2560
	global_load_dwordx4 v[20:23], v[24:25], off offset:3072
.LBB0_337:
	s_or_b64 exec, exec, s[8:9]
	v_add_u32_e32 v97, 0x200, v54
	v_ashrrev_i32_e32 v91, 5, v97
	v_add_u32_e32 v24, s16, v91
	s_movk_i32 s8, 0x5c0
	v_cmp_gt_i32_e64 s[8:9], s8, v54
	v_cmp_lt_i32_e32 vcc, -1, v24
	v_mov_b64_e32 v[30:31], v[2:3]
	s_and_b64 s[12:13], s[8:9], vcc
	v_mov_b64_e32 v[28:29], v[0:1]
	s_and_saveexec_b64 s[10:11], s[12:13]
	s_cbranch_execz .LBB0_339
	v_mov_b32_e32 v25, 0
	v_lshl_add_u64 v[0:1], s[14:15], 0, v[24:25]
	s_movk_i32 s17, 0xe00
	v_mad_u64_u32 v[2:3], s[12:13], v0, s17, v[50:51]
	v_mad_i32_i24 v3, v1, s17, v3
	v_mov_b32_e32 v53, v25
	v_lshl_add_u64 v[24:25], v[2:3], 0, v[52:53]
	global_load_dwordx4 v[28:31], v[24:25], off offset:2560
	global_load_dwordx4 v[0:3], v[24:25], off offset:3072
.LBB0_339:
	s_or_b64 exec, exec, s[10:11]
	v_add_u32_e32 v98, 0x400, v54
	v_ashrrev_i32_e32 v92, 5, v98
	v_mov_b32_e32 v25, 0
	v_add_u32_e32 v42, s16, v92
	s_movk_i32 s10, 0x3c0
	v_mov_b32_e32 v26, v25
	v_mov_b32_e32 v27, v25
	v_cmp_gt_i32_e64 s[10:11], s10, v54
	v_cmp_lt_i32_e32 vcc, -1, v42
	v_mov_b32_e32 v24, v25
	v_mov_b64_e32 v[38:39], v[26:27]
	v_mov_b64_e32 v[34:35], v[26:27]
	s_and_b64 s[22:23], s[10:11], vcc
	v_mov_b64_e32 v[36:37], v[24:25]
	v_mov_b64_e32 v[32:33], v[24:25]
	s_and_saveexec_b64 s[12:13], s[22:23]
	s_cbranch_execz .LBB0_341
	v_mov_b32_e32 v43, 0
	v_lshl_add_u64 v[26:27], s[14:15], 0, v[42:43]
	s_movk_i32 s17, 0xe00
	v_mad_u64_u32 v[32:33], s[22:23], v26, s17, v[50:51]
	v_mad_i32_i24 v33, v27, s17, v33
	v_mov_b32_e32 v53, v43
	v_lshl_add_u64 v[26:27], v[32:33], 0, v[52:53]
	global_load_dwordx4 v[32:35], v[26:27], off offset:2560
	global_load_dwordx4 v[36:39], v[26:27], off offset:3072
.LBB0_341:
	s_or_b64 exec, exec, s[12:13]
	v_add_u32_e32 v24, 0x600, v54
	v_ashrrev_i32_e32 v93, 5, v24
	v_add_u32_e32 v26, s16, v93
	s_movk_i32 s12, 0x1c0
	v_cmp_gt_i32_e64 s[12:13], s12, v54
	v_cmp_lt_i32_e32 vcc, -1, v26
	s_and_b64 s[22:23], s[12:13], vcc
	v_mov_b32_e32 v46, 0
	v_mov_b32_e32 v47, 0
	v_mov_b32_e32 v48, 0
	v_mov_b32_e32 v49, 0
	v_mov_b32_e32 v42, 0
	v_mov_b32_e32 v43, 0
	v_mov_b32_e32 v44, 0
	v_mov_b32_e32 v45, 0
	s_and_saveexec_b64 s[16:17], s[22:23]
	s_cbranch_execz .LBB0_343
	v_mov_b32_e32 v27, 0
	v_lshl_add_u64 v[42:43], s[14:15], 0, v[26:27]
	s_movk_i32 s19, 0xe00
	v_mad_u64_u32 v[44:45], s[14:15], v42, s19, v[50:51]
	v_mad_i32_i24 v45, v43, s19, v45
	v_mov_b32_e32 v53, v27
	v_lshl_add_u64 v[26:27], v[44:45], 0, v[52:53]
	global_load_dwordx4 v[42:45], v[26:27], off offset:2560
	global_load_dwordx4 v[46:49], v[26:27], off offset:3072
.LBB0_343:
	s_or_b64 exec, exec, s[16:17]
	v_lshrrev_b32_e32 v27, 4, v54
	v_lshl_add_u32 v26, v94, 2, 0
	v_and_b32_e32 v94, 0x3ffff0, v27
	v_and_b32_e32 v27, 0x3fffff00, v57
	s_ashr_i32 s16, s18, 4
	v_lshl_add_u32 v96, v27, 2, v26
	v_lshlrev_b32_e32 v27, 5, v97
	s_and_b32 s14, s16, -4
	v_and_b32_e32 v27, 0xfffffc00, v27
	v_add_u32_e32 v97, v26, v27
	v_lshlrev_b32_e32 v27, 5, v98
	v_lshlrev_b32_e32 v24, 5, v24
	s_ashr_i32 s15, s14, 31
	v_and_b32_e32 v27, 0xfffffc00, v27
	v_and_b32_e32 v24, 0xfffffc00, v24
	v_mov_b32_e32 v53, v25
	s_lshl_b64 s[14:15], s[14:15], 11
	v_add_u32_e32 v98, v26, v27
	v_add_u32_e32 v99, v26, v24
	v_lshl_add_u64 v[26:27], v[50:51], 0, v[52:53]
	v_lshl_or_b32 v50, v56, 3, s14
	s_lshl_b32 s14, s16, 10
	s_and_b32 s14, s14, 0xfffff000
	s_add_i32 s14, s14, 0
	v_mov_b32_e32 v51, s15
	v_lshl_add_u32 v24, v56, 4, s14
	v_lshl_add_u32 v95, v55, 2, 0
	v_lshl_add_u64 v[54:55], v[40:41], 0, v[50:51]
	s_lshl_b32 s21, s3, 5
	v_add_u32_e32 v100, 0xf800, v24
	s_movk_i32 s22, 0xe00
	v_mov_b32_e32 v101, 0x3727c5ac
	s_mov_b32 s23, 0x800000
	v_mov_b32_e32 v102, 0x358637bd
	s_mov_b32 s26, 0x9000000
	v_mov_b32_e32 v40, 0

.LBB0_352:
	s_or_b64 exec, exec, s[14:15]
	s_add_i32 s28, s27, s3
	s_cmp_gt_i32 s28, s99
	s_cselect_b64 s[14:15], -1, 0
	s_and_b64 vcc, exec, s[14:15]
	s_waitcnt lgkmcnt(0)
	s_barrier
	s_cbranch_vccnz .LBB0_362
	s_lshl_b32 s17, s28, 5
	s_and_b32 s17, s17, 0xfe0
	s_sub_i32 s29, s17, 30
	s_ashr_i32 s16, s28, 7
	v_add_u32_e32 v24, s29, v90
	s_waitcnt vmcnt(0)
	v_mov_b32_e32 v2, v40
	v_mov_b32_e32 v3, v40
	s_ashr_i32 s17, s16, 31
	v_cmp_lt_i32_e32 vcc, -1, v24
	v_mov_b32_e32 v0, 0
	v_mov_b32_e32 v1, v40
	v_mov_b64_e32 v[22:23], v[2:3]
	v_mov_b64_e32 v[18:19], v[2:3]
	s_lshl_b64 s[16:17], s[16:17], 12
	s_and_b64 s[30:31], s[6:7], vcc
	v_mov_b64_e32 v[20:21], v[0:1]
	v_mov_b64_e32 v[16:17], v[0:1]
	s_and_saveexec_b64 s[18:19], s[30:31]
	s_cbranch_execz .LBB0_355
	v_lshl_add_u64 v[16:17], s[16:17], 0, v[24:25]
	v_mad_u64_u32 v[28:29], s[30:31], v16, s22, v[26:27]
	v_mad_i32_i24 v29, v17, s22, v29
	global_load_dwordx4 v[16:19], v[28:29], off offset:2560
	global_load_dwordx4 v[20:23], v[28:29], off offset:3072
.LBB0_355:
	s_or_b64 exec, exec, s[18:19]
	v_add_u32_e32 v24, s29, v91
	v_cmp_lt_i32_e32 vcc, -1, v24
	v_mov_b64_e32 v[30:31], v[2:3]
	s_and_b64 s[30:31], s[8:9], vcc
	v_mov_b64_e32 v[28:29], v[0:1]
	s_and_saveexec_b64 s[18:19], s[30:31]
	s_cbranch_execz .LBB0_357
	v_lshl_add_u64 v[0:1], s[16:17], 0, v[24:25]
	v_mad_u64_u32 v[32:33], s[30:31], v0, s22, v[26:27]
	v_mad_i32_i24 v33, v1, s22, v33
	global_load_dwordx4 v[28:31], v[32:33], off offset:2560
	global_load_dwordx4 v[0:3], v[32:33], off offset:3072
.LBB0_357:
	s_or_b64 exec, exec, s[18:19]
	v_add_u32_e32 v24, s29, v92
	v_mov_b32_e32 v41, v40
	v_cmp_lt_i32_e32 vcc, -1, v24
	v_mov_b32_e32 v42, v40
	v_mov_b32_e32 v43, v40
	v_mov_b64_e32 v[36:37], v[40:41]
	v_mov_b64_e32 v[32:33], v[40:41]
	s_and_b64 s[30:31], s[10:11], vcc
	v_mov_b64_e32 v[38:39], v[42:43]
	v_mov_b64_e32 v[34:35], v[42:43]
	s_and_saveexec_b64 s[18:19], s[30:31]
	s_cbranch_execz .LBB0_359
	v_lshl_add_u64 v[32:33], s[16:17], 0, v[24:25]
	v_mad_u64_u32 v[42:43], s[30:31], v32, s22, v[26:27]
	v_mad_i32_i24 v43, v33, s22, v43
	global_load_dwordx4 v[32:35], v[42:43], off offset:2560
	global_load_dwordx4 v[36:39], v[42:43], off offset:3072
.LBB0_359:
	s_or_b64 exec, exec, s[18:19]
	v_add_u32_e32 v24, s29, v93
	v_cmp_lt_i32_e32 vcc, -1, v24
	s_and_b64 s[30:31], s[12:13], vcc
	v_mov_b32_e32 v45, 0
	v_mov_b32_e32 v44, 0
	v_mov_b32_e32 v43, 0
	v_mov_b32_e32 v42, 0
	v_mov_b32_e32 v49, 0
	v_mov_b32_e32 v48, 0
	v_mov_b32_e32 v47, 0
	v_mov_b32_e32 v46, 0
	s_and_saveexec_b64 s[18:19], s[30:31]
	s_cbranch_execz .LBB0_361
	v_lshl_add_u64 v[42:43], s[16:17], 0, v[24:25]
	v_mad_u64_u32 v[50:51], s[16:17], v42, s22, v[26:27]
	v_mad_i32_i24 v51, v43, s22, v51
	global_load_dwordx4 v[42:45], v[50:51], off offset:2560
	global_load_dwordx4 v[46:49], v[50:51], off offset:3072

.LBB0_411:
	s_or_b64 exec, exec, s[50:51]
	s_waitcnt vmcnt(0)
	v_mov_b32_e32 v0, v176
	s_and_b32 s3, s2, 7
	s_lshl_b32 s3, s3, 6
	s_lshr_b32 s98, s2, 3
	s_add_i32 s3, s3, s98
	s_add_i32 s99, s3, 32
	s_mov_b32 s18, 32
	s_waitcnt lgkmcnt(0)
	s_barrier
	s_mov_b64 s[6:7], s[0:1]
	v_readfirstlane_b32 s8, v0
	s_cmpk_lt_i32 s3, 0x200
	s_cbranch_scc0 .LBB0_445
	s_ashr_i32 s19, s8, 6
	v_and_b32_e32 v0, 63, v0
	s_lshl_b32 s8, s19, 10
	v_mov_b32_e32 v75, 0
	s_add_i32 s8, s8, 0
	v_lshlrev_b32_e32 v1, 4, v0
	v_lshlrev_b32_e32 v2, 1, v0
	s_lshl_b32 s20, s19, 3
	v_lshlrev_b32_e32 v4, 3, v0
	v_lshlrev_b32_e32 v72, 2, v0
	v_lshlrev_b32_e32 v76, 5, v0
	v_mov_b32_e32 v77, v75
	v_add_u32_e32 v73, s8, v1
	v_add_u32_e32 v108, 0, v1
	s_ashr_i32 s21, s20, 31
	v_mov_b64_e32 v[78:79], s[6:7]
	s_mov_b64 s[8:9], 0x1a000000
	s_mov_b64 s[10:11], 0x9000000
	v_lshlrev_b32_e32 v74, 4, v0
	v_lshlrev_b32_e32 v80, 4, v2
	s_mov_b64 s[12:13], 0x18000000
	s_and_b32 s22, s2, 7
	s_lshl_b32 s22, s22, 23
	s_add_u32 s22, s22, 0xd000000
	v_lshlrev_b32_e32 v82, 1, v4
	s_and_b32 s23, s2, 7
	s_lshl_b32 s23, s23, 23
	s_add_u32 s23, s23, 0xd001000
	s_and_b32 s26, s2, 7
	s_lshl_b32 s26, s26, 23
	s_add_u32 s26, s26, 0xd002000
	s_and_b32 s27, s2, 7
	s_lshl_b32 s27, s27, 23
	s_add_u32 s27, s27, 0xd003000
	s_and_b32 s28, s2, 7
	s_lshl_b32 s28, s28, 23
	s_add_u32 s28, s28, 0xd004000
	s_and_b32 s29, s2, 7
	s_lshl_b32 s29, s29, 23
	s_add_u32 s29, s29, 0xd005000
	s_and_b32 s30, s2, 7
	s_lshl_b32 s30, s30, 23
	s_add_u32 s30, s30, 0xd006000
	v_mov_b32_e32 v109, 0x358637bd
	s_mov_b32 s31, 0x800000
	s_movk_i32 s34, 0x1000
	s_movk_i32 s35, 0x2000
	s_movk_i32 s36, 0x3000
	v_mov_b32_e32 v110, 0xe00
	s_branch .LBB0_415

.LBB0_414:
	v_pk_fma_f32 v[56:57], v[62:63], 0, v[66:67] op_sel_hi:[1,0,1]
	v_mov_b32_e32 v9, v10
	v_mov_b32_e32 v13, v11
	v_pk_fma_f32 v[10:11], v[8:9], v[56:57], v[12:13]
	v_mov_b32_e32 v5, v6
	v_mov_b32_e32 v17, v7
	v_pk_mul_f32 v[8:9], v[62:63], v[8:9]
	v_pk_fma_f32 v[6:7], v[4:5], v[10:11], v[16:17]
	v_mov_b32_e32 v23, v24
	v_pk_mul_f32 v[4:5], v[4:5], v[8:9]
	v_mov_b32_e32 v31, v32
	v_pk_mul_f32 v[4:5], v[22:23], v[4:5]
	v_mov_b32_e32 v39, v40
	v_pk_mul_f32 v[4:5], v[30:31], v[4:5]
	v_pk_fma_f32 v[12:13], v[0:1], 0, v[64:65] op_sel_hi:[1,0,1]
	v_mov_b32_e32 v47, v48
	v_pk_mul_f32 v[4:5], v[38:39], v[4:5]
	v_pk_mul_f32 v[0:1], v[0:1], v[2:3]
	v_pk_fma_f32 v[12:13], v[12:13], v[2:3], v[68:69]
	v_mov_b32_e32 v21, v25
	v_pk_mul_f32 v[4:5], v[46:47], v[4:5]
	v_pk_mul_f32 v[0:1], v[0:1], v[14:15]
	v_pk_fma_f32 v[6:7], v[22:23], v[6:7], v[20:21]
	v_mov_b32_e32 v29, v33
	v_pk_mul_f32 v[10:11], v[54:55], v[4:5]
	v_pk_fma_f32 v[4:5], v[12:13], v[14:15], v[70:71]
	v_pk_mul_f32 v[0:1], v[0:1], v[18:19]
	v_pk_fma_f32 v[6:7], v[30:31], v[6:7], v[28:29]
	v_mov_b32_e32 v37, v41
	v_pk_fma_f32 v[4:5], v[4:5], v[18:19], v[84:85]
	v_pk_mul_f32 v[0:1], v[0:1], v[26:27]
	v_pk_fma_f32 v[6:7], v[38:39], v[6:7], v[36:37]
	v_pk_fma_f32 v[4:5], v[4:5], v[26:27], v[86:87]
	v_pk_mul_f32 v[0:1], v[0:1], v[34:35]
	v_pk_fma_f32 v[6:7], v[46:47], v[6:7], v[44:45]
	v_pk_fma_f32 v[4:5], v[4:5], v[34:35], v[88:89]
	v_pk_mul_f32 v[0:1], v[0:1], v[42:43]
	v_pk_fma_f32 v[6:7], v[54:55], v[6:7], v[52:53]
	v_pk_fma_f32 v[4:5], v[4:5], v[42:43], v[90:91]
	v_pk_mul_f32 v[12:13], v[0:1], v[50:51]
	v_pk_fma_f32 v[8:9], v[4:5], v[50:51], v[92:93]
	ds_write_b128 v73, v[10:13]
	ds_write_b128 v73, v[6:9] offset:8192
	s_waitcnt lgkmcnt(0)
	s_barrier
	ds_read_b128 v[0:3], v108
	ds_read_b128 v[4:7], v108 offset:8192
	ds_read_b128 v[8:11], v108 offset:1024
	ds_read_b128 v[12:15], v108 offset:9216
	s_ashr_i32 s6, s3, 6
	s_ashr_i32 s7, s6, 31
	s_lshl_b64 s[6:7], s[6:7], 12
	s_waitcnt lgkmcnt(2)
	v_pk_fma_f32 v[18:19], v[2:3], 0, v[6:7] op_sel_hi:[1,0,1]
	v_pk_fma_f32 v[20:21], v[0:1], 0, v[4:5] op_sel_hi:[1,0,1]
	ds_read_b128 v[0:3], v108 offset:2048
	ds_read_b128 v[4:7], v108 offset:10240
	s_waitcnt lgkmcnt(2)
	v_pk_fma_f32 v[18:19], v[18:19], v[10:11], v[14:15]
	v_pk_fma_f32 v[20:21], v[20:21], v[8:9], v[12:13]
	ds_read_b128 v[8:11], v108 offset:3072
	ds_read_b128 v[12:15], v108 offset:11264
	s_lshl_b32 s14, s37, 6
	s_waitcnt lgkmcnt(2)
	v_pk_fma_f32 v[18:19], v[18:19], v[2:3], v[6:7]
	v_pk_fma_f32 v[20:21], v[20:21], v[0:1], v[4:5]
	ds_read_b128 v[0:3], v108 offset:4096
	ds_read_b128 v[4:7], v108 offset:12288
	s_waitcnt lgkmcnt(2)
	v_pk_fma_f32 v[18:19], v[18:19], v[10:11], v[14:15]
	v_pk_fma_f32 v[20:21], v[20:21], v[8:9], v[12:13]
	ds_read_b128 v[8:11], v108 offset:5120
	ds_read_b128 v[12:15], v108 offset:13312
	v_mov_b32_e32 v81, v75
	s_waitcnt lgkmcnt(2)
	v_pk_fma_f32 v[18:19], v[18:19], v[2:3], v[6:7]
	v_pk_fma_f32 v[20:21], v[20:21], v[0:1], v[4:5]
	ds_read_b128 v[0:3], v108 offset:6144
	ds_read_b128 v[4:7], v108 offset:14336
	s_add_u32 s14, s14, s20
	s_waitcnt lgkmcnt(2)
	v_pk_fma_f32 v[10:11], v[18:19], v[10:11], v[14:15]
	v_pk_fma_f32 v[8:9], v[20:21], v[8:9], v[12:13]
	v_lshl_add_u64 v[12:13], v[60:61], 0, v[74:75]
	v_lshl_add_u64 v[14:15], v[60:61], 0, v[80:81]
	s_addc_u32 s15, 0, s21
	ds_read_b128 v[112:115], v108 offset:7168
	ds_read_b128 v[116:119], v108 offset:15360
	s_waitcnt lgkmcnt(2)
	v_pk_fma_f32 v[18:19], v[10:11], v[2:3], v[6:7]
	v_pk_fma_f32 v[88:89], v[8:9], v[0:1], v[4:5]
	global_load_dwordx4 v[0:3], v[14:15], off offset:1040
	global_load_dwordx4 v[8:11], v[12:13], off
	global_load_dwordx4 v[4:7], v[14:15], off offset:1024
	s_add_u32 s6, s14, s6
	v_lshlrev_b32_e32 v12, 2, v72
	v_mov_b32_e32 v13, v75
	s_addc_u32 s7, s15, s7
	v_lshl_add_u64 v[12:13], v[58:59], 0, v[12:13]
	v_lshl_add_u64 v[12:13], v[12:13], 0, s[12:13]
	s_lshl_b64 s[14:15], s[6:7], 10
	v_lshl_add_u64 v[14:15], v[12:13], 0, s[14:15]
	s_mul_i32 s16, s7, 0xe00
	v_mad_u64_u32 v[20:21], s[14:15], s6, v110, v[58:59]
	v_add_u32_e32 v21, s16, v21
	v_lshlrev_b32_e32 v104, 1, v72
	v_mov_b32_e32 v105, v75
	v_lshl_add_u64 v[86:87], v[20:21], 0, v[104:105]
	v_add_co_u32_e32 v20, vcc, s22, v86
	v_lshl_add_u64 v[16:17], v[58:59], 0, s[10:11]
	s_nop 0
	v_addc_co_u32_e32 v21, vcc, 0, v87, vcc
	global_load_dwordx4 v[120:123], v[14:15], off
	global_load_dwordx2 v[124:125], v[20:21], off offset:512
	s_lshl_b64 s[14:15], s[6:7], 11
	v_lshl_add_u64 v[106:107], v[16:17], 0, s[14:15]
	v_mov_b32_e32 v83, v75
	s_or_b32 s14, s6, 1
	s_mov_b32 s15, s7
	v_lshl_add_u64 v[84:85], v[106:107], 0, v[82:83]
	s_lshl_b64 s[16:17], s[14:15], 10
	v_lshl_add_u64 v[14:15], v[12:13], 0, s[16:17]
	global_load_dwordx4 v[68:71], v[84:85], off offset:512
	global_load_dwordx4 v[64:67], v[14:15], off
	s_lshl_b64 s[14:15], s[14:15], 11
	v_add_co_u32_e32 v14, vcc, s23, v86
	v_lshl_add_u64 v[20:21], v[16:17], 0, s[14:15]
	s_or_b32 s14, s6, 2
	s_mov_b32 s15, s7
	v_addc_co_u32_e32 v15, vcc, 0, v87, vcc
	v_lshl_add_u64 v[20:21], v[20:21], 0, v[82:83]
	s_lshl_b64 s[16:17], s[14:15], 10
	s_lshl_b64 s[14:15], s[14:15], 11
	v_lshl_add_u64 v[22:23], v[12:13], 0, s[16:17]
	global_load_dwordx4 v[60:63], v[20:21], off offset:512
	global_load_dwordx4 v[56:59], v[22:23], off
	global_load_dwordx2 v[102:103], v[14:15], off
	global_load_dwordx2 v[100:101], v[14:15], off offset:3584
	v_lshl_add_u64 v[14:15], v[16:17], 0, s[14:15]
	s_or_b32 s14, s6, 3
	s_mov_b32 s15, s7
	s_lshl_b64 s[16:17], s[14:15], 10
	v_lshl_add_u64 v[14:15], v[14:15], 0, v[82:83]
	v_lshl_add_u64 v[20:21], v[12:13], 0, s[16:17]
	s_lshl_b64 s[14:15], s[14:15], 11
	global_load_dwordx4 v[52:55], v[14:15], off offset:512
	global_load_dwordx4 v[48:51], v[20:21], off
	v_add_co_u32_e32 v14, vcc, s26, v86
	v_lshl_add_u64 v[20:21], v[16:17], 0, s[14:15]
	s_or_b32 s14, s6, 4
	s_mov_b32 s15, s7
	v_addc_co_u32_e32 v15, vcc, 0, v87, vcc
	v_lshl_add_u64 v[20:21], v[20:21], 0, v[82:83]
	s_lshl_b64 s[16:17], s[14:15], 10
	global_load_dwordx2 v[98:99], v[14:15], off offset:3072
	global_load_dwordx4 v[44:47], v[20:21], off offset:512
	v_lshl_add_u64 v[14:15], v[12:13], 0, s[16:17]
	v_add_co_u32_e32 v20, vcc, s27, v86
	s_lshl_b64 s[14:15], s[14:15], 11
	s_nop 0
	v_addc_co_u32_e32 v21, vcc, 0, v87, vcc
	global_load_dwordx4 v[40:43], v[14:15], off
	global_load_dwordx2 v[96:97], v[20:21], off offset:2560
	v_lshl_add_u64 v[14:15], v[16:17], 0, s[14:15]
	s_or_b32 s14, s6, 5
	s_mov_b32 s15, s7
	s_lshl_b64 s[16:17], s[14:15], 10
	v_lshl_add_u64 v[14:15], v[14:15], 0, v[82:83]
	v_lshl_add_u64 v[20:21], v[12:13], 0, s[16:17]
	s_lshl_b64 s[14:15], s[14:15], 11
	global_load_dwordx4 v[36:39], v[14:15], off offset:512
	global_load_dwordx4 v[32:35], v[20:21], off
	v_add_co_u32_e32 v14, vcc, s28, v86
	v_lshl_add_u64 v[20:21], v[16:17], 0, s[14:15]
	s_nop 0
	v_addc_co_u32_e32 v15, vcc, 0, v87, vcc
	v_lshl_add_u64 v[20:21], v[20:21], 0, v[82:83]
	s_or_b32 s14, s6, 6
	s_mov_b32 s15, s7
	global_load_dwordx2 v[94:95], v[14:15], off offset:2048
	global_load_dwordx4 v[28:31], v[20:21], off offset:512
	s_lshl_b64 s[16:17], s[14:15], 10
	v_add_co_u32_e32 v20, vcc, s29, v86
	v_lshl_add_u64 v[14:15], v[12:13], 0, s[16:17]
	s_nop 0
	v_addc_co_u32_e32 v21, vcc, 0, v87, vcc
	s_lshl_b64 s[14:15], s[14:15], 11
	s_or_b32 s6, s6, 7
	global_load_dwordx4 v[24:27], v[14:15], off
	global_load_dwordx2 v[92:93], v[20:21], off offset:1536
	v_lshl_add_u64 v[14:15], v[16:17], 0, s[14:15]
	s_lshl_b64 s[14:15], s[6:7], 10
	v_add_co_u32_e32 v86, vcc, s30, v86
	v_lshl_add_u64 v[14:15], v[14:15], 0, v[82:83]
	v_lshl_add_u64 v[12:13], v[12:13], 0, s[14:15]
	s_waitcnt vmcnt(18)
	v_lshlrev_b32_e32 v126, 16, v124
	v_mul_f32_e32 v81, 0x3d372713, v126
	v_mul_f32_e32 v81, v81, v126
	v_mov_b32_e32 v90, v126
	v_and_b32_e32 v127, 0xffff0000, v124
	v_fmac_f32_e32 v90, v81, v90
	v_mul_f32_e32 v81, 0x3f4c422a, v90
	v_mul_f32_e32 v90, 0x3d372713, v127
	v_mul_f32_e32 v90, v90, v127
	v_mov_b32_e32 v91, v127
	v_fmac_f32_e32 v91, v90, v91
	v_add_f32_e32 v81, v81, v81
	v_mul_f32_e32 v90, 0x3f4c422a, v91
	v_mul_f32_e32 v81, 0x3fb8aa3b, v81
	v_add_f32_e32 v90, v90, v90
	v_exp_f32_e32 v81, v81
	v_mul_f32_e32 v90, 0x3fb8aa3b, v90
	v_exp_f32_e32 v111, v90
	v_addc_co_u32_e32 v87, vcc, 0, v87, vcc
	v_add_f32_e32 v81, 1.0, v81
	global_load_dwordx4 v[20:23], v[14:15], off offset:512
	s_nop 0
	global_load_dwordx4 v[12:15], v[12:13], off
	v_rcp_f32_e32 v128, v81
	global_load_dwordx2 v[90:91], v[86:87], off offset:1024
	v_add_f32_e32 v81, 1.0, v111
	s_waitcnt lgkmcnt(0)
	v_pk_fma_f32 v[86:87], v[18:19], v[114:115], v[118:119]
	v_lshlrev_b32_e32 v114, 16, v125
	v_rcp_f32_e32 v129, v81
	v_mul_f32_e32 v81, 0x3d372713, v114
	v_mul_f32_e32 v81, v81, v114
	v_mov_b32_e32 v111, v114
	v_and_b32_e32 v115, 0xffff0000, v125
	v_fmac_f32_e32 v111, v81, v111
	v_mul_f32_e32 v81, 0x3f4c422a, v111
	v_mul_f32_e32 v111, 0x3d372713, v115
	v_pk_fma_f32 v[88:89], v[88:89], v[112:113], v[116:117]
	v_mul_f32_e32 v111, v111, v115
	v_mov_b32_e32 v116, v115
	v_fmac_f32_e32 v116, v111, v116
	v_add_f32_e32 v81, v81, v81
	v_mul_f32_e32 v111, 0x3f4c422a, v116
	v_mul_f32_e32 v81, 0x3fb8aa3b, v81
	v_add_f32_e32 v111, v111, v111
	v_exp_f32_e32 v81, v81
	v_mul_f32_e32 v111, 0x3fb8aa3b, v111
	v_exp_f32_e32 v111, v111
	v_pk_fma_f32 v[18:19], v[128:129], 2.0, 1.0 op_sel_hi:[1,0,0] neg_lo:[1,0,0] neg_hi:[1,0,0]
	v_add_f32_e32 v81, 1.0, v81
	v_rcp_f32_e32 v118, v81
	v_add_f32_e32 v81, 1.0, v111
	v_rcp_f32_e32 v119, v81
	v_pk_mul_f32 v[112:113], v[126:127], 0.5 op_sel_hi:[1,0]
	v_pk_add_f32 v[18:19], v[18:19], 1.0 op_sel_hi:[1,0]
	v_lshlrev_b32_e32 v117, 16, v121
	v_pk_mul_f32 v[18:19], v[112:113], v[18:19]
	v_and_b32_e32 v113, 0xffff0000, v121
	v_and_b32_e32 v112, 0xffff0000, v120
	v_lshlrev_b32_e32 v116, 16, v120
	v_pk_fma_f32 v[112:113], v[88:89], v[116:117], v[112:113]
	v_pk_mul_f32 v[114:115], v[114:115], 0.5 op_sel_hi:[1,0]
	v_pk_mul_f32 v[112:113], v[112:113], v[18:19]
	v_pk_fma_f32 v[18:19], v[118:119], 2.0, 1.0 op_sel_hi:[1,0,0] neg_lo:[1,0,0] neg_hi:[1,0,0]
	v_lshlrev_b32_e32 v117, 16, v123
	v_pk_add_f32 v[18:19], v[18:19], 1.0 op_sel_hi:[1,0]
	v_lshlrev_b32_e32 v116, 16, v122
	v_pk_mul_f32 v[18:19], v[114:115], v[18:19]
	v_and_b32_e32 v115, 0xffff0000, v123
	v_and_b32_e32 v114, 0xffff0000, v122
	v_pk_fma_f32 v[114:115], v[86:87], v[116:117], v[114:115]
	v_mov_b32_e32 v116, v113
	v_pk_mul_f32 v[114:115], v[114:115], v[18:19]
	v_mov_b32_e32 v18, v112
	v_mov_b32_e32 v117, v115
	v_mov_b32_e32 v19, v114
	v_pk_mul_f32 v[116:117], v[116:117], v[116:117]
	s_lshl_b64 s[6:7], s[6:7], 11
	v_pk_fma_f32 v[18:19], v[18:19], v[18:19], v[116:117]
	v_lshl_add_u64 v[16:17], v[16:17], 0, s[6:7]
	v_add_f32_e32 v18, v18, v19
	v_lshl_add_u64 v[16:17], v[16:17], 0, v[82:83]
	s_waitcnt vmcnt(20)
	v_and_b32_e32 v119, 0xffff0000, v70
	v_add_f32_dpp v18, v18, v18 quad_perm:[1,0,3,2] row_mask:0xf bank_mask:0xf bound_ctrl:1
	v_and_b32_e32 v118, 0xffff0000, v68
	v_lshlrev_b32_e32 v121, 16, v71
	v_add_f32_dpp v18, v18, v18 quad_perm:[2,3,0,1] row_mask:0xf bank_mask:0xf bound_ctrl:1
	v_and_b32_e32 v71, 0xffff0000, v71
	v_lshlrev_b32_e32 v120, 16, v69
	v_add_f32_dpp v18, v18, v18 row_half_mirror row_mask:0xf bank_mask:0xf bound_ctrl:1
	s_add_i32 s3, s3, s18
	s_cmp_gt_i32 s3, s99
	v_add_f32_dpp v18, v18, v18 row_mirror row_mask:0xf bank_mask:0xf bound_ctrl:1
	s_nop 0
	v_readlane_b32 s16, v18, 16
	v_readlane_b32 s17, v18, 48
	v_readlane_b32 s14, v18, 0
	v_readlane_b32 s15, v18, 32
	v_mov_b32_e32 v18, s16
	v_mov_b32_e32 v19, s17
	v_pk_add_f32 v[18:19], s[14:15], v[18:19]
	s_nop 0
	v_add_f32_e32 v18, v18, v19
	v_fmamk_f32 v18, v18, 0x3b800000, v109
	v_mul_f32_e32 v19, 0x4b800000, v18
	v_cmp_gt_f32_e32 vcc, s31, v18
	s_nop 1
	v_cndmask_b32_e32 v18, v18, v19, vcc
	v_rsq_f32_e32 v81, v18
	global_load_dwordx4 v[16:19], v[16:17], off offset:512
	v_mul_f32_e32 v83, 0x45800000, v81
	v_cndmask_b32_e32 v116, v81, v83, vcc
	v_pk_mul_f32 v[112:113], v[112:113], v[116:117] op_sel_hi:[1,0]
	v_pk_mul_f32 v[114:115], v[114:115], v[116:117] op_sel_hi:[1,0]
	v_lshlrev_b32_e32 v117, 16, v70
	v_and_b32_e32 v70, 0xffff0000, v69
	v_lshlrev_b32_e32 v116, 16, v68
	v_pk_mul_f32 v[68:69], v[118:119], v[118:119]
	v_pk_mul_f32 v[122:123], v[70:71], v[70:71]
	v_pk_fma_f32 v[68:69], v[116:117], v[116:117], v[68:69]
	v_pk_fma_f32 v[122:123], v[120:121], v[120:121], v[122:123]
	v_pk_mul_f32 v[114:115], v[10:11], v[114:115]
	v_pk_add_f32 v[68:69], v[68:69], v[122:123]
	v_pk_mul_f32 v[112:113], v[8:9], v[112:113]
	v_add_f32_e32 v68, v68, v69
	v_cvt_pk_bf16_f32 v112, v112, v113
	v_cvt_pk_bf16_f32 v113, v114, v115
	s_nop 1
	v_add_f32_dpp v68, v68, v68 quad_perm:[1,0,3,2] row_mask:0xf bank_mask:0xf bound_ctrl:1
	s_nop 1
	v_add_f32_dpp v68, v68, v68 quad_perm:[2,3,0,1] row_mask:0xf bank_mask:0xf bound_ctrl:1
	s_nop 1
	v_add_f32_dpp v68, v68, v68 row_half_mirror row_mask:0xf bank_mask:0xf bound_ctrl:1
	s_nop 1
	v_add_f32_dpp v68, v68, v68 row_mirror row_mask:0xf bank_mask:0xf bound_ctrl:1
	s_nop 0
	v_readlane_b32 s14, v68, 16
	v_readlane_b32 s15, v68, 48
	v_readlane_b32 s6, v68, 0
	v_readlane_b32 s7, v68, 32
	v_mov_b32_e32 v68, s14
	v_mov_b32_e32 v69, s15
	v_pk_add_f32 v[68:69], s[6:7], v[68:69]
	s_nop 0
	v_add_f32_e32 v68, v68, v69
	v_fmamk_f32 v68, v68, 0x3b000000, v109
	v_mul_f32_e32 v69, 0x4b800000, v68
	v_cmp_gt_f32_e32 vcc, s31, v68
	s_nop 1
	v_cndmask_b32_e32 v68, v68, v69, vcc
	v_rsq_f32_e32 v81, v68
	v_lshl_add_u64 v[68:69], v[106:107], 0, v[104:105]
	v_mov_b32_e32 v106, v116
	s_waitcnt vmcnt(17)
	v_lshlrev_b32_e32 v116, 16, v102
	v_mul_f32_e32 v83, 0x45800000, v81
	v_cndmask_b32_e32 v104, v81, v83, vcc
	v_mul_f32_e32 v81, 0x3d372713, v116
	v_mul_f32_e32 v81, v81, v116
	v_mov_b32_e32 v83, v116
	v_mov_b32_e32 v107, v118
	v_mov_b32_e32 v118, v117
	v_and_b32_e32 v117, 0xffff0000, v102
	v_fmac_f32_e32 v83, v81, v83
	v_mul_f32_e32 v81, 0x3f4c422a, v83
	v_mul_f32_e32 v83, 0x3d372713, v117
	v_mul_f32_e32 v83, v83, v117
	v_mov_b32_e32 v102, v117
	v_fmac_f32_e32 v102, v83, v102
	v_add_f32_e32 v81, v81, v81
	v_mul_f32_e32 v83, 0x3f4c422a, v102
	v_mul_f32_e32 v81, 0x3fb8aa3b, v81
	v_add_f32_e32 v83, v83, v83
	v_exp_f32_e32 v81, v81
	v_mul_f32_e32 v83, 0x3fb8aa3b, v83
	v_exp_f32_e32 v83, v83
	v_pk_mul_f32 v[114:115], v[118:119], v[104:105] op_sel_hi:[1,0]
	v_add_f32_e32 v81, 1.0, v81
	v_rcp_f32_e32 v118, v81
	v_add_f32_e32 v81, 1.0, v83
	v_lshlrev_b32_e32 v102, 16, v103
	v_rcp_f32_e32 v119, v81
	v_mul_f32_e32 v81, 0x3d372713, v102
	v_mul_f32_e32 v81, v81, v102
	v_mov_b32_e32 v83, v102
	v_and_b32_e32 v103, 0xffff0000, v103
	v_fmac_f32_e32 v83, v81, v83
	v_mul_f32_e32 v81, 0x3f4c422a, v83
	v_mul_f32_e32 v83, 0x3d372713, v103
	v_mul_f32_e32 v83, v83, v103
	v_mov_b32_e32 v111, v103
	v_fmac_f32_e32 v111, v83, v111
	v_add_f32_e32 v81, v81, v81
	v_mul_f32_e32 v83, 0x3f4c422a, v111
	v_mul_f32_e32 v81, 0x3fb8aa3b, v81
	v_add_f32_e32 v83, v83, v83
	v_exp_f32_e32 v81, v81
	v_mul_f32_e32 v83, 0x3fb8aa3b, v83
	v_exp_f32_e32 v83, v83
	global_store_dwordx2 v[68:69], v[112:113], off
	v_mov_b32_e32 v112, v120
	v_mov_b32_e32 v113, v70
	v_pk_mul_f32 v[112:113], v[112:113], v[104:105] op_sel_hi:[1,0]
	v_pk_mul_f32 v[106:107], v[106:107], v[104:105] op_sel_hi:[1,0]
	v_pk_mul_f32 v[112:113], v[6:7], v[112:113]
	v_mov_b32_e32 v70, v121
	v_add_f32_e32 v81, 1.0, v81
	v_pk_mul_f32 v[106:107], v[4:5], v[106:107]
	v_pk_mul_f32 v[70:71], v[70:71], v[104:105] op_sel_hi:[1,0]
	v_cvt_pk_bf16_f32 v104, v106, v107
	v_cvt_pk_bf16_f32 v105, v112, v113
	v_pk_mul_f32 v[112:113], v[116:117], 0.5 op_sel_hi:[1,0]
	v_rcp_f32_e32 v116, v81
	v_add_f32_e32 v81, 1.0, v83
	v_pk_fma_f32 v[106:107], v[118:119], 2.0, 1.0 op_sel_hi:[1,0,0] neg_lo:[1,0,0] neg_hi:[1,0,0]
	v_rcp_f32_e32 v117, v81
	v_pk_add_f32 v[106:107], v[106:107], 1.0 op_sel_hi:[1,0]
	v_pk_mul_f32 v[102:103], v[102:103], 0.5 op_sel_hi:[1,0]
	v_pk_mul_f32 v[106:107], v[112:113], v[106:107]
	v_and_b32_e32 v113, 0xffff0000, v65
	v_and_b32_e32 v112, 0xffff0000, v64
	v_lshlrev_b32_e32 v65, 16, v65
	v_lshlrev_b32_e32 v64, 16, v64
	v_pk_fma_f32 v[64:65], v[88:89], v[64:65], v[112:113]
	v_pk_mul_f32 v[70:71], v[2:3], v[70:71]
	v_pk_mul_f32 v[64:65], v[64:65], v[106:107]
	v_pk_fma_f32 v[106:107], v[116:117], 2.0, 1.0 op_sel_hi:[1,0,0] neg_lo:[1,0,0] neg_hi:[1,0,0]
	v_pk_mul_f32 v[114:115], v[0:1], v[114:115]
	v_pk_add_f32 v[106:107], v[106:107], 1.0 op_sel_hi:[1,0]
	s_nop 0
	v_pk_mul_f32 v[102:103], v[102:103], v[106:107]
	v_and_b32_e32 v107, 0xffff0000, v67
	v_and_b32_e32 v106, 0xffff0000, v66
	v_lshlrev_b32_e32 v67, 16, v67
	v_lshlrev_b32_e32 v66, 16, v66
	v_pk_fma_f32 v[66:67], v[86:87], v[66:67], v[106:107]
	v_mov_b32_e32 v106, v65
	v_pk_mul_f32 v[66:67], v[66:67], v[102:103]
	v_mov_b32_e32 v102, v64
	v_mov_b32_e32 v107, v67
	v_mov_b32_e32 v103, v66
	v_pk_mul_f32 v[106:107], v[106:107], v[106:107]
	s_nop 0
	v_pk_fma_f32 v[102:103], v[102:103], v[102:103], v[106:107]
	v_cvt_pk_bf16_f32 v106, v114, v115
	v_cvt_pk_bf16_f32 v107, v70, v71
	global_store_dwordx4 v[84:85], v[104:107], off offset:512
	v_add_f32_e32 v81, v102, v103
	s_nop 0
	v_lshlrev_b32_e32 v105, 16, v63
	v_add_f32_dpp v81, v81, v81 quad_perm:[1,0,3,2] row_mask:0xf bank_mask:0xf bound_ctrl:1
	v_and_b32_e32 v63, 0xffff0000, v63
	v_lshlrev_b32_e32 v104, 16, v61
	v_add_f32_dpp v81, v81, v81 quad_perm:[2,3,0,1] row_mask:0xf bank_mask:0xf bound_ctrl:1
	s_nop 1
	v_add_f32_dpp v81, v81, v81 row_half_mirror row_mask:0xf bank_mask:0xf bound_ctrl:1
	s_nop 1
	v_add_f32_dpp v81, v81, v81 row_mirror row_mask:0xf bank_mask:0xf bound_ctrl:1
	s_nop 0
	v_readlane_b32 s14, v81, 16
	v_readlane_b32 s15, v81, 48
	v_readlane_b32 s6, v81, 0
	v_readlane_b32 s7, v81, 32
	v_mov_b32_e32 v102, s14
	v_mov_b32_e32 v103, s15
	v_pk_add_f32 v[102:103], s[6:7], v[102:103]
	s_nop 0
	v_add_f32_e32 v81, v102, v103
	v_fmamk_f32 v81, v81, 0x3b800000, v109
	v_mul_f32_e32 v83, 0x4b800000, v81
	v_cmp_gt_f32_e32 vcc, s31, v81
	v_and_b32_e32 v103, 0xffff0000, v62
	v_and_b32_e32 v102, 0xffff0000, v60
	v_cndmask_b32_e32 v81, v81, v83, vcc
	v_rsq_f32_e32 v81, v81
	s_nop 0
	v_mul_f32_e32 v70, 0x45800000, v81
	v_cndmask_b32_e32 v70, v81, v70, vcc
	v_pk_mul_f32 v[64:65], v[64:65], v[70:71] op_sel_hi:[1,0]
	v_pk_mul_f32 v[66:67], v[66:67], v[70:71] op_sel_hi:[1,0]
	v_lshlrev_b32_e32 v71, 16, v62
	v_and_b32_e32 v62, 0xffff0000, v61
	v_lshlrev_b32_e32 v70, 16, v60
	v_pk_mul_f32 v[60:61], v[102:103], v[102:103]
	v_pk_mul_f32 v[106:107], v[62:63], v[62:63]
	v_pk_fma_f32 v[60:61], v[70:71], v[70:71], v[60:61]
	v_pk_fma_f32 v[106:107], v[104:105], v[104:105], v[106:107]
	v_pk_mul_f32 v[64:65], v[8:9], v[64:65]
	v_pk_add_f32 v[60:61], v[60:61], v[106:107]
	v_pk_mul_f32 v[66:67], v[10:11], v[66:67]
	v_add_f32_e32 v60, v60, v61
	s_nop 1
	v_add_f32_dpp v60, v60, v60 quad_perm:[1,0,3,2] row_mask:0xf bank_mask:0xf bound_ctrl:1
	s_nop 1
	v_add_f32_dpp v60, v60, v60 quad_perm:[2,3,0,1] row_mask:0xf bank_mask:0xf bound_ctrl:1
	s_nop 1
	v_add_f32_dpp v60, v60, v60 row_half_mirror row_mask:0xf bank_mask:0xf bound_ctrl:1
	s_nop 1
	v_add_f32_dpp v60, v60, v60 row_mirror row_mask:0xf bank_mask:0xf bound_ctrl:1
	s_nop 0
	v_readlane_b32 s14, v60, 16
	v_readlane_b32 s15, v60, 48
	v_readlane_b32 s6, v60, 0
	v_readlane_b32 s7, v60, 32
	v_mov_b32_e32 v60, s14
	v_mov_b32_e32 v61, s15
	v_pk_add_f32 v[60:61], s[6:7], v[60:61]
	s_nop 0
	v_add_f32_e32 v60, v60, v61
	v_fmamk_f32 v60, v60, 0x3b000000, v109
	v_mul_f32_e32 v61, 0x4b800000, v60
	v_cmp_gt_f32_e32 vcc, s31, v60
	s_nop 1
	v_cndmask_b32_e32 v60, v60, v61, vcc
	v_rsq_f32_e32 v81, v60
	v_cvt_pk_bf16_f32 v60, v64, v65
	v_cvt_pk_bf16_f32 v61, v66, v67
	global_store_dwordx2 v[68:69], v[60:61], off offset:2048
	v_mul_f32_e32 v60, 0x45800000, v81
	v_cndmask_b32_e32 v60, v81, v60, vcc
	v_mov_b32_e32 v64, v70
	v_mov_b32_e32 v65, v102
	v_mov_b32_e32 v66, v104
	v_mov_b32_e32 v67, v62
	v_mov_b32_e32 v102, v71
	v_mov_b32_e32 v62, v105
	v_pk_mul_f32 v[64:65], v[64:65], v[60:61] op_sel_hi:[1,0]
	v_pk_mul_f32 v[66:67], v[66:67], v[60:61] op_sel_hi:[1,0]
	v_pk_mul_f32 v[70:71], v[102:103], v[60:61] op_sel_hi:[1,0]
	v_pk_mul_f32 v[60:61], v[62:63], v[60:61] op_sel_hi:[1,0]
	s_waitcnt vmcnt(19)
	v_lshlrev_b32_e32 v62, 16, v100
	v_mul_f32_e32 v81, 0x3d372713, v62
	v_mul_f32_e32 v81, v81, v62
	v_mov_b32_e32 v83, v62
	v_and_b32_e32 v63, 0xffff0000, v100
	v_fmac_f32_e32 v83, v81, v83
	v_mul_f32_e32 v81, 0x3f4c422a, v83
	v_mul_f32_e32 v83, 0x3d372713, v63
	v_mul_f32_e32 v83, v83, v63
	v_mov_b32_e32 v100, v63
	v_fmac_f32_e32 v100, v83, v100
	v_add_f32_e32 v81, v81, v81
	v_mul_f32_e32 v83, 0x3f4c422a, v100
	v_mul_f32_e32 v81, 0x3fb8aa3b, v81
	v_add_f32_e32 v83, v83, v83
	v_exp_f32_e32 v81, v81
	v_mul_f32_e32 v83, 0x3fb8aa3b, v83
	v_exp_f32_e32 v83, v83
	v_pk_mul_f32 v[102:103], v[2:3], v[60:61]
	v_add_f32_e32 v60, 1.0, v81
	v_pk_mul_f32 v[66:67], v[6:7], v[66:67]
	v_rcp_f32_e32 v104, v60
	v_add_f32_e32 v60, 1.0, v83
	v_pk_mul_f32 v[64:65], v[4:5], v[64:65]
	v_rcp_f32_e32 v105, v60
	v_cvt_pk_bf16_f32 v60, v64, v65
	v_cvt_pk_bf16_f32 v61, v66, v67
	v_lshlrev_b32_e32 v66, 16, v101
	v_mul_f32_e32 v81, 0x3d372713, v66
	v_mul_f32_e32 v81, v81, v66
	v_mov_b32_e32 v83, v66
	v_and_b32_e32 v67, 0xffff0000, v101
	v_fmac_f32_e32 v83, v81, v83
	v_mul_f32_e32 v81, 0x3f4c422a, v83
	v_mul_f32_e32 v83, 0x3d372713, v67
	v_mul_f32_e32 v83, v83, v67
	v_mov_b32_e32 v100, v67
	v_fmac_f32_e32 v100, v83, v100
	v_add_f32_e32 v81, v81, v81
	v_mul_f32_e32 v83, 0x3f4c422a, v100
	v_mul_f32_e32 v81, 0x3fb8aa3b, v81
	v_add_f32_e32 v83, v83, v83
	v_exp_f32_e32 v81, v81
	v_mul_f32_e32 v83, 0x3fb8aa3b, v83
	v_exp_f32_e32 v83, v83
	v_pk_fma_f32 v[64:65], v[104:105], 2.0, 1.0 op_sel_hi:[1,0,0] neg_lo:[1,0,0] neg_hi:[1,0,0]
	v_add_f32_e32 v81, 1.0, v81
	v_rcp_f32_e32 v100, v81
	v_add_f32_e32 v81, 1.0, v83
	v_rcp_f32_e32 v101, v81
	v_pk_mul_f32 v[62:63], v[62:63], 0.5 op_sel_hi:[1,0]
	v_pk_add_f32 v[64:65], v[64:65], 1.0 op_sel_hi:[1,0]
	v_pk_mul_f32 v[70:71], v[0:1], v[70:71]
	v_pk_mul_f32 v[62:63], v[62:63], v[64:65]
	v_and_b32_e32 v65, 0xffff0000, v57
	v_and_b32_e32 v64, 0xffff0000, v56
	v_lshlrev_b32_e32 v57, 16, v57
	v_lshlrev_b32_e32 v56, 16, v56
	v_pk_fma_f32 v[56:57], v[88:89], v[56:57], v[64:65]
	v_pk_mul_f32 v[64:65], v[66:67], 0.5 op_sel_hi:[1,0]
	v_pk_mul_f32 v[56:57], v[56:57], v[62:63]
	v_pk_fma_f32 v[62:63], v[100:101], 2.0, 1.0 op_sel_hi:[1,0,0] neg_lo:[1,0,0] neg_hi:[1,0,0]
	s_nop 0
	v_pk_add_f32 v[62:63], v[62:63], 1.0 op_sel_hi:[1,0]
	s_nop 0
	v_pk_mul_f32 v[62:63], v[64:65], v[62:63]
	v_and_b32_e32 v65, 0xffff0000, v59
	v_and_b32_e32 v64, 0xffff0000, v58
	v_lshlrev_b32_e32 v59, 16, v59
	v_lshlrev_b32_e32 v58, 16, v58
	v_pk_fma_f32 v[58:59], v[86:87], v[58:59], v[64:65]
	v_mov_b32_e32 v64, v57
	v_pk_mul_f32 v[58:59], v[58:59], v[62:63]
	v_mov_b32_e32 v62, v56
	v_mov_b32_e32 v65, v59
	v_mov_b32_e32 v63, v58
	v_pk_mul_f32 v[64:65], v[64:65], v[64:65]
	s_nop 0
	v_pk_fma_f32 v[62:63], v[62:63], v[62:63], v[64:65]
	s_waitcnt vmcnt(18)
	v_lshlrev_b32_e32 v65, 16, v55
	v_add_f32_e32 v62, v62, v63
	v_and_b32_e32 v55, 0xffff0000, v55
	s_nop 0
	v_add_f32_dpp v62, v62, v62 quad_perm:[1,0,3,2] row_mask:0xf bank_mask:0xf bound_ctrl:1
	s_nop 1
	v_add_f32_dpp v62, v62, v62 quad_perm:[2,3,0,1] row_mask:0xf bank_mask:0xf bound_ctrl:1
	s_nop 1
	v_add_f32_dpp v62, v62, v62 row_half_mirror row_mask:0xf bank_mask:0xf bound_ctrl:1
	s_nop 1
	v_add_f32_dpp v62, v62, v62 row_mirror row_mask:0xf bank_mask:0xf bound_ctrl:1
	s_nop 0
	v_readlane_b32 s14, v62, 16
	v_readlane_b32 s15, v62, 48
	v_readlane_b32 s6, v62, 0
	v_readlane_b32 s7, v62, 32
	v_mov_b32_e32 v62, s14
	v_mov_b32_e32 v63, s15
	v_pk_add_f32 v[62:63], s[6:7], v[62:63]
	s_nop 0
	v_add_f32_e32 v62, v62, v63
	v_fmamk_f32 v62, v62, 0x3b800000, v109
	v_mul_f32_e32 v63, 0x4b800000, v62
	v_cmp_gt_f32_e32 vcc, s31, v62
	s_nop 1
	v_cndmask_b32_e32 v62, v62, v63, vcc
	v_rsq_f32_e32 v64, v62
	v_cvt_pk_bf16_f32 v62, v70, v71
	v_cvt_pk_bf16_f32 v63, v102, v103
	global_store_dwordx4 v[84:85], v[60:63], off offset:2560
	s_nop 1
	v_mul_f32_e32 v60, 0x45800000, v64
	v_cndmask_b32_e32 v60, v64, v60, vcc
	v_pk_mul_f32 v[58:59], v[58:59], v[60:61] op_sel_hi:[1,0]
	v_pk_mul_f32 v[56:57], v[56:57], v[60:61] op_sel_hi:[1,0]
	v_pk_mul_f32 v[58:59], v[10:11], v[58:59]
	v_pk_mul_f32 v[56:57], v[8:9], v[56:57]
	v_and_b32_e32 v63, 0xffff0000, v54
	v_cvt_pk_bf16_f32 v60, v56, v57
	v_cvt_pk_bf16_f32 v61, v58, v59
	v_lshlrev_b32_e32 v59, 16, v54
	v_and_b32_e32 v62, 0xffff0000, v52
	v_and_b32_e32 v54, 0xffff0000, v53
	v_lshlrev_b32_e32 v58, 16, v52
	v_lshlrev_b32_e32 v64, 16, v53
	v_pk_mul_f32 v[52:53], v[62:63], v[62:63]
	v_pk_mul_f32 v[66:67], v[54:55], v[54:55]
	v_pk_fma_f32 v[52:53], v[58:59], v[58:59], v[52:53]
	v_pk_fma_f32 v[66:67], v[64:65], v[64:65], v[66:67]
	v_add_co_u32_e32 v56, vcc, s34, v68
	v_pk_add_f32 v[52:53], v[52:53], v[66:67]
	s_nop 0
	v_addc_co_u32_e32 v57, vcc, 0, v69, vcc
	v_add_f32_e32 v52, v52, v53
	v_mov_b32_e32 v67, v62
	v_mov_b32_e32 v62, v59
	v_add_f32_dpp v52, v52, v52 quad_perm:[1,0,3,2] row_mask:0xf bank_mask:0xf bound_ctrl:1
	v_mov_b32_e32 v70, v64
	v_mov_b32_e32 v71, v54
	v_add_f32_dpp v52, v52, v52 quad_perm:[2,3,0,1] row_mask:0xf bank_mask:0xf bound_ctrl:1
	v_mov_b32_e32 v54, v65
	s_nop 0
	v_add_f32_dpp v52, v52, v52 row_half_mirror row_mask:0xf bank_mask:0xf bound_ctrl:1
	s_nop 1
	v_add_f32_dpp v52, v52, v52 row_mirror row_mask:0xf bank_mask:0xf bound_ctrl:1
	s_nop 0
	v_readlane_b32 s14, v52, 16
	v_readlane_b32 s15, v52, 48
	v_readlane_b32 s6, v52, 0
	v_readlane_b32 s7, v52, 32
	v_mov_b32_e32 v52, s14
	v_mov_b32_e32 v53, s15
	v_pk_add_f32 v[52:53], s[6:7], v[52:53]
	s_nop 0
	v_add_f32_e32 v52, v52, v53
	v_fmamk_f32 v52, v52, 0x3b000000, v109
	v_mul_f32_e32 v53, 0x4b800000, v52
	v_cmp_gt_f32_e32 vcc, s31, v52
	s_nop 1
	v_cndmask_b32_e32 v52, v52, v53, vcc
	v_rsq_f32_e32 v66, v52
	v_add_co_u32_e64 v52, s[6:7], s35, v68
	s_nop 1
	v_addc_co_u32_e64 v53, s[6:7], 0, v69, s[6:7]
	global_store_dwordx2 v[52:53], v[60:61], off offset:-4096
	v_mul_f32_e32 v60, 0x45800000, v66
	v_cndmask_b32_e32 v60, v66, v60, vcc
	v_mov_b32_e32 v66, v58
	v_pk_mul_f32 v[58:59], v[62:63], v[60:61] op_sel_hi:[1,0]
	s_waitcnt vmcnt(18)
	v_lshlrev_b32_e32 v62, 16, v98
	v_pk_mul_f32 v[66:67], v[66:67], v[60:61] op_sel_hi:[1,0]
	v_pk_mul_f32 v[70:71], v[70:71], v[60:61] op_sel_hi:[1,0]
	v_pk_mul_f32 v[54:55], v[54:55], v[60:61] op_sel_hi:[1,0]
	v_pk_mul_f32 v[60:61], v[0:1], v[58:59]
	v_mul_f32_e32 v58, 0x3d372713, v62
	v_mul_f32_e32 v58, v58, v62
	v_mov_b32_e32 v59, v62
	v_fmac_f32_e32 v59, v58, v59
	v_mul_f32_e32 v58, 0x3f4c422a, v59
	v_add_f32_e32 v58, v58, v58
	v_and_b32_e32 v63, 0xffff0000, v98
	v_mul_f32_e32 v58, 0x3fb8aa3b, v58
	v_exp_f32_e32 v59, v58
	v_mul_f32_e32 v58, 0x3d372713, v63
	v_mul_f32_e32 v58, v58, v63
	v_mov_b32_e32 v64, v63
	v_fmac_f32_e32 v64, v58, v64
	v_mul_f32_e32 v58, 0x3f4c422a, v64
	v_add_f32_e32 v58, v58, v58
	v_mul_f32_e32 v58, 0x3fb8aa3b, v58
	v_exp_f32_e32 v65, v58
	v_add_f32_e32 v59, 1.0, v59
	v_rcp_f32_e32 v64, v59
	v_pk_mul_f32 v[54:55], v[2:3], v[54:55]
	v_add_f32_e32 v59, 1.0, v65
	v_rcp_f32_e32 v65, v59
	v_pk_mul_f32 v[70:71], v[6:7], v[70:71]
	v_pk_mul_f32 v[66:67], v[4:5], v[66:67]
	v_pk_mul_f32 v[62:63], v[62:63], 0.5 op_sel_hi:[1,0]
	v_cvt_pk_bf16_f32 v58, v66, v67
	v_cvt_pk_bf16_f32 v59, v70, v71
	v_cvt_pk_bf16_f32 v60, v60, v61
	v_cvt_pk_bf16_f32 v61, v54, v55
	v_pk_fma_f32 v[54:55], v[64:65], 2.0, 1.0 op_sel_hi:[1,0,0] neg_lo:[1,0,0] neg_hi:[1,0,0]
	v_lshlrev_b32_e32 v64, 16, v99
	v_mul_f32_e32 v66, 0x3d372713, v64
	v_mul_f32_e32 v66, v66, v64
	v_mov_b32_e32 v67, v64
	v_and_b32_e32 v65, 0xffff0000, v99
	v_fmac_f32_e32 v67, v66, v67
	v_mul_f32_e32 v66, 0x3f4c422a, v67
	v_mul_f32_e32 v67, 0x3d372713, v65
	v_mul_f32_e32 v67, v67, v65
	v_mov_b32_e32 v70, v65
	v_fmac_f32_e32 v70, v67, v70
	v_mul_f32_e32 v67, 0x3f4c422a, v70
	v_add_f32_e32 v66, v66, v66
	v_add_f32_e32 v67, v67, v67
	v_mul_f32_e32 v66, 0x3fb8aa3b, v66
	v_mul_f32_e32 v67, 0x3fb8aa3b, v67
	v_exp_f32_e32 v66, v66
	v_exp_f32_e32 v67, v67
	v_pk_add_f32 v[54:55], v[54:55], 1.0 op_sel_hi:[1,0]
	v_add_f32_e32 v66, 1.0, v66
	v_add_f32_e32 v67, 1.0, v67
	v_rcp_f32_e32 v66, v66
	v_rcp_f32_e32 v67, v67
	v_pk_mul_f32 v[54:55], v[62:63], v[54:55]
	v_and_b32_e32 v63, 0xffff0000, v49
	v_and_b32_e32 v62, 0xffff0000, v48
	v_lshlrev_b32_e32 v49, 16, v49
	v_lshlrev_b32_e32 v48, 16, v48
	v_pk_fma_f32 v[48:49], v[88:89], v[48:49], v[62:63]
	v_pk_mul_f32 v[62:63], v[64:65], 0.5 op_sel_hi:[1,0]
	v_pk_mul_f32 v[48:49], v[48:49], v[54:55]
	v_pk_fma_f32 v[54:55], v[66:67], 2.0, 1.0 op_sel_hi:[1,0,0] neg_lo:[1,0,0] neg_hi:[1,0,0]
	s_nop 0
	v_pk_add_f32 v[54:55], v[54:55], 1.0 op_sel_hi:[1,0]
	s_nop 0
	v_pk_mul_f32 v[54:55], v[62:63], v[54:55]
	v_and_b32_e32 v63, 0xffff0000, v51
	v_and_b32_e32 v62, 0xffff0000, v50
	v_lshlrev_b32_e32 v51, 16, v51
	v_lshlrev_b32_e32 v50, 16, v50
	v_pk_fma_f32 v[50:51], v[86:87], v[50:51], v[62:63]
	v_mov_b32_e32 v62, v49
	v_pk_mul_f32 v[50:51], v[50:51], v[54:55]
	v_mov_b32_e32 v54, v48
	v_mov_b32_e32 v63, v51
	v_mov_b32_e32 v55, v50
	v_pk_mul_f32 v[62:63], v[62:63], v[62:63]
	s_nop 0
	v_pk_fma_f32 v[54:55], v[54:55], v[54:55], v[62:63]
	s_waitcnt vmcnt(17)
	v_lshlrev_b32_e32 v63, 16, v47
	v_add_f32_e32 v54, v54, v55
	v_and_b32_e32 v47, 0xffff0000, v47
	s_nop 0
	v_add_f32_dpp v54, v54, v54 quad_perm:[1,0,3,2] row_mask:0xf bank_mask:0xf bound_ctrl:1
	s_nop 1
	v_add_f32_dpp v54, v54, v54 quad_perm:[2,3,0,1] row_mask:0xf bank_mask:0xf bound_ctrl:1
	s_nop 1
	v_add_f32_dpp v54, v54, v54 row_half_mirror row_mask:0xf bank_mask:0xf bound_ctrl:1
	s_nop 1
	v_add_f32_dpp v54, v54, v54 row_mirror row_mask:0xf bank_mask:0xf bound_ctrl:1
	s_nop 0
	v_readlane_b32 s14, v54, 16
	v_readlane_b32 s15, v54, 48
	v_readlane_b32 s6, v54, 0
	v_readlane_b32 s7, v54, 32
	v_mov_b32_e32 v54, s14
	v_mov_b32_e32 v55, s15
	v_pk_add_f32 v[54:55], s[6:7], v[54:55]
	s_nop 0
	v_add_f32_e32 v54, v54, v55
	v_fmamk_f32 v54, v54, 0x3b800000, v109
	v_mul_f32_e32 v55, 0x4b800000, v54
	v_cmp_gt_f32_e32 vcc, s31, v54
	s_nop 1
	v_cndmask_b32_e32 v54, v54, v55, vcc
	v_rsq_f32_e32 v62, v54
	v_add_co_u32_e64 v54, s[6:7], s34, v84
	s_nop 1
	v_addc_co_u32_e64 v55, s[6:7], 0, v85, s[6:7]
	global_store_dwordx4 v[54:55], v[58:61], off offset:512
	s_nop 1
	v_mul_f32_e32 v58, 0x45800000, v62
	v_cndmask_b32_e32 v58, v62, v58, vcc
	v_pk_mul_f32 v[48:49], v[48:49], v[58:59] op_sel_hi:[1,0]
	v_pk_mul_f32 v[50:51], v[50:51], v[58:59] op_sel_hi:[1,0]
	v_lshlrev_b32_e32 v59, 16, v46
	v_and_b32_e32 v61, 0xffff0000, v46
	v_and_b32_e32 v60, 0xffff0000, v44
	v_and_b32_e32 v46, 0xffff0000, v45
	v_lshlrev_b32_e32 v58, 16, v44
	v_lshlrev_b32_e32 v62, 16, v45
	v_pk_mul_f32 v[44:45], v[60:61], v[60:61]
	v_pk_mul_f32 v[64:65], v[46:47], v[46:47]
	v_pk_fma_f32 v[44:45], v[58:59], v[58:59], v[44:45]
	v_pk_fma_f32 v[64:65], v[62:63], v[62:63], v[64:65]
	v_pk_mul_f32 v[48:49], v[8:9], v[48:49]
	v_pk_add_f32 v[44:45], v[44:45], v[64:65]
	v_pk_mul_f32 v[50:51], v[10:11], v[50:51]
	v_add_f32_e32 v44, v44, v45
	s_nop 1
	v_add_f32_dpp v44, v44, v44 quad_perm:[1,0,3,2] row_mask:0xf bank_mask:0xf bound_ctrl:1
	s_nop 1
	v_add_f32_dpp v44, v44, v44 quad_perm:[2,3,0,1] row_mask:0xf bank_mask:0xf bound_ctrl:1
	s_nop 1
	v_add_f32_dpp v44, v44, v44 row_half_mirror row_mask:0xf bank_mask:0xf bound_ctrl:1
	s_nop 1
	v_add_f32_dpp v44, v44, v44 row_mirror row_mask:0xf bank_mask:0xf bound_ctrl:1
	s_nop 0
	v_readlane_b32 s14, v44, 16
	v_readlane_b32 s15, v44, 48
	v_readlane_b32 s6, v44, 0
	v_readlane_b32 s7, v44, 32
	v_mov_b32_e32 v44, s14
	v_mov_b32_e32 v45, s15
	v_pk_add_f32 v[44:45], s[6:7], v[44:45]
	s_nop 0
	v_add_f32_e32 v44, v44, v45
	v_fmamk_f32 v44, v44, 0x3b000000, v109
	v_mul_f32_e32 v45, 0x4b800000, v44
	v_cmp_gt_f32_e32 vcc, s31, v44
	s_nop 1
	v_cndmask_b32_e32 v44, v44, v45, vcc
	v_rsq_f32_e32 v64, v44
	v_cvt_pk_bf16_f32 v44, v48, v49
	v_cvt_pk_bf16_f32 v45, v50, v51
	global_store_dwordx2 v[56:57], v[44:45], off offset:2048
	v_mul_f32_e32 v44, 0x45800000, v64
	v_cndmask_b32_e32 v44, v64, v44, vcc
	v_mov_b32_e32 v48, v58
	v_mov_b32_e32 v49, v60
	v_mov_b32_e32 v50, v62
	v_mov_b32_e32 v51, v46
	v_mov_b32_e32 v60, v59
	v_mov_b32_e32 v46, v63
	v_pk_mul_f32 v[48:49], v[48:49], v[44:45] op_sel_hi:[1,0]
	v_pk_mul_f32 v[50:51], v[50:51], v[44:45] op_sel_hi:[1,0]
	v_pk_mul_f32 v[56:57], v[60:61], v[44:45] op_sel_hi:[1,0]
	v_pk_mul_f32 v[44:45], v[46:47], v[44:45] op_sel_hi:[1,0]
	s_waitcnt vmcnt(17)
	v_lshlrev_b32_e32 v46, 16, v96
	v_mul_f32_e32 v58, 0x3d372713, v46
	v_mul_f32_e32 v58, v58, v46
	v_mov_b32_e32 v59, v46
	v_fmac_f32_e32 v59, v58, v59
	v_mul_f32_e32 v58, 0x3f4c422a, v59
	v_add_f32_e32 v58, v58, v58
	v_and_b32_e32 v47, 0xffff0000, v96
	v_mul_f32_e32 v58, 0x3fb8aa3b, v58
	v_exp_f32_e32 v60, v58
	v_mul_f32_e32 v58, 0x3d372713, v47
	v_mul_f32_e32 v58, v58, v47
	v_mov_b32_e32 v59, v47
	v_fmac_f32_e32 v59, v58, v59
	v_mul_f32_e32 v58, 0x3f4c422a, v59
	v_add_f32_e32 v58, v58, v58
	v_mul_f32_e32 v58, 0x3fb8aa3b, v58
	v_exp_f32_e32 v61, v58
	v_pk_mul_f32 v[58:59], v[2:3], v[44:45]
	v_add_f32_e32 v44, 1.0, v60
	v_rcp_f32_e32 v60, v44
	v_add_f32_e32 v44, 1.0, v61
	v_rcp_f32_e32 v61, v44
	v_pk_mul_f32 v[50:51], v[6:7], v[50:51]
	v_pk_mul_f32 v[48:49], v[4:5], v[48:49]
	v_pk_mul_f32 v[46:47], v[46:47], 0.5 op_sel_hi:[1,0]
	v_cvt_pk_bf16_f32 v44, v48, v49
	v_cvt_pk_bf16_f32 v45, v50, v51
	v_lshlrev_b32_e32 v50, 16, v97
	v_pk_fma_f32 v[48:49], v[60:61], 2.0, 1.0 op_sel_hi:[1,0,0] neg_lo:[1,0,0] neg_hi:[1,0,0]
	v_mul_f32_e32 v60, 0x3d372713, v50
	v_mul_f32_e32 v60, v60, v50
	v_mov_b32_e32 v61, v50
	v_and_b32_e32 v51, 0xffff0000, v97
	v_fmac_f32_e32 v61, v60, v61
	v_mul_f32_e32 v60, 0x3f4c422a, v61
	v_mul_f32_e32 v61, 0x3d372713, v51
	v_mul_f32_e32 v61, v61, v51
	v_mov_b32_e32 v62, v51
	v_fmac_f32_e32 v62, v61, v62
	v_mul_f32_e32 v61, 0x3f4c422a, v62
	v_add_f32_e32 v60, v60, v60
	v_add_f32_e32 v61, v61, v61
	v_mul_f32_e32 v60, 0x3fb8aa3b, v60
	v_mul_f32_e32 v61, 0x3fb8aa3b, v61
	v_exp_f32_e32 v60, v60
	v_exp_f32_e32 v61, v61
	v_pk_add_f32 v[48:49], v[48:49], 1.0 op_sel_hi:[1,0]
	v_pk_mul_f32 v[56:57], v[0:1], v[56:57]
	v_add_f32_e32 v60, 1.0, v60
	v_add_f32_e32 v61, 1.0, v61
	v_rcp_f32_e32 v60, v60
	v_rcp_f32_e32 v61, v61
	v_pk_mul_f32 v[46:47], v[46:47], v[48:49]
	v_and_b32_e32 v49, 0xffff0000, v41
	v_and_b32_e32 v48, 0xffff0000, v40
	v_lshlrev_b32_e32 v41, 16, v41
	v_lshlrev_b32_e32 v40, 16, v40
	v_pk_fma_f32 v[40:41], v[88:89], v[40:41], v[48:49]
	v_pk_mul_f32 v[48:49], v[50:51], 0.5 op_sel_hi:[1,0]
	v_pk_mul_f32 v[40:41], v[40:41], v[46:47]
	v_pk_fma_f32 v[46:47], v[60:61], 2.0, 1.0 op_sel_hi:[1,0,0] neg_lo:[1,0,0] neg_hi:[1,0,0]
	s_nop 0
	v_pk_add_f32 v[46:47], v[46:47], 1.0 op_sel_hi:[1,0]
	s_nop 0
	v_pk_mul_f32 v[46:47], v[48:49], v[46:47]
	v_and_b32_e32 v49, 0xffff0000, v43
	v_and_b32_e32 v48, 0xffff0000, v42
	v_lshlrev_b32_e32 v43, 16, v43
	v_lshlrev_b32_e32 v42, 16, v42
	v_pk_fma_f32 v[42:43], v[86:87], v[42:43], v[48:49]
	v_mov_b32_e32 v48, v41
	v_pk_mul_f32 v[42:43], v[42:43], v[46:47]
	v_mov_b32_e32 v46, v40
	v_mov_b32_e32 v49, v43
	v_mov_b32_e32 v47, v42
	v_pk_mul_f32 v[48:49], v[48:49], v[48:49]
	s_nop 0
	v_pk_fma_f32 v[46:47], v[46:47], v[46:47], v[48:49]
	s_waitcnt vmcnt(16)
	v_lshlrev_b32_e32 v49, 16, v39
	v_add_f32_e32 v46, v46, v47
	v_and_b32_e32 v39, 0xffff0000, v39
	s_nop 0
	v_add_f32_dpp v46, v46, v46 quad_perm:[1,0,3,2] row_mask:0xf bank_mask:0xf bound_ctrl:1
	s_nop 1
	v_add_f32_dpp v46, v46, v46 quad_perm:[2,3,0,1] row_mask:0xf bank_mask:0xf bound_ctrl:1
	s_nop 1
	v_add_f32_dpp v46, v46, v46 row_half_mirror row_mask:0xf bank_mask:0xf bound_ctrl:1
	s_nop 1
	v_add_f32_dpp v46, v46, v46 row_mirror row_mask:0xf bank_mask:0xf bound_ctrl:1
	s_nop 0
	v_readlane_b32 s14, v46, 16
	v_readlane_b32 s15, v46, 48
	v_readlane_b32 s6, v46, 0
	v_readlane_b32 s7, v46, 32
	v_mov_b32_e32 v46, s14
	v_mov_b32_e32 v47, s15
	v_pk_add_f32 v[46:47], s[6:7], v[46:47]
	s_nop 0
	v_add_f32_e32 v46, v46, v47
	v_fmamk_f32 v46, v46, 0x3b800000, v109
	v_mul_f32_e32 v47, 0x4b800000, v46
	v_cmp_gt_f32_e32 vcc, s31, v46
	s_nop 1
	v_cndmask_b32_e32 v46, v46, v47, vcc
	v_rsq_f32_e32 v48, v46
	v_cvt_pk_bf16_f32 v46, v56, v57
	v_cvt_pk_bf16_f32 v47, v58, v59
	global_store_dwordx4 v[54:55], v[44:47], off offset:2560
	s_nop 1
	v_mul_f32_e32 v44, 0x45800000, v48
	v_cndmask_b32_e32 v44, v48, v44, vcc
	v_pk_mul_f32 v[40:41], v[40:41], v[44:45] op_sel_hi:[1,0]
	v_pk_mul_f32 v[42:43], v[42:43], v[44:45] op_sel_hi:[1,0]
	v_lshlrev_b32_e32 v45, 16, v38
	v_and_b32_e32 v47, 0xffff0000, v38
	v_and_b32_e32 v46, 0xffff0000, v36
	v_and_b32_e32 v38, 0xffff0000, v37
	v_lshlrev_b32_e32 v44, 16, v36
	v_lshlrev_b32_e32 v48, 16, v37
	v_pk_mul_f32 v[36:37], v[46:47], v[46:47]
	v_pk_mul_f32 v[50:51], v[38:39], v[38:39]
	v_pk_fma_f32 v[36:37], v[44:45], v[44:45], v[36:37]
	v_pk_fma_f32 v[50:51], v[48:49], v[48:49], v[50:51]
	v_pk_mul_f32 v[40:41], v[8:9], v[40:41]
	v_pk_add_f32 v[36:37], v[36:37], v[50:51]
	v_pk_mul_f32 v[42:43], v[10:11], v[42:43]
	v_add_f32_e32 v36, v36, v37
	s_nop 1
	v_add_f32_dpp v36, v36, v36 quad_perm:[1,0,3,2] row_mask:0xf bank_mask:0xf bound_ctrl:1
	s_nop 1
	v_add_f32_dpp v36, v36, v36 quad_perm:[2,3,0,1] row_mask:0xf bank_mask:0xf bound_ctrl:1
	s_nop 1
	v_add_f32_dpp v36, v36, v36 row_half_mirror row_mask:0xf bank_mask:0xf bound_ctrl:1
	s_nop 1
	v_add_f32_dpp v36, v36, v36 row_mirror row_mask:0xf bank_mask:0xf bound_ctrl:1
	s_nop 0
	v_readlane_b32 s14, v36, 16
	v_readlane_b32 s15, v36, 48
	v_readlane_b32 s6, v36, 0
	v_readlane_b32 s7, v36, 32
	v_mov_b32_e32 v36, s14
	v_mov_b32_e32 v37, s15
	v_pk_add_f32 v[36:37], s[6:7], v[36:37]
	s_nop 0
	v_add_f32_e32 v36, v36, v37
	v_fmamk_f32 v36, v36, 0x3b000000, v109
	v_mul_f32_e32 v37, 0x4b800000, v36
	v_cmp_gt_f32_e32 vcc, s31, v36
	s_nop 1
	v_cndmask_b32_e32 v36, v36, v37, vcc
	v_rsq_f32_e32 v50, v36
	v_cvt_pk_bf16_f32 v36, v40, v41
	v_cvt_pk_bf16_f32 v37, v42, v43
	global_store_dwordx2 v[52:53], v[36:37], off
	v_mul_f32_e32 v36, 0x45800000, v50
	v_cndmask_b32_e32 v36, v50, v36, vcc
	v_mov_b32_e32 v41, v46
	v_mov_b32_e32 v46, v45
	v_mov_b32_e32 v40, v44
	v_mov_b32_e32 v42, v48
	v_mov_b32_e32 v43, v38
	v_pk_mul_f32 v[44:45], v[46:47], v[36:37] op_sel_hi:[1,0]
	v_mov_b32_e32 v38, v49
	v_pk_mul_f32 v[40:41], v[40:41], v[36:37] op_sel_hi:[1,0]
	v_pk_mul_f32 v[42:43], v[42:43], v[36:37] op_sel_hi:[1,0]
	v_pk_mul_f32 v[36:37], v[38:39], v[36:37] op_sel_hi:[1,0]
	v_pk_mul_f32 v[38:39], v[0:1], v[44:45]
	s_waitcnt vmcnt(16)
	v_lshlrev_b32_e32 v44, 16, v94
	v_pk_mul_f32 v[46:47], v[2:3], v[36:37]
	v_mul_f32_e32 v36, 0x3d372713, v44
	v_mul_f32_e32 v36, v36, v44
	v_mov_b32_e32 v37, v44
	v_fmac_f32_e32 v37, v36, v37
	v_mul_f32_e32 v36, 0x3f4c422a, v37
	v_add_f32_e32 v36, v36, v36
	v_and_b32_e32 v45, 0xffff0000, v94
	v_mul_f32_e32 v36, 0x3fb8aa3b, v36
	v_exp_f32_e32 v37, v36
	v_mul_f32_e32 v36, 0x3d372713, v45
	v_mul_f32_e32 v36, v36, v45
	v_mov_b32_e32 v48, v45
	v_fmac_f32_e32 v48, v36, v48
	v_mul_f32_e32 v36, 0x3f4c422a, v48
	v_add_f32_e32 v36, v36, v36
	v_mul_f32_e32 v36, 0x3fb8aa3b, v36
	v_exp_f32_e32 v48, v36
	v_pk_mul_f32 v[40:41], v[4:5], v[40:41]
	v_add_f32_e32 v37, 1.0, v37
	v_pk_mul_f32 v[42:43], v[6:7], v[42:43]
	v_cvt_pk_bf16_f32 v36, v40, v41
	v_rcp_f32_e32 v40, v37
	v_add_f32_e32 v37, 1.0, v48
	v_rcp_f32_e32 v41, v37
	v_cvt_pk_bf16_f32 v37, v42, v43
	v_pk_mul_f32 v[42:43], v[44:45], 0.5 op_sel_hi:[1,0]
	v_lshlrev_b32_e32 v44, 16, v95
	v_cvt_pk_bf16_f32 v38, v38, v39
	v_cvt_pk_bf16_f32 v39, v46, v47
	v_mul_f32_e32 v46, 0x3d372713, v44
	v_mul_f32_e32 v46, v46, v44
	v_mov_b32_e32 v47, v44
	v_and_b32_e32 v45, 0xffff0000, v95
	v_fmac_f32_e32 v47, v46, v47
	v_mul_f32_e32 v46, 0x3f4c422a, v47
	v_mul_f32_e32 v47, 0x3d372713, v45
	v_mul_f32_e32 v47, v47, v45
	v_mov_b32_e32 v48, v45
	v_fmac_f32_e32 v48, v47, v48
	v_mul_f32_e32 v47, 0x3f4c422a, v48
	v_add_f32_e32 v46, v46, v46
	v_add_f32_e32 v47, v47, v47
	v_mul_f32_e32 v46, 0x3fb8aa3b, v46
	v_mul_f32_e32 v47, 0x3fb8aa3b, v47
	v_exp_f32_e32 v46, v46
	v_exp_f32_e32 v47, v47
	v_pk_fma_f32 v[40:41], v[40:41], 2.0, 1.0 op_sel_hi:[1,0,0] neg_lo:[1,0,0] neg_hi:[1,0,0]
	v_add_f32_e32 v46, 1.0, v46
	v_add_f32_e32 v47, 1.0, v47
	v_rcp_f32_e32 v46, v46
	v_rcp_f32_e32 v47, v47
	v_pk_add_f32 v[40:41], v[40:41], 1.0 op_sel_hi:[1,0]
	s_nop 0
	v_pk_mul_f32 v[40:41], v[42:43], v[40:41]
	v_and_b32_e32 v43, 0xffff0000, v33
	v_and_b32_e32 v42, 0xffff0000, v32
	v_lshlrev_b32_e32 v33, 16, v33
	v_lshlrev_b32_e32 v32, 16, v32
	v_pk_fma_f32 v[32:33], v[88:89], v[32:33], v[42:43]
	v_pk_mul_f32 v[42:43], v[44:45], 0.5 op_sel_hi:[1,0]
	v_pk_mul_f32 v[32:33], v[32:33], v[40:41]
	v_pk_fma_f32 v[40:41], v[46:47], 2.0, 1.0 op_sel_hi:[1,0,0] neg_lo:[1,0,0] neg_hi:[1,0,0]
	s_nop 0
	v_pk_add_f32 v[40:41], v[40:41], 1.0 op_sel_hi:[1,0]
	s_nop 0
	v_pk_mul_f32 v[40:41], v[42:43], v[40:41]
	v_and_b32_e32 v43, 0xffff0000, v35
	v_and_b32_e32 v42, 0xffff0000, v34
	v_lshlrev_b32_e32 v35, 16, v35
	v_lshlrev_b32_e32 v34, 16, v34
	v_pk_fma_f32 v[34:35], v[86:87], v[34:35], v[42:43]
	v_mov_b32_e32 v42, v33
	v_pk_mul_f32 v[34:35], v[34:35], v[40:41]
	v_mov_b32_e32 v40, v32
	v_mov_b32_e32 v43, v35
	v_mov_b32_e32 v41, v34
	v_pk_mul_f32 v[42:43], v[42:43], v[42:43]
	s_nop 0
	v_pk_fma_f32 v[40:41], v[40:41], v[40:41], v[42:43]
	s_waitcnt vmcnt(15)
	v_lshlrev_b32_e32 v43, 16, v31
	v_add_f32_e32 v40, v40, v41
	v_and_b32_e32 v31, 0xffff0000, v31
	s_nop 0
	v_add_f32_dpp v40, v40, v40 quad_perm:[1,0,3,2] row_mask:0xf bank_mask:0xf bound_ctrl:1
	s_nop 1
	v_add_f32_dpp v40, v40, v40 quad_perm:[2,3,0,1] row_mask:0xf bank_mask:0xf bound_ctrl:1
	s_nop 1
	v_add_f32_dpp v40, v40, v40 row_half_mirror row_mask:0xf bank_mask:0xf bound_ctrl:1
	s_nop 1
	v_add_f32_dpp v40, v40, v40 row_mirror row_mask:0xf bank_mask:0xf bound_ctrl:1
	s_nop 0
	v_readlane_b32 s14, v40, 16
	v_readlane_b32 s15, v40, 48
	v_readlane_b32 s6, v40, 0
	v_readlane_b32 s7, v40, 32
	v_mov_b32_e32 v40, s14
	v_mov_b32_e32 v41, s15
	v_pk_add_f32 v[40:41], s[6:7], v[40:41]
	s_nop 0
	v_add_f32_e32 v40, v40, v41
	v_fmamk_f32 v40, v40, 0x3b800000, v109
	v_mul_f32_e32 v41, 0x4b800000, v40
	v_cmp_gt_f32_e32 vcc, s31, v40
	s_nop 1
	v_cndmask_b32_e32 v40, v40, v41, vcc
	v_rsq_f32_e32 v42, v40
	v_add_co_u32_e64 v40, s[6:7], s35, v84
	s_nop 1
	v_addc_co_u32_e64 v41, s[6:7], 0, v85, s[6:7]
	global_store_dwordx4 v[40:41], v[36:39], off offset:512
	s_nop 1
	v_mul_f32_e32 v36, 0x45800000, v42
	v_cndmask_b32_e32 v36, v42, v36, vcc
	v_pk_mul_f32 v[32:33], v[32:33], v[36:37] op_sel_hi:[1,0]
	v_pk_mul_f32 v[34:35], v[34:35], v[36:37] op_sel_hi:[1,0]
	v_lshlrev_b32_e32 v37, 16, v30
	v_and_b32_e32 v39, 0xffff0000, v30
	v_and_b32_e32 v38, 0xffff0000, v28
	v_and_b32_e32 v30, 0xffff0000, v29
	v_lshlrev_b32_e32 v36, 16, v28
	v_lshlrev_b32_e32 v42, 16, v29
	v_pk_mul_f32 v[28:29], v[38:39], v[38:39]
	v_pk_mul_f32 v[44:45], v[30:31], v[30:31]
	v_pk_fma_f32 v[28:29], v[36:37], v[36:37], v[28:29]
	v_pk_fma_f32 v[44:45], v[42:43], v[42:43], v[44:45]
	v_pk_mul_f32 v[32:33], v[8:9], v[32:33]
	v_pk_add_f32 v[28:29], v[28:29], v[44:45]
	v_pk_mul_f32 v[34:35], v[10:11], v[34:35]
	v_add_f32_e32 v28, v28, v29
	s_nop 1
	v_add_f32_dpp v28, v28, v28 quad_perm:[1,0,3,2] row_mask:0xf bank_mask:0xf bound_ctrl:1
	s_nop 1
	v_add_f32_dpp v28, v28, v28 quad_perm:[2,3,0,1] row_mask:0xf bank_mask:0xf bound_ctrl:1
	s_nop 1
	v_add_f32_dpp v28, v28, v28 row_half_mirror row_mask:0xf bank_mask:0xf bound_ctrl:1
	s_nop 1
	v_add_f32_dpp v28, v28, v28 row_mirror row_mask:0xf bank_mask:0xf bound_ctrl:1
	s_nop 0
	v_readlane_b32 s14, v28, 16
	v_readlane_b32 s15, v28, 48
	v_readlane_b32 s6, v28, 0
	v_readlane_b32 s7, v28, 32
	v_mov_b32_e32 v28, s14
	v_mov_b32_e32 v29, s15
	v_pk_add_f32 v[28:29], s[6:7], v[28:29]
	s_nop 0
	v_add_f32_e32 v28, v28, v29
	v_fmamk_f32 v28, v28, 0x3b000000, v109
	v_mul_f32_e32 v29, 0x4b800000, v28
	v_cmp_gt_f32_e32 vcc, s31, v28
	s_nop 1
	v_cndmask_b32_e32 v28, v28, v29, vcc
	v_rsq_f32_e32 v44, v28
	v_cvt_pk_bf16_f32 v28, v32, v33
	v_cvt_pk_bf16_f32 v29, v34, v35
	global_store_dwordx2 v[52:53], v[28:29], off offset:2048
	v_mul_f32_e32 v28, 0x45800000, v44
	v_cndmask_b32_e32 v28, v44, v28, vcc
	v_mov_b32_e32 v32, v36
	v_mov_b32_e32 v33, v38
	v_mov_b32_e32 v34, v42
	v_mov_b32_e32 v35, v30
	v_mov_b32_e32 v38, v37
	v_mov_b32_e32 v30, v43
	v_pk_mul_f32 v[32:33], v[32:33], v[28:29] op_sel_hi:[1,0]
	v_pk_mul_f32 v[34:35], v[34:35], v[28:29] op_sel_hi:[1,0]
	v_pk_mul_f32 v[36:37], v[38:39], v[28:29] op_sel_hi:[1,0]
	v_pk_mul_f32 v[28:29], v[30:31], v[28:29] op_sel_hi:[1,0]
	s_waitcnt vmcnt(15)
	v_lshlrev_b32_e32 v30, 16, v92
	v_mul_f32_e32 v38, 0x3d372713, v30
	v_mul_f32_e32 v38, v38, v30
	v_mov_b32_e32 v39, v30
	v_fmac_f32_e32 v39, v38, v39
	v_mul_f32_e32 v38, 0x3f4c422a, v39
	v_add_f32_e32 v38, v38, v38
	v_and_b32_e32 v31, 0xffff0000, v92
	v_mul_f32_e32 v38, 0x3fb8aa3b, v38
	v_exp_f32_e32 v42, v38
	v_mul_f32_e32 v38, 0x3d372713, v31
	v_mul_f32_e32 v38, v38, v31
	v_mov_b32_e32 v39, v31
	v_fmac_f32_e32 v39, v38, v39
	v_mul_f32_e32 v38, 0x3f4c422a, v39
	v_add_f32_e32 v38, v38, v38
	v_mul_f32_e32 v38, 0x3fb8aa3b, v38
	v_exp_f32_e32 v43, v38
	v_pk_mul_f32 v[38:39], v[2:3], v[28:29]
	v_add_f32_e32 v28, 1.0, v42
	v_rcp_f32_e32 v42, v28
	v_add_f32_e32 v28, 1.0, v43
	v_rcp_f32_e32 v43, v28
	v_pk_mul_f32 v[34:35], v[6:7], v[34:35]
	v_pk_mul_f32 v[32:33], v[4:5], v[32:33]
	v_pk_mul_f32 v[30:31], v[30:31], 0.5 op_sel_hi:[1,0]
	v_cvt_pk_bf16_f32 v28, v32, v33
	v_cvt_pk_bf16_f32 v29, v34, v35
	v_lshlrev_b32_e32 v34, 16, v93
	v_pk_fma_f32 v[32:33], v[42:43], 2.0, 1.0 op_sel_hi:[1,0,0] neg_lo:[1,0,0] neg_hi:[1,0,0]
	v_mul_f32_e32 v42, 0x3d372713, v34
	v_mul_f32_e32 v42, v42, v34
	v_mov_b32_e32 v43, v34
	v_and_b32_e32 v35, 0xffff0000, v93
	v_fmac_f32_e32 v43, v42, v43
	v_mul_f32_e32 v42, 0x3f4c422a, v43
	v_mul_f32_e32 v43, 0x3d372713, v35
	v_mul_f32_e32 v43, v43, v35
	v_mov_b32_e32 v44, v35
	v_fmac_f32_e32 v44, v43, v44
	v_mul_f32_e32 v43, 0x3f4c422a, v44
	v_add_f32_e32 v42, v42, v42
	v_add_f32_e32 v43, v43, v43
	v_mul_f32_e32 v42, 0x3fb8aa3b, v42
	v_mul_f32_e32 v43, 0x3fb8aa3b, v43
	v_exp_f32_e32 v42, v42
	v_exp_f32_e32 v43, v43
	v_pk_add_f32 v[32:33], v[32:33], 1.0 op_sel_hi:[1,0]
	v_pk_mul_f32 v[36:37], v[0:1], v[36:37]
	v_add_f32_e32 v42, 1.0, v42
	v_add_f32_e32 v43, 1.0, v43
	v_rcp_f32_e32 v42, v42
	v_rcp_f32_e32 v43, v43
	v_pk_mul_f32 v[30:31], v[30:31], v[32:33]
	v_and_b32_e32 v33, 0xffff0000, v25
	v_and_b32_e32 v32, 0xffff0000, v24
	v_lshlrev_b32_e32 v25, 16, v25
	v_lshlrev_b32_e32 v24, 16, v24
	v_pk_fma_f32 v[24:25], v[88:89], v[24:25], v[32:33]
	v_pk_mul_f32 v[32:33], v[34:35], 0.5 op_sel_hi:[1,0]
	v_pk_mul_f32 v[24:25], v[24:25], v[30:31]
	v_pk_fma_f32 v[30:31], v[42:43], 2.0, 1.0 op_sel_hi:[1,0,0] neg_lo:[1,0,0] neg_hi:[1,0,0]
	s_nop 0
	v_pk_add_f32 v[30:31], v[30:31], 1.0 op_sel_hi:[1,0]
	s_nop 0
	v_pk_mul_f32 v[30:31], v[32:33], v[30:31]
	v_and_b32_e32 v33, 0xffff0000, v27
	v_and_b32_e32 v32, 0xffff0000, v26
	v_lshlrev_b32_e32 v27, 16, v27
	v_lshlrev_b32_e32 v26, 16, v26
	v_pk_fma_f32 v[26:27], v[86:87], v[26:27], v[32:33]
	v_mov_b32_e32 v32, v25
	v_pk_mul_f32 v[26:27], v[26:27], v[30:31]
	v_mov_b32_e32 v30, v24
	v_mov_b32_e32 v33, v27
	v_mov_b32_e32 v31, v26
	v_pk_mul_f32 v[32:33], v[32:33], v[32:33]
	s_nop 0
	v_pk_fma_f32 v[30:31], v[30:31], v[30:31], v[32:33]
	s_nop 0
	v_add_f32_e32 v30, v30, v31
	s_nop 1
	v_add_f32_dpp v30, v30, v30 quad_perm:[1,0,3,2] row_mask:0xf bank_mask:0xf bound_ctrl:1
	s_nop 1
	v_add_f32_dpp v30, v30, v30 quad_perm:[2,3,0,1] row_mask:0xf bank_mask:0xf bound_ctrl:1
	s_nop 1
	v_add_f32_dpp v30, v30, v30 row_half_mirror row_mask:0xf bank_mask:0xf bound_ctrl:1
	s_nop 1
	v_add_f32_dpp v30, v30, v30 row_mirror row_mask:0xf bank_mask:0xf bound_ctrl:1
	s_nop 0
	v_readlane_b32 s14, v30, 16
	v_readlane_b32 s15, v30, 48
	v_readlane_b32 s6, v30, 0
	v_readlane_b32 s7, v30, 32
	v_mov_b32_e32 v30, s14
	v_mov_b32_e32 v31, s15
	v_pk_add_f32 v[30:31], s[6:7], v[30:31]
	s_nop 0
	v_add_f32_e32 v30, v30, v31
	v_fmamk_f32 v30, v30, 0x3b800000, v109
	v_mul_f32_e32 v31, 0x4b800000, v30
	v_cmp_gt_f32_e32 vcc, s31, v30
	s_nop 1
	v_cndmask_b32_e32 v30, v30, v31, vcc
	v_rsq_f32_e32 v32, v30
	v_cvt_pk_bf16_f32 v30, v36, v37
	v_cvt_pk_bf16_f32 v31, v38, v39
	global_store_dwordx4 v[40:41], v[28:31], off offset:2560
	s_nop 1
	v_mul_f32_e32 v28, 0x45800000, v32
	v_cndmask_b32_e32 v28, v32, v28, vcc
	v_pk_mul_f32 v[24:25], v[24:25], v[28:29] op_sel_hi:[1,0]
	v_pk_mul_f32 v[26:27], v[26:27], v[28:29] op_sel_hi:[1,0]
	v_pk_mul_f32 v[24:25], v[8:9], v[24:25]
	v_pk_mul_f32 v[26:27], v[10:11], v[26:27]
	v_cvt_pk_bf16_f32 v24, v24, v25
	s_waitcnt vmcnt(15)
	v_and_b32_e32 v29, 0xffff0000, v22
	v_cvt_pk_bf16_f32 v25, v26, v27
	v_lshlrev_b32_e32 v27, 16, v22
	v_and_b32_e32 v28, 0xffff0000, v20
	v_lshlrev_b32_e32 v31, 16, v23
	v_and_b32_e32 v23, 0xffff0000, v23
	v_and_b32_e32 v22, 0xffff0000, v21
	v_lshlrev_b32_e32 v26, 16, v20
	v_lshlrev_b32_e32 v30, 16, v21
	v_pk_mul_f32 v[20:21], v[28:29], v[28:29]
	v_pk_mul_f32 v[32:33], v[22:23], v[22:23]
	v_pk_fma_f32 v[20:21], v[26:27], v[26:27], v[20:21]
	v_pk_fma_f32 v[32:33], v[30:31], v[30:31], v[32:33]
	v_mov_b32_e32 v34, v30
	v_pk_add_f32 v[20:21], v[20:21], v[32:33]
	v_mov_b32_e32 v35, v22
	v_add_f32_e32 v20, v20, v21
	v_mov_b32_e32 v22, v31
	s_nop 0
	v_add_f32_dpp v20, v20, v20 quad_perm:[1,0,3,2] row_mask:0xf bank_mask:0xf bound_ctrl:1
	s_nop 1
	v_add_f32_dpp v20, v20, v20 quad_perm:[2,3,0,1] row_mask:0xf bank_mask:0xf bound_ctrl:1
	s_nop 1
	v_add_f32_dpp v20, v20, v20 row_half_mirror row_mask:0xf bank_mask:0xf bound_ctrl:1
	s_nop 1
	v_add_f32_dpp v20, v20, v20 row_mirror row_mask:0xf bank_mask:0xf bound_ctrl:1
	s_nop 0
	v_readlane_b32 s14, v20, 16
	v_readlane_b32 s15, v20, 48
	v_readlane_b32 s6, v20, 0
	v_readlane_b32 s7, v20, 32
	v_mov_b32_e32 v20, s14
	v_mov_b32_e32 v21, s15
	v_pk_add_f32 v[20:21], s[6:7], v[20:21]
	v_add_co_u32_e64 v32, s[6:7], s36, v68
	v_add_f32_e32 v20, v20, v21
	v_fmamk_f32 v20, v20, 0x3b000000, v109
	v_mul_f32_e32 v21, 0x4b800000, v20
	v_cmp_gt_f32_e32 vcc, s31, v20
	v_addc_co_u32_e64 v33, s[6:7], 0, v69, s[6:7]
	s_nop 0
	v_cndmask_b32_e32 v20, v20, v21, vcc
	v_rsq_f32_e32 v20, v20
	global_store_dwordx2 v[32:33], v[24:25], off
	v_mov_b32_e32 v25, v28
	v_mov_b32_e32 v28, v27
	v_mul_f32_e32 v21, 0x45800000, v20
	v_cndmask_b32_e32 v20, v20, v21, vcc
	v_mov_b32_e32 v24, v26
	v_pk_mul_f32 v[26:27], v[28:29], v[20:21] op_sel_hi:[1,0]
	v_pk_mul_f32 v[24:25], v[24:25], v[20:21] op_sel_hi:[1,0]
	v_pk_mul_f32 v[34:35], v[34:35], v[20:21] op_sel_hi:[1,0]
	v_pk_mul_f32 v[20:21], v[22:23], v[20:21] op_sel_hi:[1,0]
	v_pk_mul_f32 v[22:23], v[0:1], v[26:27]
	s_waitcnt vmcnt(14)
	v_lshlrev_b32_e32 v26, 16, v90
	v_pk_mul_f32 v[28:29], v[2:3], v[20:21]
	v_mul_f32_e32 v20, 0x3d372713, v26
	v_mul_f32_e32 v20, v20, v26
	v_mov_b32_e32 v21, v26
	v_fmac_f32_e32 v21, v20, v21
	v_mul_f32_e32 v20, 0x3f4c422a, v21
	v_add_f32_e32 v20, v20, v20
	v_and_b32_e32 v27, 0xffff0000, v90
	v_mul_f32_e32 v20, 0x3fb8aa3b, v20
	v_exp_f32_e32 v21, v20
	v_mul_f32_e32 v20, 0x3d372713, v27
	v_mul_f32_e32 v20, v20, v27
	v_mov_b32_e32 v30, v27
	v_fmac_f32_e32 v30, v20, v30
	v_mul_f32_e32 v20, 0x3f4c422a, v30
	v_add_f32_e32 v20, v20, v20
	v_mul_f32_e32 v20, 0x3fb8aa3b, v20
	v_exp_f32_e32 v30, v20
	v_pk_mul_f32 v[24:25], v[4:5], v[24:25]
	v_add_f32_e32 v21, 1.0, v21
	v_cvt_pk_bf16_f32 v20, v24, v25
	v_rcp_f32_e32 v24, v21
	v_add_f32_e32 v21, 1.0, v30
	v_pk_mul_f32 v[34:35], v[6:7], v[34:35]
	v_rcp_f32_e32 v25, v21
	v_cvt_pk_bf16_f32 v21, v34, v35
	v_cvt_pk_bf16_f32 v22, v22, v23
	v_cvt_pk_bf16_f32 v23, v28, v29
	v_lshlrev_b32_e32 v28, 16, v91
	v_mul_f32_e32 v30, 0x3d372713, v28
	v_mul_f32_e32 v30, v30, v28
	v_mov_b32_e32 v31, v28
	v_and_b32_e32 v29, 0xffff0000, v91
	v_fmac_f32_e32 v31, v30, v31
	v_mul_f32_e32 v30, 0x3f4c422a, v31
	v_mul_f32_e32 v31, 0x3d372713, v29
	v_mul_f32_e32 v31, v31, v29
	v_mov_b32_e32 v34, v29
	v_fmac_f32_e32 v34, v31, v34
	v_mul_f32_e32 v31, 0x3f4c422a, v34
	v_add_f32_e32 v30, v30, v30
	v_add_f32_e32 v31, v31, v31
	v_mul_f32_e32 v30, 0x3fb8aa3b, v30
	v_mul_f32_e32 v31, 0x3fb8aa3b, v31
	v_exp_f32_e32 v30, v30
	v_exp_f32_e32 v31, v31
	v_pk_fma_f32 v[24:25], v[24:25], 2.0, 1.0 op_sel_hi:[1,0,0] neg_lo:[1,0,0] neg_hi:[1,0,0]
	v_pk_mul_f32 v[26:27], v[26:27], 0.5 op_sel_hi:[1,0]
	v_add_f32_e32 v30, 1.0, v30
	v_add_f32_e32 v31, 1.0, v31
	v_rcp_f32_e32 v30, v30
	v_rcp_f32_e32 v31, v31
	v_pk_add_f32 v[24:25], v[24:25], 1.0 op_sel_hi:[1,0]
	s_nop 0
	v_pk_mul_f32 v[24:25], v[26:27], v[24:25]
	v_and_b32_e32 v27, 0xffff0000, v13
	v_and_b32_e32 v26, 0xffff0000, v12
	v_lshlrev_b32_e32 v13, 16, v13
	v_lshlrev_b32_e32 v12, 16, v12
	v_pk_fma_f32 v[12:13], v[88:89], v[12:13], v[26:27]
	v_pk_mul_f32 v[26:27], v[28:29], 0.5 op_sel_hi:[1,0]
	v_pk_mul_f32 v[12:13], v[12:13], v[24:25]
	v_pk_fma_f32 v[24:25], v[30:31], 2.0, 1.0 op_sel_hi:[1,0,0] neg_lo:[1,0,0] neg_hi:[1,0,0]
	s_nop 0
	v_pk_add_f32 v[24:25], v[24:25], 1.0 op_sel_hi:[1,0]
	s_nop 0
	v_pk_mul_f32 v[24:25], v[26:27], v[24:25]
	v_and_b32_e32 v27, 0xffff0000, v15
	v_and_b32_e32 v26, 0xffff0000, v14
	v_lshlrev_b32_e32 v15, 16, v15
	v_lshlrev_b32_e32 v14, 16, v14
	v_pk_fma_f32 v[14:15], v[86:87], v[14:15], v[26:27]
	v_mov_b32_e32 v26, v13
	v_pk_mul_f32 v[14:15], v[14:15], v[24:25]
	v_mov_b32_e32 v24, v12
	v_mov_b32_e32 v27, v15
	v_mov_b32_e32 v25, v14
	v_pk_mul_f32 v[26:27], v[26:27], v[26:27]
	s_nop 0
	v_pk_fma_f32 v[24:25], v[24:25], v[24:25], v[26:27]
	s_nop 0
	v_add_f32_e32 v24, v24, v25
	s_nop 1
	v_add_f32_dpp v24, v24, v24 quad_perm:[1,0,3,2] row_mask:0xf bank_mask:0xf bound_ctrl:1
	s_nop 1
	v_add_f32_dpp v24, v24, v24 quad_perm:[2,3,0,1] row_mask:0xf bank_mask:0xf bound_ctrl:1
	s_nop 1
	v_add_f32_dpp v24, v24, v24 row_half_mirror row_mask:0xf bank_mask:0xf bound_ctrl:1
	s_nop 1
	v_add_f32_dpp v24, v24, v24 row_mirror row_mask:0xf bank_mask:0xf bound_ctrl:1
	s_nop 0
	v_readlane_b32 s14, v24, 16
	v_readlane_b32 s15, v24, 48
	v_readlane_b32 s6, v24, 0
	v_readlane_b32 s7, v24, 32
	v_mov_b32_e32 v24, s14
	v_mov_b32_e32 v25, s15
	v_pk_add_f32 v[24:25], s[6:7], v[24:25]
	s_nop 0
	v_add_f32_e32 v24, v24, v25
	v_fmamk_f32 v24, v24, 0x3b800000, v109
	v_mul_f32_e32 v25, 0x4b800000, v24
	v_cmp_gt_f32_e32 vcc, s31, v24
	s_nop 1
	v_cndmask_b32_e32 v24, v24, v25, vcc
	v_rsq_f32_e32 v26, v24
	v_add_co_u32_e64 v24, s[6:7], s36, v84
	s_nop 1
	v_addc_co_u32_e64 v25, s[6:7], 0, v85, s[6:7]
	global_store_dwordx4 v[24:25], v[20:23], off offset:512
	s_nop 1
	v_mul_f32_e32 v20, 0x45800000, v26
	v_cndmask_b32_e32 v20, v26, v20, vcc
	v_pk_mul_f32 v[12:13], v[12:13], v[20:21] op_sel_hi:[1,0]
	v_pk_mul_f32 v[14:15], v[14:15], v[20:21] op_sel_hi:[1,0]
	v_pk_mul_f32 v[8:9], v[8:9], v[12:13]
	v_pk_mul_f32 v[10:11], v[10:11], v[14:15]
	s_waitcnt vmcnt(14)
	v_lshlrev_b32_e32 v13, 16, v18
	v_and_b32_e32 v15, 0xffff0000, v18
	v_and_b32_e32 v14, 0xffff0000, v16
	v_lshlrev_b32_e32 v21, 16, v19
	v_and_b32_e32 v19, 0xffff0000, v19
	v_and_b32_e32 v18, 0xffff0000, v17
	v_lshlrev_b32_e32 v12, 16, v16
	v_lshlrev_b32_e32 v20, 16, v17
	v_pk_mul_f32 v[16:17], v[14:15], v[14:15]
	v_pk_mul_f32 v[22:23], v[18:19], v[18:19]
	v_pk_fma_f32 v[16:17], v[12:13], v[12:13], v[16:17]
	v_pk_fma_f32 v[22:23], v[20:21], v[20:21], v[22:23]
	v_cvt_pk_bf16_f32 v8, v8, v9
	v_cvt_pk_bf16_f32 v9, v10, v11
	global_store_dwordx2 v[32:33], v[8:9], off offset:2048
	v_pk_add_f32 v[16:17], v[16:17], v[22:23]
	v_mov_b32_e32 v10, v12
	v_add_f32_e32 v16, v16, v17
	v_mov_b32_e32 v11, v14
	v_mov_b32_e32 v14, v13
	v_add_f32_dpp v16, v16, v16 quad_perm:[1,0,3,2] row_mask:0xf bank_mask:0xf bound_ctrl:1
	s_nop 1
	v_add_f32_dpp v16, v16, v16 quad_perm:[2,3,0,1] row_mask:0xf bank_mask:0xf bound_ctrl:1
	s_nop 1
	v_add_f32_dpp v16, v16, v16 row_half_mirror row_mask:0xf bank_mask:0xf bound_ctrl:1
	s_nop 1
	v_add_f32_dpp v16, v16, v16 row_mirror row_mask:0xf bank_mask:0xf bound_ctrl:1
	s_nop 0
	v_readlane_b32 s14, v16, 16
	v_readlane_b32 s15, v16, 48
	v_readlane_b32 s6, v16, 0
	v_readlane_b32 s7, v16, 32
	v_mov_b32_e32 v16, s14
	v_mov_b32_e32 v17, s15
	v_pk_add_f32 v[16:17], s[6:7], v[16:17]
	s_nop 0
	v_add_f32_e32 v16, v16, v17
	v_fmamk_f32 v16, v16, 0x3b000000, v109
	v_mul_f32_e32 v17, 0x4b800000, v16
	v_cmp_gt_f32_e32 vcc, s31, v16
	s_nop 1
	v_cndmask_b32_e32 v16, v16, v17, vcc
	v_rsq_f32_e32 v16, v16
	v_mov_b32_e32 v17, v18
	v_mov_b32_e32 v18, v21
	v_mul_f32_e32 v8, 0x45800000, v16
	v_cndmask_b32_e32 v8, v16, v8, vcc
	v_pk_mul_f32 v[10:11], v[10:11], v[8:9] op_sel_hi:[1,0]
	v_mov_b32_e32 v16, v20
	v_pk_mul_f32 v[16:17], v[16:17], v[8:9] op_sel_hi:[1,0]
	v_pk_mul_f32 v[4:5], v[4:5], v[10:11]
	v_pk_mul_f32 v[10:11], v[14:15], v[8:9] op_sel_hi:[1,0]
	v_pk_mul_f32 v[8:9], v[18:19], v[8:9] op_sel_hi:[1,0]
	v_pk_mul_f32 v[6:7], v[6:7], v[16:17]
	v_pk_mul_f32 v[8:9], v[2:3], v[8:9]
	v_pk_mul_f32 v[2:3], v[0:1], v[10:11]
	v_cvt_pk_bf16_f32 v0, v4, v5
	v_cvt_pk_bf16_f32 v1, v6, v7
	s_nop 0
	v_cvt_pk_bf16_f32 v2, v2, v3
	v_cvt_pk_bf16_f32 v3, v8, v9
	global_store_dwordx4 v[24:25], v[0:3], off offset:2560
	s_barrier
	s_cbranch_scc1 .LBB0_445

.Llb_fast_4:
	v_add_co_u32_e32 v0, vcc, 0x2000, v2
	v_mov_b32_e32 v2, 1
	s_nop 0
	v_addc_co_u32_e32 v1, vcc, 0, v3, vcc
	s_waitcnt vmcnt(0)
	buffer_inv sc1
	global_atomic_add v[0:1], v2, off offset:1024
	s_waitcnt vmcnt(0)
.LBB0_489:
	s_or_b64 exec, exec, s[50:51]
	s_mov_b64 s[6:7], s[0:1]
	s_waitcnt lgkmcnt(0)
	s_barrier
	v_mov_b32_e32 v12, v176
	s_waitcnt vmcnt(0)
	v_mov_b64_e32 v[0:1], s[6:7]
	flat_load_dwordx2 v[0:1], v[0:1] offset:216
	s_and_b64 vcc, exec, s[46:47]
	v_readfirstlane_b32 s10, v12
	s_cbranch_vccz .LBB0_495
	s_lshr_b32 s3, s33, 29
	s_add_i32 s3, s2, s3
	s_and_b32 s6, s3, -8
	s_sub_i32 s8, s2, s6
	s_cmp_gt_i32 s8, -1
	s_cbranch_scc0 .LBB0_492
	s_lshl_b32 s9, s8, 6
	s_cbranch_execz .LBB0_493
	s_branch .LBB0_494

.LBB0_495:
	s_and_b64 vcc, exec, s[4:5]
	s_cbranch_vccnz .LBB0_564
	s_mov_b64 s[6:7], 0x9000000
	s_waitcnt vmcnt(0) lgkmcnt(0)
	v_lshl_add_u64 v[178:179], v[0:1], 0, s[6:7]
	s_mov_b64 s[6:7], 0x1500000
	v_lshl_add_u64 v[180:181], v[0:1], 0, s[6:7]
	v_ashrrev_i32_e32 v1, 31, v12
	v_lshrrev_b32_e32 v1, 26, v1
	v_add_u32_e32 v1, v12, v1
	v_ashrrev_i32_e32 v13, 6, v1
	v_bfe_i32 v1, v12, 27, 1
	v_lshlrev_b32_e32 v0, 4, v12
	v_lshrrev_b32_e32 v1, 22, v1
	v_add_u32_e32 v1, v0, v1
	v_and_b32_e32 v1, 0xfffffc00, v1
	v_sub_u32_e32 v1, v0, v1
	v_lshrrev_b32_e32 v2, 4, v1
	v_bitop3_b32 v1, v2, v1, 32 bitop3:0x6c
	v_ashrrev_i32_e32 v3, 31, v1
	v_lshrrev_b32_e32 v3, 26, v3
	v_add_u32_e32 v3, v1, v3
	v_lshlrev_b32_e32 v2, 3, v13
	v_ashrrev_i32_e32 v14, 6, v3
	v_and_b32_e32 v3, 0xc0, v3
	v_and_b32_e32 v2, -16, v2
	v_sub_u32_e32 v1, v1, v3
	v_mov_b32_e32 v217, 1
	v_add_u32_e32 v2, v14, v2
	v_ashrrev_i16_sdwa v1, v217, sext(v1) dst_sel:DWORD dst_unused:UNUSED_PAD src0_sel:DWORD src1_sel:BYTE_0
	v_lshlrev_b32_e32 v4, 5, v13
	v_bfe_i32 v15, v1, 0, 16
	v_lshlrev_b32_e32 v1, 1, v2
	v_lshrrev_b32_e32 v3, 2, v2
	v_and_b32_e32 v5, 3, v14
	s_mov_b32 s3, 0x1fffe0
	v_and_b32_e32 v4, 32, v4
	v_and_b32_e32 v1, 24, v1
	v_and_b32_e32 v3, 4, v3
	v_and_or_b32 v5, v2, s3, v5
	v_or3_b32 v1, v5, v3, v1
	v_add_lshl_u32 v3, v4, v15, 1
	v_add_u32_e32 v0, 0x2000, v0
	v_lshl_add_u32 v184, v1, 11, v3
	v_ashrrev_i32_e32 v1, 31, v0
	v_lshrrev_b32_e32 v1, 22, v1
	v_add_u32_e32 v1, v0, v1
	v_ashrrev_i32_e32 v16, 10, v1
	v_mul_i32_i24_e32 v1, 0x400, v16
	v_sub_u32_e32 v0, v0, v1
	v_lshrrev_b32_e32 v1, 4, v0
	v_bitop3_b32 v0, v1, v0, 32 bitop3:0x6c
	v_lshl_add_u32 v182, v2, 11, v3
	v_ashrrev_i32_e32 v2, 31, v0
	v_lshrrev_b32_e32 v2, 26, v2
	v_add_u32_e32 v2, v0, v2
	v_lshlrev_b32_e32 v1, 3, v16
	v_ashrrev_i32_e32 v17, 6, v2
	v_and_b32_e32 v2, 0xc0, v2
	v_and_b32_e32 v1, -16, v1
	v_sub_u32_e32 v0, v0, v2
	v_add_u32_e32 v1, v17, v1
	v_ashrrev_i16_sdwa v0, v217, sext(v0) dst_sel:DWORD dst_unused:UNUSED_PAD src0_sel:DWORD src1_sel:BYTE_0
	v_lshlrev_b32_e32 v3, 5, v16
	v_bfe_i32 v18, v0, 0, 16
	v_lshlrev_b32_e32 v0, 1, v1
	v_lshrrev_b32_e32 v2, 2, v1
	v_and_b32_e32 v4, 3, v17
	s_ashr_i32 s6, s10, 6
	v_and_b32_e32 v3, 32, v3
	v_and_b32_e32 v0, 24, v0
	v_and_b32_e32 v2, 4, v2
	v_and_or_b32 v4, v1, s3, v4
	s_ashr_i32 s13, s12, 31
	v_or3_b32 v0, v4, v2, v0
	v_add_lshl_u32 v2, v3, v18, 1
	s_lshl_b32 s3, s6, 10
	s_lshl_b64 s[14:15], s[12:13], 19
	v_lshl_add_u32 v186, v1, 11, v2
	v_lshl_add_u32 v188, v0, 11, v2
	v_lshl_add_u64 v[0:1], v[180:181], 0, s[14:15]
	s_add_i32 s42, s3, 0
	v_mov_b32_e32 v185, 0
	s_add_i32 m0, s42, 0x10000
	v_lshl_add_u64 v[4:5], v[0:1], 0, v[184:185]
	v_mov_b32_e32 v189, v185
	s_mov_b64 s[14:15], 0x40000
	global_load_lds_dwordx4 v[4:5], off
	v_lshl_add_u64 v[6:7], v[0:1], 0, v[188:189]
	s_add_i32 m0, s42, 0x12000
	v_lshl_add_u64 v[2:3], v[0:1], 0, s[14:15]
	s_ashr_i32 s9, s8, 31
	global_load_lds_dwordx4 v[6:7], off
	s_add_i32 m0, s42, 0x14000
	v_lshl_add_u64 v[8:9], v[2:3], 0, v[184:185]
	s_lshl_b64 s[16:17], s[8:9], 19
	global_load_lds_dwordx4 v[8:9], off
	v_lshl_add_u64 v[2:3], v[2:3], 0, v[188:189]
	s_add_i32 m0, s42, 0x16000
	v_mov_b32_e32 v183, v185
	global_load_lds_dwordx4 v[2:3], off
	v_lshl_add_u64 v[2:3], v[178:179], 0, s[16:17]
	v_lshl_add_u64 v[8:9], v[2:3], 0, v[182:183]
	s_mov_b32 m0, s42
	v_mov_b32_e32 v187, v185
	s_add_i32 s43, s42, 0x2000
	global_load_lds_dwordx4 v[8:9], off
	v_lshl_add_u64 v[10:11], v[2:3], 0, v[186:187]
	s_mov_b32 m0, s43
	v_lshl_add_u64 v[20:21], v[2:3], 0, s[14:15]
	s_add_i32 s44, s42, 0x4000
	global_load_lds_dwordx4 v[10:11], off
	v_lshl_add_u64 v[22:23], v[20:21], 0, v[182:183]
	s_mov_b32 m0, s44
	s_add_i32 s45, s42, 0x6000
	global_load_lds_dwordx4 v[22:23], off
	v_lshl_add_u64 v[20:21], v[20:21], 0, v[186:187]
	s_mov_b32 m0, s45
	s_ashr_i32 s70, s10, 8
	global_load_lds_dwordx4 v[20:21], off
	s_cmp_eq_u32 s70, 1
	s_cselect_b64 s[16:17], -1, 0
	s_cmp_lg_u32 s70, 1
	s_mov_b32 s18, 0
	s_cbranch_scc1 .LBB0_498
	s_barrier

.LBB0_989:
	s_mov_b64 s[16:17], 0x80
	s_add_i32 m0, s35, 0x18000
	v_lshl_add_u64 v[6:7], v[6:7], 0, s[16:17]
	s_waitcnt vmcnt(2)
	s_barrier
	global_load_lds_dwordx4 v[6:7], off
	v_lshl_add_u64 v[6:7], v[8:9], 0, s[16:17]
	s_add_i32 m0, s35, 0x1a000
	s_add_i32 s39, s35, 0x8000
	global_load_lds_dwordx4 v[6:7], off
	v_lshl_add_u64 v[6:7], v[10:11], 0, s[16:17]
	s_mov_b32 m0, s39
	s_add_i32 s40, s35, 0xa000
	global_load_lds_dwordx4 v[6:7], off
	v_lshl_add_u64 v[6:7], v[12:13], 0, s[16:17]
	s_mov_b32 m0, s40
	s_mov_b64 s[18:19], 0x40080
	global_load_lds_dwordx4 v[6:7], off
	v_lshl_add_u64 v[6:7], v[2:3], 0, s[18:19]
	s_add_i32 m0, s35, 0x1c000
	v_lshl_add_u64 v[8:9], v[6:7], 0, v[134:135]
	global_load_lds_dwordx4 v[8:9], off
	v_lshl_add_u64 v[6:7], v[6:7], 0, v[140:141]
	s_add_i32 m0, s35, 0x1e000
	s_and_b32 s20, s2, 7
	s_lshl_b32 s20, s20, 23
	s_add_u32 s20, s20, 0xd000000
	s_mov_b32 s21, 0
	global_load_lds_dwordx4 v[6:7], off
	v_lshl_add_u64 v[142:143], v[4:5], 0, s[20:21]
	v_lshrrev_b32_e32 v5, 1, v14
	v_and_b32_e32 v5, 24, v5
	v_and_b32_e32 v4, 15, v14
	v_lshlrev_b32_e32 v6, 1, v5
	v_lshl_or_b32 v166, s11, 6, v4
	v_lshl_or_b32 v4, v4, 6, v6
	v_lshlrev_b32_e32 v6, 2, v14
	s_sext_i32_i8 s52, s9
	s_lshl_b32 s9, s11, 13
	v_and_b32_e32 v6, 32, v6
	v_bitop3_b32 v7, v4, s9, v6 bitop3:0xde
	s_lshl_b32 s9, s10, 5
	s_and_b32 s9, s9, 0x60
	s_lshl_b32 s10, s9, 7
	v_bitop3_b32 v167, v4, s10, v6 bitop3:0xde
	v_lshlrev_b32_e32 v4, 14, v18
	v_and_b32_e32 v4, 0xffff8000, v4
	v_or_b32_e32 v169, s9, v5
	v_lshl_add_u32 v4, v19, 11, v4
	v_and_b32_e32 v5, 1, v18
	v_lshl_or_b32 v4, v5, 6, v4
	v_lshl_add_u32 v144, v20, 1, v4
	v_lshlrev_b32_e32 v4, 14, v15
	v_and_b32_e32 v4, 0xffff8000, v4
	s_waitcnt vmcnt(6)
	s_cmpk_lt_u32 s8, 0x100
	v_lshl_add_u32 v4, v16, 11, v4
	v_and_b32_e32 v5, 1, v15
	s_cselect_b64 s[20:21], -1, 0
	s_add_i32 s8, 0, 0x21c00
	v_lshl_or_b32 v4, v5, 6, v4
	s_mov_b32 s26, 0xfffc0080
	s_mov_b32 s53, 0
	v_lshl_add_u32 v168, v166, 4, s8
	v_mov_b32_e32 v145, v135
	v_lshl_add_u32 v146, v17, 1, v4
	v_mov_b32_e32 v147, v135
	v_mov_b64_e32 v[148:149], 0x380
	v_mov_b64_e32 v[150:151], 0x37f
	s_movk_i32 s41, 0x71
	s_mov_b64 s[22:23], 0x100
	s_mov_b32 s27, -1
	s_add_i32 s42, 0, 0x10000
	s_add_i32 s43, 0, 0x14000
	v_add_u32_e32 v170, 0, v7
	s_add_i32 s44, s35, 0xc000
	s_add_i32 s45, s35, 0xe000
	s_movk_i32 s48, 0xe00
	v_mov_b32_e32 v171, 0x358637bd
	s_mov_b32 s49, 0x800000
	s_mov_b32 s50, 0
	s_barrier
	s_branch .LBB0_992

.LBB0_1049:
	s_or_b64 exec, exec, s[48:49]
	v_mov_b32_e32 v0, v176
	s_mov_b32 s12, s68
	s_and_b32 s3, s2, 7
	s_lshl_b32 s3, s3, 5
	s_lshr_b32 s98, s2, 3
	s_add_i32 s3, s3, s98
	s_waitcnt lgkmcnt(0)
	s_barrier
	s_lshl_b32 s3, s3, 3
	v_readfirstlane_b32 s8, v0
	s_ashr_i32 s9, s8, 6
	s_add_i32 s3, s3, s9
	s_mov_b64 s[10:11], s[0:1]
	s_cmpk_gt_i32 s3, 0x7ff
	s_cbranch_scc1 .LBB0_1058
	v_bfe_u32 v3, v0, 4, 2
	s_mulk_i32 s9, 0x4400
	v_lshlrev_b32_e32 v77, 2, v3
	v_and_b32_e32 v1, 63, v0
	s_add_i32 s9, s9, 0
	v_and_b32_e32 v72, 15, v0
	v_and_b32_e32 v0, 48, v0
	v_or_b32_e32 v102, 1, v77
	v_or_b32_e32 v104, 2, v77
	v_or_b32_e32 v106, 3, v77
	v_lshlrev_b32_e32 v2, 9, v3
	v_add_u32_e32 v76, s9, v0
	v_lshl_add_u32 v0, v3, 11, s9
	v_lshlrev_b32_e32 v3, 3, v72
	v_lshl_add_u32 v4, v102, 9, s9
	v_lshl_add_u32 v5, v104, 9, s9
	v_lshl_add_u32 v6, v106, 9, s9
	v_add_u32_e32 v79, v0, v3
	v_add_u32_e32 v103, v4, v3
	v_add_u32_e32 v105, v5, v3
	v_add_u32_e32 v107, v6, v3
	v_or_b32_e32 v7, 0x80, v3
	v_or_b32_e32 v3, 0x100, v3
	s_bfe_u32 s8, s8, 0x20006
	s_lshl_b32 s26, s12, 3
	v_add_u32_e32 v112, v0, v3
	v_add_u32_e32 v113, v4, v3
	v_add_u32_e32 v114, v5, v3
	v_add_u32_e32 v115, v6, v3
	v_or_b32_e32 v3, 48, v1
	s_lshl_b32 s12, s8, 6
	v_lshl_add_u32 v73, v1, 1, s9
	v_add_u32_e32 v108, v0, v7
	v_add_u32_e32 v109, v4, v7
	v_add_u32_e32 v110, v5, v7
	v_add_u32_e32 v111, v6, v7
	v_lshlrev_b32_e32 v7, 3, v3
	v_or_b32_e32 v78, s12, v1
	v_lshl_add_u32 v1, v1, 3, s9
	v_mov_b32_e32 v75, 0
	v_add_u32_e32 v116, v0, v7
	s_lshl_b32 s8, s8, 12
	v_or_b32_e32 v0, s12, v72
	v_add_u32_e32 v122, 0x2400, v1
	v_mov_b32_e32 v1, 0x18000800
	s_mov_b32 s13, 0
	v_add_u32_e32 v117, v4, v7
	v_add_u32_e32 v118, v5, v7
	v_add_u32_e32 v119, v6, v7
	v_lshl_add_u32 v120, v72, 1, s9
	v_lshl_add_u32 v121, v3, 1, s9
	v_lshlrev_b32_e32 v80, 3, v78
	v_mov_b32_e32 v81, v75
	v_lshl_or_b32 v82, v78, 2, v1
	v_mov_b32_e32 v83, v75
	v_mov_b64_e32 v[84:85], s[10:11]
	v_lshlrev_b32_e32 v86, 2, v78
	v_mov_b32_e32 v87, v75
	s_mov_b64 s[14:15], 0x1000
	s_movk_i32 s27, 0x1000
	s_and_b32 s16, s2, 7
	s_lshl_b32 s16, s16, 23
	s_add_u32 s16, s16, 0xd000000
	s_mov_b32 s17, 0
	s_lshl_b32 s12, s8, 2
	v_lshlrev_b32_e32 v88, 2, v2
	v_lshlrev_b32_e32 v90, 2, v72
	s_mov_b64 s[18:19], 0x10000
	s_mov_b32 s28, 0x10000
	s_mov_b32 s29, 0x12000
	s_movk_i32 s30, 0x2000
	s_movk_i32 s31, 0x3000
	s_movk_i32 s34, 0x4000
	s_movk_i32 s35, 0x5000
	s_movk_i32 s36, 0x6000
	s_movk_i32 s37, 0x7000
	s_mov_b32 s38, 0x8000
	s_mov_b32 s39, 0x9000
	s_mov_b32 s40, 0xa000
	s_mov_b32 s41, 0xb000
	s_mov_b32 s42, 0xc000
	s_mov_b32 s43, 0xd000
	s_mov_b32 s44, 0xe000
	s_mov_b32 s45, 0xf000
	s_mov_b32 s48, 0x11000
	s_mov_b32 s49, 0x13000
	s_mov_b32 s50, 0x14000
	s_mov_b32 s51, 0x15000
	s_mov_b32 s52, 0x16000
	s_mov_b32 s53, 0x17000
	s_mov_b32 s54, 0x18000
	s_mov_b32 s55, 0x19000
	s_mov_b32 s56, 0x1a000
	s_mov_b32 s57, 0x1b000
	s_mov_b32 s58, 0x1c000
	s_mov_b32 s59, 0x1d000
	s_mov_b32 s60, 0x1e000
	s_mov_b32 s61, 0x1f000
	s_mov_b32 s62, 0x20000
	s_mov_b32 s63, 0x21000
	s_mov_b32 s64, 0x22000
	s_mov_b32 s65, 0x23000
	s_mov_b32 s66, 0x24000
	s_mov_b32 s67, 0x25000
	s_mov_b32 s70, 0x26000
	s_mov_b32 s71, 0x27000
	s_mov_b32 s72, 0x28000
	s_mov_b32 s73, 0x29000
	s_mov_b32 s74, 0x2a000
	s_mov_b32 s75, 0x2b000
	s_mov_b32 s76, 0x2c000
	s_mov_b32 s77, 0x2d000
	s_mov_b32 s78, 0x2e000
	s_mov_b32 s79, 0x2f000
	s_mov_b32 s80, 0x30000
	s_mov_b32 s81, 0x31000
	s_mov_b32 s82, 0x32000
	s_mov_b32 s83, 0x33000
	s_mov_b32 s84, 0x34000
	s_mov_b32 s85, 0x35000
	s_mov_b32 s86, 0x36000
	s_mov_b32 s87, 0x37000
	v_lshlrev_b32_e32 v92, 2, v0
	s_mov_b32 s88, 0x3f2aaaab
	v_mov_b32_e32 v123, 0x3ecc95a3
	s_mov_b32 s89, 0x3f317218
	s_mov_b32 s90, 0x7f800000
	s_mov_b32 s91, 0x33800000
	s_movk_i32 s92, 0x90
	s_mov_b32 s93, 0xf800000
	v_mov_b32_e32 v124, 0x260
	s_mov_b64 s[20:21], 0x4000
	v_mov_b32_e32 v125, 0xe00
	v_mov_b32_e32 v126, 0x7f800000
	v_mov_b32_e32 v127, 0x7fc00000
	v_mov_b32_e32 v128, 0xff800000

.LBB0_1058:
	v_mov_b32_e32 v0, v176
	s_and_b32 s3, s2, 7
	s_lshl_b32 s3, s3, 6
	s_lshr_b32 s98, s2, 3
	s_add_i32 s3, s3, s98
	s_add_i32 s99, s3, 32
	s_mov_b32 s42, 32
	s_mov_b64 s[26:27], s[0:1]
	s_barrier
	s_load_dwordx2 s[86:87], s[0:1], 0xe0
	v_readfirstlane_b32 s8, v0
	s_cmpk_gt_i32 s3, 0x1ff
	s_cbranch_scc1 .LBB0_1071
	v_mbcnt_hi_u32_b32 v10, -1, v216
	v_and_b32_e32 v12, 64, v10
	v_xor_b32_e32 v11, 16, v10
	v_add_u32_e32 v12, 64, v12
	v_cmp_lt_i32_e32 vcc, v11, v12
	v_and_b32_e32 v1, 7, v0
	v_add_u32_e32 v6, 0x400, v0
	v_cndmask_b32_e32 v11, v10, v11, vcc
	s_ashr_i32 s28, s8, 6
	v_lshl_add_u32 v3, v1, 4, 0
	s_movk_i32 s8, 0x1070
	v_add_u32_e32 v5, 0x200, v0
	v_ashrrev_i32_e32 v90, 3, v6
	v_add_u32_e32 v6, 0x600, v0
	v_lshlrev_b32_e32 v111, 2, v11
	v_xor_b32_e32 v11, 32, v10
	v_mad_u32_u24 v4, v1, s8, v3
	v_ashrrev_i32_e32 v86, 3, v0
	v_ashrrev_i32_e32 v88, 3, v5
	v_ashrrev_i32_e32 v92, 3, v6
	v_bfe_u32 v6, v0, 4, 2
	v_cmp_lt_i32_e32 vcc, v11, v12
	v_lshl_add_u32 v85, v86, 1, v4
	v_lshl_add_u32 v108, v88, 1, v4
	v_lshl_add_u32 v109, v90, 1, v4
	v_lshl_add_u32 v110, v92, 1, v4
	v_lshlrev_b32_e32 v4, 3, v6
	v_lshlrev_b32_e32 v6, 2, v6
	v_cndmask_b32_e32 v10, v10, v11, vcc
	s_and_b32 s43, s28, 3
	s_lshl_b32 s16, s28, 4
	v_and_b32_e32 v9, 15, v0
	v_lshlrev_b32_e32 v112, 2, v10
	v_or_b32_e32 v10, 2, v6
	s_lshr_b32 s28, s28, 2
	v_cmp_gt_u32_e64 s[20:21], v10, v9
	v_or_b32_e32 v10, 3, v6
	s_lshl_b32 s31, s28, 7
	v_cmp_gt_u32_e64 s[22:23], v10, v9
	v_and_or_b32 v10, v0, 63, 48
	s_movk_i32 s34, 0x210
	v_mov_b32_e32 v11, s31
	v_mad_u32_u24 v10, v10, s34, v11
	v_add3_u32 v10, v10, v4, 0
	v_add_u32_e32 v113, 0x9000, v10
	v_mad_u32_u24 v10, v9, s34, v11
	v_add3_u32 v10, v10, v4, 0
	s_lshl_b32 s44, s28, 6
	s_mulk_i32 s28, 0x2400
	s_movk_i32 s30, 0x90
	s_andn2_b32 s16, s16, 63
	v_add_u32_e32 v114, 0x9000, v10
	v_mov_b32_e32 v10, s28
	v_lshlrev_b32_e32 v84, 3, v1
	s_movk_i32 s14, 0x7f
	v_mul_lo_u32 v1, v86, s30
	v_mul_lo_u32 v5, v88, s30
	v_mul_lo_u32 v7, v90, s30
	v_mul_lo_u32 v8, v92, s30
	s_ashr_i32 s17, s16, 31
	v_mad_u32_u24 v10, v9, s30, v10
	v_and_b32_e32 v0, 48, v0
	s_mov_b32 s29, 0
	v_mov_b32_e32 v2, 0
	v_cmp_lt_i32_e64 s[8:9], s14, v86
	v_ashrrev_i32_e32 v87, 31, v86
	v_cmp_lt_i32_e64 s[10:11], s14, v88
	v_ashrrev_i32_e32 v89, 31, v88
	v_cmp_lt_i32_e64 s[12:13], s14, v90
	v_ashrrev_i32_e32 v91, 31, v90
	v_cmp_lt_i32_e64 s[14:15], s14, v92
	v_ashrrev_i32_e32 v93, 31, v92
	v_or_b32_e32 v94, s16, v9
	v_mov_b32_e32 v95, s17
	v_cmp_gt_u32_e64 s[16:17], v6, v9
	v_cmp_lt_u32_e64 s[18:19], v6, v9
	v_add3_u32 v115, v10, v0, 0
	v_or_b32_e32 v116, s44, v9
	v_mov_b64_e32 v[96:97], s[26:27]
	s_and_b32 s30, s2, 7
	s_lshl_b32 s30, s30, 23
	s_add_u32 s30, s30, 0xd000000
	s_mov_b32 s31, 0
	s_movk_i32 s45, 0xe00
	v_add_u32_e32 v117, v3, v1
	v_add_u32_e32 v118, v3, v5
	v_add_u32_e32 v119, v3, v7
	v_add_u32_e32 v120, v3, v8
	v_lshlrev_b32_e32 v98, 1, v4
	s_mov_b32 s48, 0xf149f2ca
	v_lshlrev_b32_e32 v100, 1, v6
	s_mov_b64 s[34:35], 0x9000200
	s_mov_b32 s49, 0x9000000
	v_mov_b32_e32 v121, 0xf149f2ca

.LBB0_1069:
	ds_read_b128 v[16:19], v125
	s_nop 0
	ds_read_b128 v[12:15], v125 offset:64
	ds_read_b128 v[20:23], v125 offset:2304
	ds_read_b128 v[36:39], v125 offset:4608
	s_add_i32 s52, s44, s50
	s_add_i32 s51, s50, 16
	s_cmp_lg_u32 s50, 48
	s_cselect_b32 s28, s51, 48
	v_add_u32_e32 v0, s50, v116
	s_waitcnt vmcnt(1) lgkmcnt(3)
	v_mfma_f32_16x16x32_bf16 v[32:35], v[16:19], v[8:11], 0
	ds_read_b128 v[24:27], v125 offset:2368
	ds_read_b128 v[16:19], v125 offset:4672
	ds_read_b128 v[40:43], v125 offset:6912
	v_ashrrev_i32_e32 v1, 31, v0
	v_lshl_add_u64 v[0:1], s[36:37], 0, v[0:1]
	s_waitcnt lgkmcnt(4)
	v_mfma_f32_16x16x32_bf16 v[44:47], v[20:23], v[8:11], 0
	ds_read_b128 v[20:23], v125 offset:6976
	ds_read_b128 v[52:55], v125 offset:9216
	ds_read_b128 v[28:31], v125 offset:9280
	v_lshlrev_b64 v[0:1], 11, v[0:1]
	v_lshl_add_u64 v[0:1], v[102:103], 0, v[0:1]
	s_waitcnt lgkmcnt(6)
	v_mfma_f32_16x16x32_bf16 v[56:59], v[36:39], v[8:11], 0
	ds_read_b128 v[80:83], v125 offset:11520
	ds_read_b128 v[36:39], v125 offset:11584
	ds_read_b128 v[76:79], v125 offset:13824
	v_mov_b32_e32 v101, v2
	v_lshl_add_u64 v[0:1], v[0:1], 0, s[40:41]
	s_waitcnt lgkmcnt(6)
	v_mfma_f32_16x16x32_bf16 v[60:63], v[40:43], v[8:11], 0
	ds_read_b128 v[40:43], v125 offset:13888
	ds_read_b128 v[72:75], v125 offset:16128
	ds_read_b128 v[48:51], v125 offset:16192
	s_add_i32 s53, s52, 16
	s_add_i32 s56, s52, 32
	s_waitcnt lgkmcnt(7)
	v_mfma_f32_16x16x32_bf16 v[64:67], v[52:55], v[8:11], 0
	ds_read_b128 v[68:71], v125 offset:18432
	ds_read_b128 v[52:55], v125 offset:18496
	s_add_i32 s57, s52, 48
	s_add_i32 s58, s52, 64
	s_waitcnt lgkmcnt(7)
	v_mfma_f32_16x16x32_bf16 v[126:129], v[80:83], v[8:11], 0
	s_add_i32 s59, s52, 0x50
	s_add_i32 s60, s52, 0x60
	s_add_i32 s61, s52, 0x70
	s_waitcnt lgkmcnt(5)
	v_mfma_f32_16x16x32_bf16 v[76:79], v[76:79], v[8:11], 0
	v_lshl_add_u64 v[0:1], v[0:1], 0, v[100:101]
	s_cmpk_lt_i32 s52, 0x80
	v_add_u32_e32 v124, 0x900, v125
	s_waitcnt lgkmcnt(3)
	v_mfma_f32_16x16x32_bf16 v[72:75], v[72:75], v[8:11], 0
	v_mov_b32_e32 v125, v124
	v_mov_b32_e32 v3, v2
	v_add_u32_e32 v81, 0x2000, v99
	s_waitcnt lgkmcnt(1)
	v_mfma_f32_16x16x32_bf16 v[68:71], v[68:71], v[8:11], 0
	v_lshl_add_u64 v[8:9], v[104:105], 0, s[28:29]
	v_add_u32_e32 v82, 0x4000, v99
	v_add_u32_e32 v80, 32, v99
	s_waitcnt vmcnt(0)
	v_mfma_f32_16x16x32_bf16 v[32:35], v[12:15], v[4:7], v[32:35]
	v_mad_u64_u32 v[12:13], s[26:27], v8, s45, v[106:107]
	v_mov_b32_e32 v8, v13
	v_mad_u64_u32 v[8:9], s[54:55], v9, s45, v[8:9]
	v_mov_b32_e32 v13, v8
	global_load_dwordx4 v[8:11], v[12:13], off offset:1024
	s_nop 0
	global_load_dwordx4 v[12:15], v[12:13], off offset:1088
	v_mfma_f32_16x16x32_bf16 v[24:27], v[24:27], v[4:7], v[44:47]
	s_cselect_b64 s[26:27], -1, 0
	v_add_u32_e32 v83, 32, v123
	s_mov_b32 s50, s51
	v_mfma_f32_16x16x32_bf16 v[44:47], v[16:19], v[4:7], v[56:59]
	v_add_co_u32_e32 v18, vcc, s49, v0
	v_lshl_add_u64 v[16:17], v[0:1], 0, s[34:35]
	s_nop 0
	v_addc_co_u32_e32 v19, vcc, 0, v1, vcc
	s_and_b64 vcc, s[38:39], s[26:27]
	s_or_b64 s[26:27], s[18:19], vcc
	v_mul_f32_e32 v1, 0x3e000000, v33
	s_cmpk_lt_i32 s53, 0x80
	v_mul_f32_e32 v0, 0x3e000000, v32
	v_mul_f32_e32 v32, 0x3e000000, v34
	v_mul_f32_e32 v33, 0x3e000000, v35
	v_cndmask_b32_e64 v1, v1, v121, s[26:27]
	s_cselect_b64 s[26:27], -1, 0
	v_cndmask_b32_e32 v0, v0, v121, vcc
	v_cndmask_b32_e32 v32, v32, v121, vcc
	v_cndmask_b32_e32 v33, v33, v121, vcc
	s_and_b64 vcc, s[38:39], s[26:27]
	s_cmpk_lt_i32 s56, 0x80
	v_mul_f32_e32 v24, 0x3e000000, v24
	v_mul_f32_e32 v25, 0x3e000000, v25
	v_mul_f32_e32 v26, 0x3e000000, v26
	v_mul_f32_e32 v27, 0x3e000000, v27
	s_cselect_b64 s[26:27], -1, 0
	v_cndmask_b32_e32 v24, v24, v121, vcc
	v_cndmask_b32_e32 v25, v25, v121, vcc
	v_cndmask_b32_e32 v26, v26, v121, vcc
	v_cndmask_b32_e32 v27, v27, v121, vcc
	s_and_b64 vcc, s[38:39], s[26:27]
	v_mfma_f32_16x16x32_bf16 v[20:23], v[20:23], v[4:7], v[60:63]
	s_cmpk_lt_i32 s57, 0x80
	v_mul_f32_e32 v34, 0x3e000000, v44
	v_mul_f32_e32 v35, 0x3e000000, v45
	v_mfma_f32_16x16x32_bf16 v[48:51], v[48:51], v[4:7], v[72:75]
	v_mul_f32_e32 v44, 0x3e000000, v46
	v_mul_f32_e32 v45, 0x3e000000, v47
	s_cselect_b64 s[26:27], -1, 0
	v_cndmask_b32_e32 v34, v34, v121, vcc
	v_cndmask_b32_e32 v35, v35, v121, vcc
	v_cndmask_b32_e32 v44, v44, v121, vcc
	v_cndmask_b32_e32 v45, v45, v121, vcc
	s_and_b64 vcc, s[38:39], s[26:27]
	v_mfma_f32_16x16x32_bf16 v[28:31], v[28:31], v[4:7], v[64:67]
	v_cndmask_b32_e64 v0, v121, v0, s[16:17]
	s_cmpk_lt_i32 s58, 0x80
	v_mul_f32_e32 v20, 0x3e000000, v20
	v_mul_f32_e32 v21, 0x3e000000, v21
	v_mul_f32_e32 v22, 0x3e000000, v22
	v_mul_f32_e32 v23, 0x3e000000, v23
	v_mul_f32_e32 v46, 0x3e000000, v48
	v_mul_f32_e32 v48, 0x3e000000, v50
	v_cndmask_b32_e64 v32, v121, v32, s[20:21]
	v_cndmask_b32_e64 v33, v121, v33, s[22:23]
	v_max3_f32 v50, v0, s48, v1
	s_cselect_b64 s[26:27], -1, 0
	v_max3_f32 v50, v50, v32, v33
	v_cndmask_b32_e32 v20, v20, v121, vcc
	v_cndmask_b32_e32 v21, v21, v121, vcc
	v_cndmask_b32_e32 v22, v22, v121, vcc
	v_cndmask_b32_e32 v23, v23, v121, vcc
	s_and_b64 vcc, s[38:39], s[26:27]
	v_mfma_f32_16x16x32_bf16 v[36:39], v[36:39], v[4:7], v[126:129]
	v_max3_f32 v50, v50, v24, v25
	s_cmpk_lt_i32 s59, 0x80
	v_mul_f32_e32 v28, 0x3e000000, v28
	v_mul_f32_e32 v29, 0x3e000000, v29
	v_mul_f32_e32 v30, 0x3e000000, v30
	v_mul_f32_e32 v31, 0x3e000000, v31
	v_max3_f32 v50, v50, v26, v27
	s_cselect_b64 s[26:27], -1, 0
	v_max3_f32 v50, v50, v34, v35
	v_cndmask_b32_e32 v28, v28, v121, vcc
	v_cndmask_b32_e32 v29, v29, v121, vcc
	v_cndmask_b32_e32 v30, v30, v121, vcc
	v_cndmask_b32_e32 v31, v31, v121, vcc
	s_and_b64 vcc, s[38:39], s[26:27]
	v_mfma_f32_16x16x32_bf16 v[40:43], v[40:43], v[4:7], v[76:79]
	v_max3_f32 v50, v50, v44, v45
	s_cmpk_lt_i32 s60, 0x80
	v_mul_f32_e32 v36, 0x3e000000, v36
	v_mul_f32_e32 v37, 0x3e000000, v37
	v_mul_f32_e32 v38, 0x3e000000, v38
	v_mul_f32_e32 v39, 0x3e000000, v39
	v_max3_f32 v50, v50, v20, v21
	s_cselect_b64 s[26:27], -1, 0
	v_max3_f32 v50, v50, v22, v23
	v_cndmask_b32_e32 v36, v36, v121, vcc
	v_cndmask_b32_e32 v37, v37, v121, vcc
	v_cndmask_b32_e32 v38, v38, v121, vcc
	v_cndmask_b32_e32 v39, v39, v121, vcc
	s_and_b64 vcc, s[38:39], s[26:27]
	v_max3_f32 v50, v50, v28, v29
	s_cmpk_lt_i32 s61, 0x80
	s_waitcnt lgkmcnt(0)
	v_mfma_f32_16x16x32_bf16 v[4:7], v[52:55], v[4:7], v[68:71]
	v_mul_f32_e32 v40, 0x3e000000, v40
	v_mul_f32_e32 v41, 0x3e000000, v41
	v_mul_f32_e32 v42, 0x3e000000, v42
	v_mul_f32_e32 v43, 0x3e000000, v43
	v_max3_f32 v50, v50, v30, v31
	s_cselect_b64 s[26:27], -1, 0
	v_max3_f32 v50, v50, v36, v37
	v_cndmask_b32_e32 v40, v40, v121, vcc
	v_cndmask_b32_e32 v41, v41, v121, vcc
	v_cndmask_b32_e32 v42, v42, v121, vcc
	v_cndmask_b32_e32 v43, v43, v121, vcc
	s_and_b64 vcc, s[38:39], s[26:27]
	v_max3_f32 v50, v50, v38, v39
	s_cmp_gt_u32 s52, 0x7fffff7f
	v_mul_f32_e32 v47, 0x3e000000, v49
	v_mul_f32_e32 v49, 0x3e000000, v51
	v_max3_f32 v50, v50, v40, v41
	s_cselect_b64 s[26:27], -1, 0
	v_mul_f32_e32 v5, 0x3e000000, v5
	v_max3_f32 v50, v50, v42, v43
	v_cndmask_b32_e32 v46, v46, v121, vcc
	v_cndmask_b32_e32 v47, v47, v121, vcc
	v_cndmask_b32_e32 v48, v48, v121, vcc
	v_cndmask_b32_e32 v49, v49, v121, vcc
	s_and_b64 vcc, s[38:39], s[26:27]
	v_mul_f32_e32 v4, 0x3e000000, v4
	v_max3_f32 v50, v50, v46, v47
	v_cndmask_b32_e32 v5, v5, v121, vcc
	s_or_b64 s[26:27], s[16:17], vcc
	v_mul_f32_e32 v6, 0x3e000000, v6
	v_mul_f32_e32 v7, 0x3e000000, v7
	v_max3_f32 v50, v50, v48, v49
	v_cndmask_b32_e64 v4, v4, v121, s[26:27]
	v_cndmask_b32_e64 v5, v121, v5, s[18:19]
	s_or_b64 s[26:27], s[20:21], vcc
	s_or_b64 vcc, s[22:23], vcc
	v_cndmask_b32_e64 v6, v6, v121, s[26:27]
	v_cndmask_b32_e32 v7, v7, v121, vcc
	v_max3_f32 v50, v50, v4, v5
	v_max3_f32 v50, v50, v6, v7
	ds_bpermute_b32 v51, v111, v50
	s_cmp_lg_u32 s51, 64
	s_waitcnt lgkmcnt(0)
	v_max_f32_e32 v51, v51, v51
	v_max_f32_e32 v50, v50, v51
	ds_bpermute_b32 v51, v112, v50
	s_waitcnt lgkmcnt(0)
	v_max3_f32 v50, v50, v51, v122
	v_sub_f32_e32 v0, v0, v50
	v_sub_f32_e32 v1, v1, v50
	v_mul_f32_e32 v0, 0x3fb8aa3b, v0
	v_sub_f32_e32 v32, v32, v50
	v_mul_f32_e32 v1, 0x3fb8aa3b, v1
	v_exp_f32_e32 v0, v0
	v_sub_f32_e32 v33, v33, v50
	v_mul_f32_e32 v32, 0x3fb8aa3b, v32
	v_exp_f32_e32 v51, v1
	v_sub_f32_e32 v24, v24, v50
	v_sub_f32_e32 v25, v25, v50
	v_sub_f32_e32 v26, v26, v50
	v_sub_f32_e32 v27, v27, v50
	v_sub_f32_e32 v34, v34, v50
	v_sub_f32_e32 v35, v35, v50
	v_sub_f32_e32 v44, v44, v50
	v_sub_f32_e32 v45, v45, v50
	v_sub_f32_e32 v20, v20, v50
	v_sub_f32_e32 v21, v21, v50
	v_sub_f32_e32 v22, v22, v50
	v_sub_f32_e32 v23, v23, v50
	v_sub_f32_e32 v28, v28, v50
	v_sub_f32_e32 v29, v29, v50
	v_sub_f32_e32 v30, v30, v50
	v_sub_f32_e32 v31, v31, v50
	v_sub_f32_e32 v36, v36, v50
	v_sub_f32_e32 v37, v37, v50
	v_sub_f32_e32 v38, v38, v50
	v_sub_f32_e32 v39, v39, v50
	v_sub_f32_e32 v40, v40, v50
	v_sub_f32_e32 v41, v41, v50
	v_sub_f32_e32 v42, v42, v50
	v_sub_f32_e32 v43, v43, v50
	v_sub_f32_e32 v46, v46, v50
	v_sub_f32_e32 v47, v47, v50
	v_sub_f32_e32 v48, v48, v50
	v_sub_f32_e32 v49, v49, v50
	v_sub_f32_e32 v4, v4, v50
	v_sub_f32_e32 v5, v5, v50
	v_sub_f32_e32 v6, v6, v50
	v_sub_f32_e32 v7, v7, v50
	v_sub_f32_e32 v50, v122, v50
	v_mul_f32_e32 v33, 0x3fb8aa3b, v33
	v_exp_f32_e32 v52, v32
	v_mul_f32_e32 v24, 0x3fb8aa3b, v24
	v_mul_f32_e32 v50, 0x3fb8aa3b, v50
	v_exp_f32_e32 v53, v33
	v_mul_f32_e32 v25, 0x3fb8aa3b, v25
	v_exp_f32_e32 v54, v24
	v_exp_f32_e32 v130, v50
	v_add_f32_e32 v50, 0, v0
	v_mul_f32_e32 v26, 0x3fb8aa3b, v26
	v_exp_f32_e32 v55, v25
	v_add_f32_e32 v50, v51, v50
	v_mul_f32_e32 v27, 0x3fb8aa3b, v27
	v_exp_f32_e32 v56, v26
	v_add_f32_e32 v50, v52, v50
	v_mul_f32_e32 v34, 0x3fb8aa3b, v34
	v_exp_f32_e32 v57, v27
	v_add_f32_e32 v50, v53, v50
	v_mul_f32_e32 v35, 0x3fb8aa3b, v35
	v_mul_f32_e32 v20, 0x3fb8aa3b, v20
	v_mul_f32_e32 v21, 0x3fb8aa3b, v21
	v_exp_f32_e32 v58, v34
	v_add_f32_e32 v50, v54, v50
	v_mul_f32_e32 v44, 0x3fb8aa3b, v44
	v_exp_f32_e32 v59, v35
	v_exp_f32_e32 v62, v20
	v_exp_f32_e32 v63, v21
	v_cvt_pk_bf16_f32 v20, v0, v51
	v_cvt_pk_bf16_f32 v21, v52, v53
	v_add_f32_e32 v52, v55, v50
	v_mul_f32_e32 v45, 0x3fb8aa3b, v45
	v_exp_f32_e32 v60, v44
	v_add_f32_e32 v52, v56, v52
	v_exp_f32_e32 v61, v45
	v_add_f32_e32 v52, v57, v52
	v_mul_f32_e32 v22, 0x3fb8aa3b, v22
	v_mul_f32_e32 v23, 0x3fb8aa3b, v23
	v_mul_f32_e32 v28, 0x3fb8aa3b, v28
	v_mul_f32_e32 v29, 0x3fb8aa3b, v29
	v_mul_f32_e32 v30, 0x3fb8aa3b, v30
	v_mul_f32_e32 v31, 0x3fb8aa3b, v31
	v_mul_f32_e32 v36, 0x3fb8aa3b, v36
	v_mul_f32_e32 v37, 0x3fb8aa3b, v37
	v_mul_f32_e32 v38, 0x3fb8aa3b, v38
	v_mul_f32_e32 v39, 0x3fb8aa3b, v39
	v_mul_f32_e32 v40, 0x3fb8aa3b, v40
	v_mul_f32_e32 v41, 0x3fb8aa3b, v41
	v_mul_f32_e32 v42, 0x3fb8aa3b, v42
	v_mul_f32_e32 v43, 0x3fb8aa3b, v43
	v_mul_f32_e32 v46, 0x3fb8aa3b, v46
	v_mul_f32_e32 v47, 0x3fb8aa3b, v47
	v_mul_f32_e32 v48, 0x3fb8aa3b, v48
	v_mul_f32_e32 v49, 0x3fb8aa3b, v49
	v_mul_f32_e32 v4, 0x3fb8aa3b, v4
	v_mul_f32_e32 v5, 0x3fb8aa3b, v5
	v_mul_f32_e32 v6, 0x3fb8aa3b, v6
	v_mul_f32_e32 v7, 0x3fb8aa3b, v7
	v_add_f32_e32 v52, v58, v52
	v_exp_f32_e32 v64, v22
	v_exp_f32_e32 v65, v23
	v_exp_f32_e32 v66, v28
	v_exp_f32_e32 v67, v29
	v_exp_f32_e32 v68, v30
	v_exp_f32_e32 v69, v31
	v_exp_f32_e32 v70, v36
	v_exp_f32_e32 v71, v37
	v_exp_f32_e32 v72, v38
	v_exp_f32_e32 v73, v39
	v_exp_f32_e32 v74, v40
	v_exp_f32_e32 v75, v41
	v_exp_f32_e32 v76, v42
	v_exp_f32_e32 v77, v43
	v_exp_f32_e32 v78, v46
	v_exp_f32_e32 v79, v47
	v_exp_f32_e32 v101, v48
	v_exp_f32_e32 v124, v49
	v_exp_f32_e32 v126, v4
	v_exp_f32_e32 v127, v5
	v_exp_f32_e32 v128, v6
	v_exp_f32_e32 v129, v7
	v_cvt_pk_bf16_f32 v22, v54, v55
	v_cvt_pk_bf16_f32 v23, v56, v57
	v_cvt_pk_bf16_f32 v24, v58, v59
	v_cvt_pk_bf16_f32 v25, v60, v61
	v_cvt_pk_bf16_f32 v26, v62, v63
	v_cvt_pk_bf16_f32 v27, v64, v65
	v_cvt_pk_bf16_f32 v28, v66, v67
	v_cvt_pk_bf16_f32 v29, v68, v69
	v_cvt_pk_bf16_f32 v30, v70, v71
	v_cvt_pk_bf16_f32 v31, v72, v73
	v_cvt_pk_bf16_f32 v32, v74, v75
	v_cvt_pk_bf16_f32 v33, v76, v77
	v_cvt_pk_bf16_f32 v34, v78, v79
	v_cvt_pk_bf16_f32 v35, v101, v124
	v_cvt_pk_bf16_f32 v0, v126, v127
	v_cvt_pk_bf16_f32 v1, v128, v129
	ds_read2_b64 v[4:7], v99 offset1:4
	ds_read2_b64 v[36:39], v99 offset0:8 offset1:12
	ds_read2_b64 v[40:43], v99 offset0:16 offset1:20
	ds_read2_b64 v[44:47], v99 offset0:24 offset1:28
	ds_read_b64 v[48:49], v99 offset:256
	v_add_f32_e32 v52, v59, v52
	s_waitcnt lgkmcnt(4)
	v_mfma_f32_16x16x32_bf16 v[4:7], v[4:7], v[20:23], 0
	v_add_f32_e32 v52, v60, v52
	v_add_f32_e32 v52, v61, v52
	v_add_f32_e32 v52, v62, v52
	v_add_f32_e32 v52, v63, v52
	s_waitcnt lgkmcnt(3)
	v_mfma_f32_16x16x32_bf16 v[4:7], v[36:39], v[24:27], v[4:7]
	v_add_f32_e32 v36, v64, v52
	v_add_f32_e32 v36, v65, v36
	v_add_f32_e32 v36, v66, v36
	v_add_f32_e32 v36, v67, v36
	s_waitcnt lgkmcnt(2)
	v_mfma_f32_16x16x32_bf16 v[4:7], v[40:43], v[28:31], v[4:7]
	v_add_f32_e32 v36, v68, v36
	v_add_f32_e32 v36, v69, v36
	v_add_f32_e32 v36, v70, v36
	s_waitcnt lgkmcnt(0)
	v_mov_b32_e32 v50, v48
	v_mov_b32_e32 v51, v49
	v_add_f32_e32 v40, v71, v36
	v_mfma_f32_16x16x32_bf16 v[36:39], v[44:47], v[32:35], v[4:7]
	s_nop 2
	v_add_f32_e32 v4, v72, v40
	v_add_f32_e32 v40, v73, v4
	s_waitcnt vmcnt(0)
	v_mov_b64_e32 v[4:5], v[12:13]
	v_mov_b64_e32 v[6:7], v[14:15]
	v_add_f32_e32 v12, v74, v40
	v_add_f32_e32 v40, v75, v12
	v_mfma_f32_16x16x32_bf16 v[12:15], v[48:51], v[0:3], v[36:39]
	s_nop 2
	v_add_f32_e32 v36, v76, v40
	v_add_f32_e32 v36, v77, v36
	v_add_f32_e32 v36, v78, v36
	v_add_f32_e32 v36, v79, v36
	v_add_f32_e32 v36, v101, v36
	v_add_f32_e32 v36, v124, v36
	v_add_f32_e32 v36, v126, v36
	v_add_f32_e32 v36, v127, v36
	v_add_f32_e32 v36, v128, v36
	v_add_f32_e32 v36, v129, v36
	ds_bpermute_b32 v37, v111, v36
	s_waitcnt lgkmcnt(0)
	v_add_f32_e32 v36, v36, v37
	ds_bpermute_b32 v37, v112, v36
	s_waitcnt lgkmcnt(0)
	v_add_f32_e32 v36, v36, v37
	v_add_f32_e32 v36, v130, v36
	v_div_scale_f32 v37, s[26:27], v36, v36, 1.0
	v_rcp_f32_e32 v39, v37
	v_div_scale_f32 v38, vcc, 1.0, v36, 1.0
	v_fma_f32 v40, -v37, v39, 1.0
	v_fmac_f32_e32 v39, v40, v39
	v_mul_f32_e32 v40, v38, v39
	v_fma_f32 v41, -v37, v40, v38
	v_fmac_f32_e32 v40, v41, v39
	v_fma_f32 v37, -v37, v40, v38
	v_div_fmas_f32 v37, v37, v39, v40
	v_div_fixup_f32 v48, v37, v36, 1.0
	v_mul_f32_e32 v12, v12, v48
	v_mul_f32_e32 v13, v13, v48
	v_mul_f32_e32 v14, v14, v48
	v_mul_f32_e32 v15, v15, v48
	v_cvt_pk_bf16_f32 v44, v12, v13
	v_cvt_pk_bf16_f32 v45, v14, v15
	ds_read2_b64 v[12:15], v81 offset0:32 offset1:36
	ds_read2_b64 v[36:39], v81 offset0:40 offset1:44
	s_waitcnt lgkmcnt(1)
	v_mfma_f32_16x16x32_bf16 v[12:15], v[12:15], v[20:23], 0
	s_waitcnt lgkmcnt(0)
	v_mfma_f32_16x16x32_bf16 v[12:15], v[36:39], v[24:27], v[12:15]
	ds_read2_b64 v[36:39], v81 offset0:48 offset1:52
	ds_read2_b64 v[40:43], v81 offset0:56 offset1:60
	global_store_dwordx2 v[18:19], v[44:45], off offset:512 nt
	s_waitcnt lgkmcnt(1)
	v_mfma_f32_16x16x32_bf16 v[12:15], v[36:39], v[28:31], v[12:15]
	ds_read_b64 v[36:37], v99 offset:8704
	s_waitcnt lgkmcnt(0)
	v_mov_b32_e32 v38, v36
	v_mov_b32_e32 v39, v37
	v_mfma_f32_16x16x32_bf16 v[12:15], v[40:43], v[32:35], v[12:15]
	s_nop 0
	v_mfma_f32_16x16x32_bf16 v[12:15], v[36:39], v[0:3], v[12:15]
	s_nop 7
	v_mul_f32_e32 v12, v48, v12
	v_mul_f32_e32 v13, v48, v13
	v_mul_f32_e32 v14, v48, v14
	v_mul_f32_e32 v15, v48, v15
	v_cvt_pk_bf16_f32 v18, v12, v13
	v_cvt_pk_bf16_f32 v19, v14, v15
	ds_read2_b64 v[12:15], v82 offset0:64 offset1:68
	ds_read2_b64 v[36:39], v82 offset0:72 offset1:76
	ds_read2_b64 v[40:43], v82 offset0:80 offset1:84
	s_waitcnt lgkmcnt(2)
	v_mfma_f32_16x16x32_bf16 v[12:15], v[12:15], v[20:23], 0
	s_waitcnt lgkmcnt(1)
	v_mfma_f32_16x16x32_bf16 v[12:15], v[36:39], v[24:27], v[12:15]
	ds_read2_b64 v[36:39], v82 offset0:88 offset1:92
	ds_read_b64 v[44:45], v99 offset:17152
	global_store_dwordx2 v[16:17], v[18:19], off offset:32 nt
	v_mov_b32_e32 v99, v80
	s_waitcnt lgkmcnt(2)
	v_mfma_f32_16x16x32_bf16 v[12:15], v[40:43], v[28:31], v[12:15]
	s_waitcnt lgkmcnt(0)
	v_mov_b32_e32 v46, v44
	v_mov_b32_e32 v47, v45
	v_mfma_f32_16x16x32_bf16 v[12:15], v[36:39], v[32:35], v[12:15]
	s_nop 0
	v_mfma_f32_16x16x32_bf16 v[12:15], v[44:47], v[0:3], v[12:15]
	s_nop 7
	v_mul_f32_e32 v12, v48, v12
	v_mul_f32_e32 v13, v48, v13
	v_mul_f32_e32 v14, v48, v14
	v_mul_f32_e32 v15, v48, v15
	v_cvt_pk_bf16_f32 v40, v12, v13
	v_cvt_pk_bf16_f32 v41, v14, v15
	ds_read2_b64 v[12:15], v123 offset1:4
	ds_read2_b64 v[36:39], v123 offset0:8 offset1:12
	s_waitcnt lgkmcnt(1)
	v_mfma_f32_16x16x32_bf16 v[12:15], v[12:15], v[20:23], 0
	ds_read2_b64 v[18:21], v123 offset0:16 offset1:20
	s_waitcnt lgkmcnt(1)
	v_mfma_f32_16x16x32_bf16 v[12:15], v[36:39], v[24:27], v[12:15]
	ds_read2_b64 v[22:25], v123 offset0:24 offset1:28
	ds_read_b64 v[26:27], v123 offset:256
	v_mov_b32_e32 v123, v83
	global_store_dwordx2 v[16:17], v[40:41], off offset:64 nt
	s_waitcnt lgkmcnt(2)
	v_mfma_f32_16x16x32_bf16 v[12:15], v[18:21], v[28:31], v[12:15]
	s_waitcnt lgkmcnt(0)
	v_mov_b32_e32 v28, v26
	v_mov_b32_e32 v29, v27
	v_mfma_f32_16x16x32_bf16 v[12:15], v[22:25], v[32:35], v[12:15]
	s_nop 0
	v_mfma_f32_16x16x32_bf16 v[12:15], v[26:29], v[0:3], v[12:15]
	s_nop 7
	v_mul_f32_e32 v0, v48, v12
	v_mul_f32_e32 v1, v48, v13
	v_mul_f32_e32 v3, v48, v14
	v_mul_f32_e32 v12, v48, v15
	v_cvt_pk_bf16_f32 v0, v0, v1
	v_cvt_pk_bf16_f32 v1, v3, v12
	global_store_dwordx2 v[16:17], v[0:1], off offset:96 nt
	s_cbranch_scc1 .LBB0_1069
	s_add_i32 s3, s3, s42
	s_cmp_gt_i32 s3, s99
	s_barrier
	s_cbranch_scc0 .LBB0_1060
.LBB0_1071:
	v_mov_b32_e32 v54, v176
	s_mov_b32 s3, 32
	s_and_b32 s29, s2, 7
	s_lshl_b32 s29, s29, 7
	s_lshr_b32 s98, s2, 3
	s_add_i32 s29, s29, s98
	s_add_i32 s99, s29, 96
	s_mov_b64 s[8:9], s[0:1]
	v_readfirstlane_b32 s20, v54
	s_cmpk_gt_i32 s29, 0x3ff
	s_cbranch_scc1 .LBB0_1104
	v_mov_b64_e32 v[10:11], s[8:9]
	flat_load_dwordx4 v[2:5], v[10:11] offset:120
	flat_load_dwordx4 v[6:9], v[10:11] offset:136
	flat_load_dwordx2 v[40:41], v[10:11] offset:216
	flat_load_dwordx2 v[12:13], v[10:11] offset:152
	v_and_b32_e32 v55, 0xff, v54
	v_mov_b32_e32 v0, 0
	v_lshlrev_b32_e32 v10, 2, v55
	v_mov_b32_e32 v11, v0
	s_movk_i32 s10, 0x7000
	s_mov_b32 s11, 0x8000
	s_mov_b32 s12, 0x9000
	s_mov_b32 s13, 0xa000
	s_mov_b32 s14, 0xb000
	s_mov_b32 s15, 0xc000
	s_mov_b32 s16, 0xd000
	s_mov_b32 s17, 0xe000
	s_mov_b64 s[8:9], 0x7c00
	s_mov_b32 s18, 0xf000
	v_and_b32_e32 v56, 63, v54
	s_lshl_b32 s22, s29, 5
	v_ashrrev_i32_e32 v90, 5, v54
	v_lshlrev_b32_e32 v57, 3, v54
	v_and_b32_e32 v94, 0xf8, v57
	v_mov_b32_e32 v1, v0
	v_lshlrev_b32_e32 v52, 1, v94
	s_waitcnt vmcnt(0) lgkmcnt(0)
	v_lshl_add_u64 v[2:3], v[2:3], 0, v[10:11]
	v_add_co_u32_e32 v16, vcc, s10, v2
	v_lshl_add_u64 v[14:15], v[2:3], 0, s[8:9]
	s_nop 0
	v_addc_co_u32_e32 v17, vcc, 0, v3, vcc
	v_add_co_u32_e32 v18, vcc, s11, v2
	s_movk_i32 s8, 0x1000
	s_nop 0
	v_addc_co_u32_e32 v19, vcc, 0, v3, vcc
	v_add_co_u32_e32 v20, vcc, s12, v2
	s_nop 1
	v_addc_co_u32_e32 v21, vcc, 0, v3, vcc
	v_add_co_u32_e32 v22, vcc, s13, v2
	s_nop 1
	v_addc_co_u32_e32 v23, vcc, 0, v3, vcc
	v_add_co_u32_e32 v24, vcc, s14, v2
	s_nop 1
	v_addc_co_u32_e32 v25, vcc, 0, v3, vcc
	v_add_co_u32_e32 v26, vcc, s15, v2
	s_nop 1
	v_addc_co_u32_e32 v27, vcc, 0, v3, vcc
	v_add_co_u32_e32 v28, vcc, s16, v2
	s_nop 1
	v_addc_co_u32_e32 v29, vcc, 0, v3, vcc
	v_add_co_u32_e32 v30, vcc, s17, v2
	s_nop 1
	v_addc_co_u32_e32 v31, vcc, 0, v3, vcc
	v_add_co_u32_e32 v2, vcc, s18, v2
	s_nop 1
	v_addc_co_u32_e32 v3, vcc, 0, v3, vcc
	global_load_dword v58, v[16:17], off offset:3072
	global_load_dword v59, v[14:15], off offset:1024
	global_load_dword v60, v[14:15], off offset:2048
	global_load_dword v61, v[18:19], off offset:3072
	global_load_dword v62, v[20:21], off offset:1024
	global_load_dword v63, v[20:21], off offset:2048
	global_load_dword v64, v[20:21], off offset:3072
	global_load_dword v65, v[14:15], off offset:3072
	global_load_dword v66, v[22:23], off offset:-4096
	global_load_dword v67, v[22:23], off
	global_load_dword v68, v[22:23], off offset:1024
	global_load_dword v69, v[22:23], off offset:2048
	global_load_dword v70, v[22:23], off offset:3072
	global_load_dword v71, v[26:27], off offset:-4096
	global_load_dword v72, v[26:27], off
	global_load_dword v73, v[26:27], off offset:1024
	global_load_dword v74, v[26:27], off offset:2048
	global_load_dword v75, v[26:27], off offset:3072
	global_load_dword v76, v[30:31], off offset:-4096
	global_load_dword v77, v[30:31], off
	global_load_dword v78, v[30:31], off offset:1024
	global_load_dword v79, v[30:31], off offset:2048
	global_load_dword v80, v[30:31], off offset:3072
	global_load_dword v81, v[24:25], off offset:1024
	global_load_dword v82, v[24:25], off offset:2048
	global_load_dword v83, v[24:25], off offset:3072
	global_load_dword v84, v[28:29], off offset:1024
	global_load_dword v85, v[28:29], off offset:2048
	global_load_dword v86, v[28:29], off offset:3072
	global_load_dword v87, v[2:3], off
	global_load_dword v88, v[2:3], off offset:1024
	v_lshl_add_u64 v[2:3], v[4:5], 0, v[10:11]
	global_load_dword v89, v[2:3], off offset:1024
	v_lshlrev_b32_e32 v2, 4, v56
	v_mov_b32_e32 v3, v0
	v_lshl_add_u64 v[4:5], v[6:7], 0, v[2:3]
	v_lshl_add_u64 v[8:9], v[8:9], 0, v[2:3]
	v_lshl_add_u64 v[2:3], v[12:13], 0, v[2:3]
	v_add_co_u32_e32 v2, vcc, s8, v2
	global_load_dwordx4 v[4:7], v[4:5], off offset:1024
	s_nop 0
	v_addc_co_u32_e32 v3, vcc, 0, v3, vcc
	global_load_dwordx4 v[8:11], v[8:9], off offset:1024
	s_and_b32 s8, s2, 7
	s_lshl_b32 s8, s8, 23
	s_add_u32 s8, s8, 0xd000000
	s_mov_b32 s9, 0
	global_load_dwordx4 v[12:15], v[2:3], off offset:3072
	v_lshl_add_u64 v[50:51], v[40:41], 0, s[8:9]
	s_ashr_i32 s8, s29, 7
	s_and_b32 s9, s22, 0xfe0
	s_sub_i32 s18, s9, 30
	s_ashr_i32 s9, s8, 31
	s_lshl_b64 s[16:17], s[8:9], 12
	v_add_u32_e32 v24, s18, v90
	s_movk_i32 s8, 0x7c0
	v_mov_b32_e32 v2, v0
	v_mov_b32_e32 v3, v0
	v_cmp_gt_i32_e64 s[8:9], s8, v54
	v_cmp_lt_i32_e32 vcc, -1, v24
	v_mov_b64_e32 v[22:23], v[2:3]
	v_mov_b64_e32 v[18:19], v[2:3]
	s_and_b64 s[12:13], s[8:9], vcc
	v_mov_b64_e32 v[20:21], v[0:1]
	v_mov_b64_e32 v[16:17], v[0:1]
	s_and_saveexec_b64 s[10:11], s[12:13]
	s_cbranch_execz .LBB0_1074
	v_mov_b32_e32 v25, v0
	v_lshl_add_u64 v[16:17], s[16:17], 0, v[24:25]
	s_movk_i32 s14, 0xe00
	v_mad_u64_u32 v[18:19], s[12:13], v16, s14, v[50:51]
	v_mad_i32_i24 v19, v17, s14, v19
	v_mov_b32_e32 v53, v0
	v_lshl_add_u64 v[24:25], v[18:19], 0, v[52:53]
	global_load_dwordx4 v[16:19], v[24:25], off offset:2560
	global_load_dwordx4 v[20:23], v[24:25], off offset:3072
.LBB0_1074:
	s_or_b64 exec, exec, s[10:11]
	v_add_u32_e32 v97, 0x200, v54
	v_ashrrev_i32_e32 v91, 5, v97
	v_add_u32_e32 v24, s18, v91
	s_movk_i32 s10, 0x5c0
	v_cmp_gt_i32_e64 s[10:11], s10, v54
	v_cmp_lt_i32_e32 vcc, -1, v24
	v_mov_b64_e32 v[30:31], v[2:3]
	s_and_b64 s[14:15], s[10:11], vcc
	v_mov_b64_e32 v[28:29], v[0:1]
	s_and_saveexec_b64 s[12:13], s[14:15]
	s_cbranch_execz .LBB0_1076
	v_mov_b32_e32 v25, 0
	v_lshl_add_u64 v[0:1], s[16:17], 0, v[24:25]
	s_movk_i32 s19, 0xe00
	v_mad_u64_u32 v[2:3], s[14:15], v0, s19, v[50:51]
	v_mad_i32_i24 v3, v1, s19, v3
	v_mov_b32_e32 v53, v25
	v_lshl_add_u64 v[24:25], v[2:3], 0, v[52:53]
	global_load_dwordx4 v[28:31], v[24:25], off offset:2560
	global_load_dwordx4 v[0:3], v[24:25], off offset:3072
.LBB0_1076:
	s_or_b64 exec, exec, s[12:13]
	v_add_u32_e32 v98, 0x400, v54
	v_ashrrev_i32_e32 v92, 5, v98
	v_mov_b32_e32 v25, 0
	v_add_u32_e32 v42, s18, v92
	s_movk_i32 s12, 0x3c0
	v_mov_b32_e32 v26, v25
	v_mov_b32_e32 v27, v25
	v_cmp_gt_i32_e64 s[12:13], s12, v54
	v_cmp_lt_i32_e32 vcc, -1, v42
	v_mov_b32_e32 v24, v25
	v_mov_b64_e32 v[38:39], v[26:27]
	v_mov_b64_e32 v[34:35], v[26:27]
	s_and_b64 s[26:27], s[12:13], vcc
	v_mov_b64_e32 v[36:37], v[24:25]
	v_mov_b64_e32 v[32:33], v[24:25]
	s_and_saveexec_b64 s[14:15], s[26:27]
	s_cbranch_execz .LBB0_1078
	v_mov_b32_e32 v43, 0
	v_lshl_add_u64 v[26:27], s[16:17], 0, v[42:43]
	s_movk_i32 s19, 0xe00
	v_mad_u64_u32 v[32:33], s[26:27], v26, s19, v[50:51]
	v_mad_i32_i24 v33, v27, s19, v33
	v_mov_b32_e32 v53, v43
	v_lshl_add_u64 v[26:27], v[32:33], 0, v[52:53]
	global_load_dwordx4 v[32:35], v[26:27], off offset:2560
	global_load_dwordx4 v[36:39], v[26:27], off offset:3072
.LBB0_1078:
	s_or_b64 exec, exec, s[14:15]
	v_add_u32_e32 v24, 0x600, v54
	v_ashrrev_i32_e32 v93, 5, v24
	v_add_u32_e32 v26, s18, v93
	s_movk_i32 s14, 0x1c0
	v_cmp_gt_i32_e64 s[14:15], s14, v54
	v_cmp_lt_i32_e32 vcc, -1, v26
	s_and_b64 s[26:27], s[14:15], vcc
	v_mov_b32_e32 v46, 0
	v_mov_b32_e32 v47, 0
	v_mov_b32_e32 v48, 0
	v_mov_b32_e32 v49, 0
	v_mov_b32_e32 v42, 0
	v_mov_b32_e32 v43, 0
	v_mov_b32_e32 v44, 0
	v_mov_b32_e32 v45, 0
	s_and_saveexec_b64 s[18:19], s[26:27]
	s_cbranch_execz .LBB0_1080
	v_mov_b32_e32 v27, 0
	v_lshl_add_u64 v[42:43], s[16:17], 0, v[26:27]
	s_movk_i32 s21, 0xe00
	v_mad_u64_u32 v[44:45], s[16:17], v42, s21, v[50:51]
	v_mad_i32_i24 v45, v43, s21, v45
	v_mov_b32_e32 v53, v27
	v_lshl_add_u64 v[26:27], v[44:45], 0, v[52:53]
	global_load_dwordx4 v[42:45], v[26:27], off offset:2560
	global_load_dwordx4 v[46:49], v[26:27], off offset:3072
.LBB0_1080:
	s_or_b64 exec, exec, s[18:19]
	v_lshrrev_b32_e32 v27, 4, v54
	v_lshl_add_u32 v26, v94, 2, 0
	v_and_b32_e32 v94, 0x3ffff0, v27
	v_and_b32_e32 v27, 0x3fffff00, v57
	s_ashr_i32 s18, s20, 4
	v_lshl_add_u32 v96, v27, 2, v26
	v_lshlrev_b32_e32 v27, 5, v97
	s_and_b32 s16, s18, -4
	v_and_b32_e32 v27, 0xfffffc00, v27
	v_add_u32_e32 v97, v26, v27
	v_lshlrev_b32_e32 v27, 5, v98
	v_lshlrev_b32_e32 v24, 5, v24
	s_ashr_i32 s17, s16, 31
	v_and_b32_e32 v27, 0xfffffc00, v27
	v_and_b32_e32 v24, 0xfffffc00, v24
	v_mov_b32_e32 v53, v25
	s_lshl_b64 s[16:17], s[16:17], 11
	v_add_u32_e32 v98, v26, v27
	v_add_u32_e32 v99, v26, v24
	v_lshl_add_u64 v[26:27], v[50:51], 0, v[52:53]
	v_lshl_or_b32 v50, v56, 3, s16
	s_lshl_b32 s16, s18, 10
	s_and_b32 s16, s16, 0xfffff000
	s_add_i32 s16, s16, 0
	v_mov_b32_e32 v51, s17
	v_lshl_add_u32 v24, v56, 4, s16
	v_lshl_add_u32 v95, v55, 2, 0
	v_lshl_add_u64 v[54:55], v[40:41], 0, v[50:51]
	s_lshl_b32 s23, s3, 5
	v_add_u32_e32 v100, 0xf800, v24
	s_movk_i32 s26, 0xe00
	v_mov_b32_e32 v101, 0x3727c5ac
	s_mov_b32 s27, 0x800000
	v_mov_b32_e32 v102, 0x358637bd
	s_mov_b32 s28, 0x9000000
	v_mov_b32_e32 v40, 0

.LBB0_1089:
	s_or_b64 exec, exec, s[16:17]
	s_add_i32 s30, s29, s3
	s_cmp_gt_i32 s30, s99
	s_cselect_b64 s[16:17], -1, 0
	s_and_b64 vcc, exec, s[16:17]
	s_waitcnt lgkmcnt(0)
	s_barrier
	s_cbranch_vccnz .LBB0_1099
	s_lshl_b32 s19, s30, 5
	s_and_b32 s19, s19, 0xfe0
	s_sub_i32 s31, s19, 30
	s_ashr_i32 s18, s30, 7
	v_add_u32_e32 v24, s31, v90
	s_waitcnt vmcnt(0)
	v_mov_b32_e32 v2, v40
	v_mov_b32_e32 v3, v40
	s_ashr_i32 s19, s18, 31
	v_cmp_lt_i32_e32 vcc, -1, v24
	v_mov_b32_e32 v0, 0
	v_mov_b32_e32 v1, v40
	v_mov_b64_e32 v[22:23], v[2:3]
	v_mov_b64_e32 v[18:19], v[2:3]
	s_lshl_b64 s[18:19], s[18:19], 12
	s_and_b64 s[34:35], s[8:9], vcc
	v_mov_b64_e32 v[20:21], v[0:1]
	v_mov_b64_e32 v[16:17], v[0:1]
	s_and_saveexec_b64 s[20:21], s[34:35]
	s_cbranch_execz .LBB0_1092
	v_lshl_add_u64 v[16:17], s[18:19], 0, v[24:25]
	v_mad_u64_u32 v[28:29], s[34:35], v16, s26, v[26:27]
	v_mad_i32_i24 v29, v17, s26, v29
	global_load_dwordx4 v[16:19], v[28:29], off offset:2560
	global_load_dwordx4 v[20:23], v[28:29], off offset:3072
.LBB0_1092:
	s_or_b64 exec, exec, s[20:21]
	v_add_u32_e32 v24, s31, v91
	v_cmp_lt_i32_e32 vcc, -1, v24
	v_mov_b64_e32 v[30:31], v[2:3]
	s_and_b64 s[34:35], s[10:11], vcc
	v_mov_b64_e32 v[28:29], v[0:1]
	s_and_saveexec_b64 s[20:21], s[34:35]
	s_cbranch_execz .LBB0_1094
	v_lshl_add_u64 v[0:1], s[18:19], 0, v[24:25]
	v_mad_u64_u32 v[32:33], s[34:35], v0, s26, v[26:27]
	v_mad_i32_i24 v33, v1, s26, v33
	global_load_dwordx4 v[28:31], v[32:33], off offset:2560
	global_load_dwordx4 v[0:3], v[32:33], off offset:3072
.LBB0_1094:
	s_or_b64 exec, exec, s[20:21]
	v_add_u32_e32 v24, s31, v92
	v_mov_b32_e32 v41, v40
	v_cmp_lt_i32_e32 vcc, -1, v24
	v_mov_b32_e32 v42, v40
	v_mov_b32_e32 v43, v40
	v_mov_b64_e32 v[36:37], v[40:41]
	v_mov_b64_e32 v[32:33], v[40:41]
	s_and_b64 s[34:35], s[12:13], vcc
	v_mov_b64_e32 v[38:39], v[42:43]
	v_mov_b64_e32 v[34:35], v[42:43]
	s_and_saveexec_b64 s[20:21], s[34:35]
	s_cbranch_execz .LBB0_1096
	v_lshl_add_u64 v[32:33], s[18:19], 0, v[24:25]
	v_mad_u64_u32 v[42:43], s[34:35], v32, s26, v[26:27]
	v_mad_i32_i24 v43, v33, s26, v43
	global_load_dwordx4 v[32:35], v[42:43], off offset:2560
	global_load_dwordx4 v[36:39], v[42:43], off offset:3072
.LBB0_1096:
	s_or_b64 exec, exec, s[20:21]
	v_add_u32_e32 v24, s31, v93
	v_cmp_lt_i32_e32 vcc, -1, v24
	s_and_b64 s[34:35], s[14:15], vcc
	v_mov_b32_e32 v45, 0
	v_mov_b32_e32 v44, 0
	v_mov_b32_e32 v43, 0
	v_mov_b32_e32 v42, 0
	v_mov_b32_e32 v49, 0
	v_mov_b32_e32 v48, 0
	v_mov_b32_e32 v47, 0
	v_mov_b32_e32 v46, 0
	s_and_saveexec_b64 s[20:21], s[34:35]
	s_cbranch_execz .LBB0_1098
	v_lshl_add_u64 v[42:43], s[18:19], 0, v[24:25]
	v_mad_u64_u32 v[50:51], s[18:19], v42, s26, v[26:27]
	v_mad_i32_i24 v51, v43, s26, v51
	global_load_dwordx4 v[42:45], v[50:51], off offset:2560
	global_load_dwordx4 v[46:49], v[50:51], off offset:3072

.LBB0_1148:
	s_or_b64 exec, exec, s[48:49]
	s_waitcnt vmcnt(0)
	v_mov_b32_e32 v0, v176
	s_and_b32 s3, s2, 7
	s_lshl_b32 s3, s3, 6
	s_lshr_b32 s98, s2, 3
	s_add_i32 s3, s3, s98
	s_add_i32 s99, s3, 32
	s_mov_b32 s22, 32
	s_waitcnt lgkmcnt(0)
	s_barrier
	s_mov_b64 s[8:9], s[0:1]
	v_readfirstlane_b32 s10, v0
	s_cmpk_lt_i32 s3, 0x200
	s_cbranch_scc0 .LBB0_1182
	s_ashr_i32 s23, s10, 6
	v_and_b32_e32 v0, 63, v0
	s_lshl_b32 s10, s23, 10
	v_mov_b32_e32 v75, 0
	s_add_i32 s10, s10, 0
	v_lshlrev_b32_e32 v1, 4, v0
	v_lshlrev_b32_e32 v2, 1, v0
	s_lshl_b32 s26, s23, 3
	v_lshlrev_b32_e32 v4, 3, v0
	v_lshlrev_b32_e32 v72, 2, v0
	v_lshlrev_b32_e32 v76, 5, v0
	v_mov_b32_e32 v77, v75
	v_add_u32_e32 v73, s10, v1
	v_add_u32_e32 v108, 0, v1
	s_ashr_i32 s27, s26, 31
	v_mov_b64_e32 v[78:79], s[8:9]
	s_mov_b64 s[10:11], 0x1a000000
	s_mov_b64 s[12:13], 0x9000000
	v_lshlrev_b32_e32 v74, 4, v0
	s_movk_i32 s28, 0x1000
	v_lshlrev_b32_e32 v80, 4, v2
	s_mov_b64 s[14:15], 0x1400
	s_mov_b64 s[16:17], 0x18000000
	s_and_b32 s29, s2, 7
	s_lshl_b32 s29, s29, 23
	s_add_u32 s29, s29, 0xd000000
	v_lshlrev_b32_e32 v82, 1, v4
	s_and_b32 s30, s2, 7
	s_lshl_b32 s30, s30, 23
	s_add_u32 s30, s30, 0xd001000
	s_and_b32 s31, s2, 7
	s_lshl_b32 s31, s31, 23
	s_add_u32 s31, s31, 0xd002000
	s_and_b32 s34, s2, 7
	s_lshl_b32 s34, s34, 23
	s_add_u32 s34, s34, 0xd003000
	s_and_b32 s35, s2, 7
	s_lshl_b32 s35, s35, 23
	s_add_u32 s35, s35, 0xd004000
	s_and_b32 s36, s2, 7
	s_lshl_b32 s36, s36, 23
	s_add_u32 s36, s36, 0xd005000
	s_and_b32 s37, s2, 7
	s_lshl_b32 s37, s37, 23
	s_add_u32 s37, s37, 0xd006000
	v_mov_b32_e32 v109, 0x358637bd
	s_mov_b32 s38, 0x800000
	s_movk_i32 s39, 0x2000
	s_movk_i32 s40, 0x3000
	v_mov_b32_e32 v110, 0xe00
	s_branch .LBB0_1152

.LBB0_1151:
	v_pk_fma_f32 v[56:57], v[62:63], 0, v[66:67] op_sel_hi:[1,0,1]
	v_mov_b32_e32 v9, v10
	v_mov_b32_e32 v13, v11
	v_pk_fma_f32 v[10:11], v[8:9], v[56:57], v[12:13]
	v_mov_b32_e32 v5, v6
	v_mov_b32_e32 v17, v7
	v_pk_mul_f32 v[8:9], v[62:63], v[8:9]
	v_pk_fma_f32 v[6:7], v[4:5], v[10:11], v[16:17]
	v_mov_b32_e32 v23, v24
	v_pk_mul_f32 v[4:5], v[4:5], v[8:9]
	v_mov_b32_e32 v31, v32
	v_pk_mul_f32 v[4:5], v[22:23], v[4:5]
	v_mov_b32_e32 v39, v40
	v_pk_mul_f32 v[4:5], v[30:31], v[4:5]
	v_pk_fma_f32 v[12:13], v[0:1], 0, v[64:65] op_sel_hi:[1,0,1]
	v_mov_b32_e32 v47, v48
	v_pk_mul_f32 v[4:5], v[38:39], v[4:5]
	v_pk_mul_f32 v[0:1], v[0:1], v[2:3]
	v_pk_fma_f32 v[12:13], v[12:13], v[2:3], v[68:69]
	v_mov_b32_e32 v21, v25
	v_pk_mul_f32 v[4:5], v[46:47], v[4:5]
	v_pk_mul_f32 v[0:1], v[0:1], v[14:15]
	v_pk_fma_f32 v[6:7], v[22:23], v[6:7], v[20:21]
	v_mov_b32_e32 v29, v33
	v_pk_mul_f32 v[10:11], v[54:55], v[4:5]
	v_pk_fma_f32 v[4:5], v[12:13], v[14:15], v[70:71]
	v_pk_mul_f32 v[0:1], v[0:1], v[18:19]
	v_pk_fma_f32 v[6:7], v[30:31], v[6:7], v[28:29]
	v_mov_b32_e32 v37, v41
	v_pk_fma_f32 v[4:5], v[4:5], v[18:19], v[84:85]
	v_pk_mul_f32 v[0:1], v[0:1], v[26:27]
	v_pk_fma_f32 v[6:7], v[38:39], v[6:7], v[36:37]
	v_pk_fma_f32 v[4:5], v[4:5], v[26:27], v[86:87]
	v_pk_mul_f32 v[0:1], v[0:1], v[34:35]
	v_pk_fma_f32 v[6:7], v[46:47], v[6:7], v[44:45]
	v_pk_fma_f32 v[4:5], v[4:5], v[34:35], v[88:89]
	v_pk_mul_f32 v[0:1], v[0:1], v[42:43]
	v_pk_fma_f32 v[6:7], v[54:55], v[6:7], v[52:53]
	v_pk_fma_f32 v[4:5], v[4:5], v[42:43], v[90:91]
	v_pk_mul_f32 v[12:13], v[0:1], v[50:51]
	v_pk_fma_f32 v[8:9], v[4:5], v[50:51], v[92:93]
	ds_write_b128 v73, v[10:13]
	ds_write_b128 v73, v[6:9] offset:8192
	s_waitcnt lgkmcnt(0)
	s_barrier
	ds_read_b128 v[0:3], v108
	ds_read_b128 v[4:7], v108 offset:8192
	ds_read_b128 v[8:11], v108 offset:1024
	ds_read_b128 v[12:15], v108 offset:9216
	s_ashr_i32 s8, s3, 6
	v_mov_b32_e32 v81, v75
	s_ashr_i32 s9, s8, 31
	s_waitcnt lgkmcnt(2)
	v_pk_fma_f32 v[18:19], v[2:3], 0, v[6:7] op_sel_hi:[1,0,1]
	v_pk_fma_f32 v[20:21], v[0:1], 0, v[4:5] op_sel_hi:[1,0,1]
	ds_read_b128 v[0:3], v108 offset:2048
	ds_read_b128 v[4:7], v108 offset:10240
	s_waitcnt lgkmcnt(2)
	v_pk_fma_f32 v[18:19], v[18:19], v[10:11], v[14:15]
	v_pk_fma_f32 v[20:21], v[20:21], v[8:9], v[12:13]
	ds_read_b128 v[8:11], v108 offset:3072
	ds_read_b128 v[12:15], v108 offset:11264
	s_lshl_b64 s[8:9], s[8:9], 12
	s_waitcnt lgkmcnt(2)
	v_pk_fma_f32 v[18:19], v[18:19], v[2:3], v[6:7]
	v_pk_fma_f32 v[20:21], v[20:21], v[0:1], v[4:5]
	ds_read_b128 v[0:3], v108 offset:4096
	ds_read_b128 v[4:7], v108 offset:12288
	s_waitcnt lgkmcnt(2)
	v_pk_fma_f32 v[18:19], v[18:19], v[10:11], v[14:15]
	v_pk_fma_f32 v[20:21], v[20:21], v[8:9], v[12:13]
	ds_read_b128 v[8:11], v108 offset:5120
	ds_read_b128 v[12:15], v108 offset:13312
	s_lshl_b32 s18, s41, 6
	s_waitcnt lgkmcnt(2)
	v_pk_fma_f32 v[18:19], v[18:19], v[2:3], v[6:7]
	v_pk_fma_f32 v[20:21], v[20:21], v[0:1], v[4:5]
	ds_read_b128 v[0:3], v108 offset:6144
	ds_read_b128 v[4:7], v108 offset:14336
	s_waitcnt lgkmcnt(2)
	v_pk_fma_f32 v[8:9], v[20:21], v[8:9], v[12:13]
	s_add_u32 s18, s18, s26
	v_pk_fma_f32 v[10:11], v[18:19], v[10:11], v[14:15]
	s_addc_u32 s19, 0, s27
	s_waitcnt lgkmcnt(0)
	v_pk_fma_f32 v[88:89], v[8:9], v[0:1], v[4:5]
	v_lshl_add_u64 v[0:1], v[60:61], 0, v[74:75]
	v_add_co_u32_e32 v12, vcc, s28, v0
	ds_read_b128 v[112:115], v108 offset:7168
	ds_read_b128 v[116:119], v108 offset:15360
	v_addc_co_u32_e32 v13, vcc, 0, v1, vcc
	v_lshl_add_u64 v[0:1], v[60:61], 0, v[80:81]
	v_add_co_u32_e32 v20, vcc, s28, v0
	v_pk_fma_f32 v[18:19], v[10:11], v[2:3], v[6:7]
	s_nop 0
	v_addc_co_u32_e32 v21, vcc, 0, v1, vcc
	v_lshl_add_u64 v[14:15], v[0:1], 0, s[14:15]
	global_load_dwordx4 v[4:7], v[20:21], off offset:1024
	global_load_dwordx4 v[8:11], v[12:13], off
	global_load_dwordx4 v[0:3], v[14:15], off offset:16
	s_add_u32 s8, s18, s8
	v_lshlrev_b32_e32 v12, 2, v72
	v_mov_b32_e32 v13, v75
	s_addc_u32 s9, s19, s9
	v_lshl_add_u64 v[12:13], v[58:59], 0, v[12:13]
	v_lshl_add_u64 v[12:13], v[12:13], 0, s[16:17]
	s_lshl_b64 s[18:19], s[8:9], 10
	v_lshl_add_u64 v[14:15], v[12:13], 0, s[18:19]
	s_mul_i32 s20, s9, 0xe00
	v_mad_u64_u32 v[20:21], s[18:19], s8, v110, v[58:59]
	v_add_u32_e32 v21, s20, v21
	v_lshlrev_b32_e32 v104, 1, v72
	v_mov_b32_e32 v105, v75
	v_lshl_add_u64 v[86:87], v[20:21], 0, v[104:105]
	v_add_co_u32_e32 v20, vcc, s29, v86
	v_lshl_add_u64 v[16:17], v[58:59], 0, s[12:13]
	s_nop 0
	v_addc_co_u32_e32 v21, vcc, 0, v87, vcc
	global_load_dwordx4 v[120:123], v[14:15], off
	global_load_dwordx2 v[124:125], v[20:21], off offset:512
	s_lshl_b64 s[18:19], s[8:9], 11
	v_lshl_add_u64 v[106:107], v[16:17], 0, s[18:19]
	v_mov_b32_e32 v83, v75
	s_or_b32 s18, s8, 1
	s_mov_b32 s19, s9
	v_lshl_add_u64 v[84:85], v[106:107], 0, v[82:83]
	s_lshl_b64 s[20:21], s[18:19], 10
	v_lshl_add_u64 v[14:15], v[12:13], 0, s[20:21]
	global_load_dwordx4 v[68:71], v[84:85], off offset:512
	global_load_dwordx4 v[64:67], v[14:15], off
	s_lshl_b64 s[18:19], s[18:19], 11
	v_add_co_u32_e32 v14, vcc, s30, v86
	v_lshl_add_u64 v[20:21], v[16:17], 0, s[18:19]
	s_or_b32 s18, s8, 2
	s_mov_b32 s19, s9
	v_addc_co_u32_e32 v15, vcc, 0, v87, vcc
	v_lshl_add_u64 v[20:21], v[20:21], 0, v[82:83]
	s_lshl_b64 s[20:21], s[18:19], 10
	s_lshl_b64 s[18:19], s[18:19], 11
	v_lshl_add_u64 v[22:23], v[12:13], 0, s[20:21]
	global_load_dwordx4 v[60:63], v[20:21], off offset:512
	global_load_dwordx4 v[56:59], v[22:23], off
	global_load_dwordx2 v[102:103], v[14:15], off
	global_load_dwordx2 v[100:101], v[14:15], off offset:3584
	v_lshl_add_u64 v[14:15], v[16:17], 0, s[18:19]
	s_or_b32 s18, s8, 3
	s_mov_b32 s19, s9
	s_lshl_b64 s[20:21], s[18:19], 10
	v_lshl_add_u64 v[14:15], v[14:15], 0, v[82:83]
	v_lshl_add_u64 v[20:21], v[12:13], 0, s[20:21]
	s_lshl_b64 s[18:19], s[18:19], 11
	global_load_dwordx4 v[52:55], v[14:15], off offset:512
	global_load_dwordx4 v[48:51], v[20:21], off
	v_add_co_u32_e32 v14, vcc, s31, v86
	v_lshl_add_u64 v[20:21], v[16:17], 0, s[18:19]
	s_or_b32 s18, s8, 4
	s_mov_b32 s19, s9
	v_addc_co_u32_e32 v15, vcc, 0, v87, vcc
	v_lshl_add_u64 v[20:21], v[20:21], 0, v[82:83]
	s_lshl_b64 s[20:21], s[18:19], 10
	global_load_dwordx2 v[98:99], v[14:15], off offset:3072
	global_load_dwordx4 v[44:47], v[20:21], off offset:512
	v_lshl_add_u64 v[14:15], v[12:13], 0, s[20:21]
	v_add_co_u32_e32 v20, vcc, s34, v86
	s_lshl_b64 s[18:19], s[18:19], 11
	s_nop 0
	v_addc_co_u32_e32 v21, vcc, 0, v87, vcc
	global_load_dwordx4 v[40:43], v[14:15], off
	global_load_dwordx2 v[96:97], v[20:21], off offset:2560
	v_lshl_add_u64 v[14:15], v[16:17], 0, s[18:19]
	s_or_b32 s18, s8, 5
	s_mov_b32 s19, s9
	s_lshl_b64 s[20:21], s[18:19], 10
	v_lshl_add_u64 v[14:15], v[14:15], 0, v[82:83]
	v_lshl_add_u64 v[20:21], v[12:13], 0, s[20:21]
	s_lshl_b64 s[18:19], s[18:19], 11
	global_load_dwordx4 v[36:39], v[14:15], off offset:512
	global_load_dwordx4 v[32:35], v[20:21], off
	v_add_co_u32_e32 v14, vcc, s35, v86
	v_lshl_add_u64 v[20:21], v[16:17], 0, s[18:19]
	s_nop 0
	v_addc_co_u32_e32 v15, vcc, 0, v87, vcc
	v_lshl_add_u64 v[20:21], v[20:21], 0, v[82:83]
	s_or_b32 s18, s8, 6
	s_mov_b32 s19, s9
	global_load_dwordx2 v[94:95], v[14:15], off offset:2048
	global_load_dwordx4 v[28:31], v[20:21], off offset:512
	s_lshl_b64 s[20:21], s[18:19], 10
	v_add_co_u32_e32 v20, vcc, s36, v86
	v_lshl_add_u64 v[14:15], v[12:13], 0, s[20:21]
	s_nop 0
	v_addc_co_u32_e32 v21, vcc, 0, v87, vcc
	s_lshl_b64 s[18:19], s[18:19], 11
	s_or_b32 s8, s8, 7
	global_load_dwordx4 v[24:27], v[14:15], off
	global_load_dwordx2 v[92:93], v[20:21], off offset:1536
	v_lshl_add_u64 v[14:15], v[16:17], 0, s[18:19]
	s_lshl_b64 s[18:19], s[8:9], 10
	v_add_co_u32_e32 v86, vcc, s37, v86
	v_lshl_add_u64 v[14:15], v[14:15], 0, v[82:83]
	v_lshl_add_u64 v[12:13], v[12:13], 0, s[18:19]
	s_waitcnt vmcnt(18)
	v_lshlrev_b32_e32 v126, 16, v124
	v_mul_f32_e32 v81, 0x3d372713, v126
	v_mul_f32_e32 v81, v81, v126
	v_mov_b32_e32 v90, v126
	v_and_b32_e32 v127, 0xffff0000, v124
	v_fmac_f32_e32 v90, v81, v90
	v_mul_f32_e32 v81, 0x3f4c422a, v90
	v_mul_f32_e32 v90, 0x3d372713, v127
	v_mul_f32_e32 v90, v90, v127
	v_mov_b32_e32 v91, v127
	v_fmac_f32_e32 v91, v90, v91
	v_add_f32_e32 v81, v81, v81
	v_mul_f32_e32 v90, 0x3f4c422a, v91
	v_mul_f32_e32 v81, 0x3fb8aa3b, v81
	v_add_f32_e32 v90, v90, v90
	v_exp_f32_e32 v81, v81
	v_mul_f32_e32 v90, 0x3fb8aa3b, v90
	v_exp_f32_e32 v111, v90
	v_addc_co_u32_e32 v87, vcc, 0, v87, vcc
	v_add_f32_e32 v81, 1.0, v81
	global_load_dwordx4 v[20:23], v[14:15], off offset:512
	s_nop 0
	global_load_dwordx4 v[12:15], v[12:13], off
	v_rcp_f32_e32 v128, v81
	global_load_dwordx2 v[90:91], v[86:87], off offset:1024
	v_add_f32_e32 v81, 1.0, v111
	s_waitcnt lgkmcnt(0)
	v_pk_fma_f32 v[86:87], v[18:19], v[114:115], v[118:119]
	v_lshlrev_b32_e32 v114, 16, v125
	v_rcp_f32_e32 v129, v81
	v_mul_f32_e32 v81, 0x3d372713, v114
	v_mul_f32_e32 v81, v81, v114
	v_mov_b32_e32 v111, v114
	v_and_b32_e32 v115, 0xffff0000, v125
	v_fmac_f32_e32 v111, v81, v111
	v_mul_f32_e32 v81, 0x3f4c422a, v111
	v_mul_f32_e32 v111, 0x3d372713, v115
	v_pk_fma_f32 v[88:89], v[88:89], v[112:113], v[116:117]
	v_mul_f32_e32 v111, v111, v115
	v_mov_b32_e32 v116, v115
	v_fmac_f32_e32 v116, v111, v116
	v_add_f32_e32 v81, v81, v81
	v_mul_f32_e32 v111, 0x3f4c422a, v116
	v_mul_f32_e32 v81, 0x3fb8aa3b, v81
	v_add_f32_e32 v111, v111, v111
	v_exp_f32_e32 v81, v81
	v_mul_f32_e32 v111, 0x3fb8aa3b, v111
	v_exp_f32_e32 v111, v111
	v_pk_fma_f32 v[18:19], v[128:129], 2.0, 1.0 op_sel_hi:[1,0,0] neg_lo:[1,0,0] neg_hi:[1,0,0]
	v_add_f32_e32 v81, 1.0, v81
	v_rcp_f32_e32 v118, v81
	v_add_f32_e32 v81, 1.0, v111
	v_rcp_f32_e32 v119, v81
	v_pk_mul_f32 v[112:113], v[126:127], 0.5 op_sel_hi:[1,0]
	v_pk_add_f32 v[18:19], v[18:19], 1.0 op_sel_hi:[1,0]
	v_lshlrev_b32_e32 v117, 16, v121
	v_pk_mul_f32 v[18:19], v[112:113], v[18:19]
	v_and_b32_e32 v113, 0xffff0000, v121
	v_and_b32_e32 v112, 0xffff0000, v120
	v_lshlrev_b32_e32 v116, 16, v120
	v_pk_fma_f32 v[112:113], v[88:89], v[116:117], v[112:113]
	v_pk_mul_f32 v[114:115], v[114:115], 0.5 op_sel_hi:[1,0]
	v_pk_mul_f32 v[112:113], v[112:113], v[18:19]
	v_pk_fma_f32 v[18:19], v[118:119], 2.0, 1.0 op_sel_hi:[1,0,0] neg_lo:[1,0,0] neg_hi:[1,0,0]
	v_lshlrev_b32_e32 v117, 16, v123
	v_pk_add_f32 v[18:19], v[18:19], 1.0 op_sel_hi:[1,0]
	v_lshlrev_b32_e32 v116, 16, v122
	v_pk_mul_f32 v[18:19], v[114:115], v[18:19]
	v_and_b32_e32 v115, 0xffff0000, v123
	v_and_b32_e32 v114, 0xffff0000, v122
	v_pk_fma_f32 v[114:115], v[86:87], v[116:117], v[114:115]
	v_mov_b32_e32 v116, v113
	v_pk_mul_f32 v[114:115], v[114:115], v[18:19]
	v_mov_b32_e32 v18, v112
	v_mov_b32_e32 v117, v115
	v_mov_b32_e32 v19, v114
	v_pk_mul_f32 v[116:117], v[116:117], v[116:117]
	s_lshl_b64 s[8:9], s[8:9], 11
	v_pk_fma_f32 v[18:19], v[18:19], v[18:19], v[116:117]
	v_lshl_add_u64 v[16:17], v[16:17], 0, s[8:9]
	v_add_f32_e32 v18, v18, v19
	v_lshl_add_u64 v[16:17], v[16:17], 0, v[82:83]
	s_waitcnt vmcnt(20)
	v_and_b32_e32 v119, 0xffff0000, v70
	v_add_f32_dpp v18, v18, v18 quad_perm:[1,0,3,2] row_mask:0xf bank_mask:0xf bound_ctrl:1
	v_and_b32_e32 v118, 0xffff0000, v68
	v_lshlrev_b32_e32 v121, 16, v71
	v_add_f32_dpp v18, v18, v18 quad_perm:[2,3,0,1] row_mask:0xf bank_mask:0xf bound_ctrl:1
	v_and_b32_e32 v71, 0xffff0000, v71
	v_lshlrev_b32_e32 v120, 16, v69
	v_add_f32_dpp v18, v18, v18 row_half_mirror row_mask:0xf bank_mask:0xf bound_ctrl:1
	s_add_i32 s3, s3, s22
	s_cmp_gt_i32 s3, s99
	v_add_f32_dpp v18, v18, v18 row_mirror row_mask:0xf bank_mask:0xf bound_ctrl:1
	s_nop 0
	v_readlane_b32 s20, v18, 16
	v_readlane_b32 s21, v18, 48
	v_readlane_b32 s18, v18, 0
	v_readlane_b32 s19, v18, 32
	v_mov_b32_e32 v18, s20
	v_mov_b32_e32 v19, s21
	v_pk_add_f32 v[18:19], s[18:19], v[18:19]
	s_nop 0
	v_add_f32_e32 v18, v18, v19
	v_fmamk_f32 v18, v18, 0x3b800000, v109
	v_mul_f32_e32 v19, 0x4b800000, v18
	v_cmp_gt_f32_e32 vcc, s38, v18
	s_nop 1
	v_cndmask_b32_e32 v18, v18, v19, vcc
	v_rsq_f32_e32 v81, v18
	global_load_dwordx4 v[16:19], v[16:17], off offset:512
	v_mul_f32_e32 v83, 0x45800000, v81
	v_cndmask_b32_e32 v116, v81, v83, vcc
	v_pk_mul_f32 v[112:113], v[112:113], v[116:117] op_sel_hi:[1,0]
	v_pk_mul_f32 v[114:115], v[114:115], v[116:117] op_sel_hi:[1,0]
	v_lshlrev_b32_e32 v117, 16, v70
	v_and_b32_e32 v70, 0xffff0000, v69
	v_lshlrev_b32_e32 v116, 16, v68
	v_pk_mul_f32 v[68:69], v[118:119], v[118:119]
	v_pk_mul_f32 v[122:123], v[70:71], v[70:71]
	v_pk_fma_f32 v[68:69], v[116:117], v[116:117], v[68:69]
	v_pk_fma_f32 v[122:123], v[120:121], v[120:121], v[122:123]
	v_pk_mul_f32 v[114:115], v[10:11], v[114:115]
	v_pk_add_f32 v[68:69], v[68:69], v[122:123]
	v_pk_mul_f32 v[112:113], v[8:9], v[112:113]
	v_add_f32_e32 v68, v68, v69
	v_cvt_pk_bf16_f32 v112, v112, v113
	v_cvt_pk_bf16_f32 v113, v114, v115
	s_nop 1
	v_add_f32_dpp v68, v68, v68 quad_perm:[1,0,3,2] row_mask:0xf bank_mask:0xf bound_ctrl:1
	s_nop 1
	v_add_f32_dpp v68, v68, v68 quad_perm:[2,3,0,1] row_mask:0xf bank_mask:0xf bound_ctrl:1
	s_nop 1
	v_add_f32_dpp v68, v68, v68 row_half_mirror row_mask:0xf bank_mask:0xf bound_ctrl:1
	s_nop 1
	v_add_f32_dpp v68, v68, v68 row_mirror row_mask:0xf bank_mask:0xf bound_ctrl:1
	s_nop 0
	v_readlane_b32 s18, v68, 16
	v_readlane_b32 s19, v68, 48
	v_readlane_b32 s8, v68, 0
	v_readlane_b32 s9, v68, 32
	v_mov_b32_e32 v68, s18
	v_mov_b32_e32 v69, s19
	v_pk_add_f32 v[68:69], s[8:9], v[68:69]
	s_nop 0
	v_add_f32_e32 v68, v68, v69
	v_fmamk_f32 v68, v68, 0x3b000000, v109
	v_mul_f32_e32 v69, 0x4b800000, v68
	v_cmp_gt_f32_e32 vcc, s38, v68
	s_nop 1
	v_cndmask_b32_e32 v68, v68, v69, vcc
	v_rsq_f32_e32 v81, v68
	v_lshl_add_u64 v[68:69], v[106:107], 0, v[104:105]
	v_mov_b32_e32 v106, v116
	s_waitcnt vmcnt(17)
	v_lshlrev_b32_e32 v116, 16, v102
	v_mul_f32_e32 v83, 0x45800000, v81
	v_cndmask_b32_e32 v104, v81, v83, vcc
	v_mul_f32_e32 v81, 0x3d372713, v116
	v_mul_f32_e32 v81, v81, v116
	v_mov_b32_e32 v83, v116
	v_mov_b32_e32 v107, v118
	v_mov_b32_e32 v118, v117
	v_and_b32_e32 v117, 0xffff0000, v102
	v_fmac_f32_e32 v83, v81, v83
	v_mul_f32_e32 v81, 0x3f4c422a, v83
	v_mul_f32_e32 v83, 0x3d372713, v117
	v_mul_f32_e32 v83, v83, v117
	v_mov_b32_e32 v102, v117
	v_fmac_f32_e32 v102, v83, v102
	v_add_f32_e32 v81, v81, v81
	v_mul_f32_e32 v83, 0x3f4c422a, v102
	v_mul_f32_e32 v81, 0x3fb8aa3b, v81
	v_add_f32_e32 v83, v83, v83
	v_exp_f32_e32 v81, v81
	v_mul_f32_e32 v83, 0x3fb8aa3b, v83
	v_exp_f32_e32 v83, v83
	v_pk_mul_f32 v[114:115], v[118:119], v[104:105] op_sel_hi:[1,0]
	v_add_f32_e32 v81, 1.0, v81
	v_rcp_f32_e32 v118, v81
	v_add_f32_e32 v81, 1.0, v83
	v_lshlrev_b32_e32 v102, 16, v103
	v_rcp_f32_e32 v119, v81
	v_mul_f32_e32 v81, 0x3d372713, v102
	v_mul_f32_e32 v81, v81, v102
	v_mov_b32_e32 v83, v102
	v_and_b32_e32 v103, 0xffff0000, v103
	v_fmac_f32_e32 v83, v81, v83
	v_mul_f32_e32 v81, 0x3f4c422a, v83
	v_mul_f32_e32 v83, 0x3d372713, v103
	v_mul_f32_e32 v83, v83, v103
	v_mov_b32_e32 v111, v103
	v_fmac_f32_e32 v111, v83, v111
	v_add_f32_e32 v81, v81, v81
	v_mul_f32_e32 v83, 0x3f4c422a, v111
	v_mul_f32_e32 v81, 0x3fb8aa3b, v81
	v_add_f32_e32 v83, v83, v83
	v_exp_f32_e32 v81, v81
	v_mul_f32_e32 v83, 0x3fb8aa3b, v83
	v_exp_f32_e32 v83, v83
	global_store_dwordx2 v[68:69], v[112:113], off
	v_mov_b32_e32 v112, v120
	v_mov_b32_e32 v113, v70
	v_pk_mul_f32 v[112:113], v[112:113], v[104:105] op_sel_hi:[1,0]
	v_pk_mul_f32 v[106:107], v[106:107], v[104:105] op_sel_hi:[1,0]
	v_pk_mul_f32 v[112:113], v[6:7], v[112:113]
	v_mov_b32_e32 v70, v121
	v_add_f32_e32 v81, 1.0, v81
	v_pk_mul_f32 v[106:107], v[4:5], v[106:107]
	v_pk_mul_f32 v[70:71], v[70:71], v[104:105] op_sel_hi:[1,0]
	v_cvt_pk_bf16_f32 v104, v106, v107
	v_cvt_pk_bf16_f32 v105, v112, v113
	v_pk_mul_f32 v[112:113], v[116:117], 0.5 op_sel_hi:[1,0]
	v_rcp_f32_e32 v116, v81
	v_add_f32_e32 v81, 1.0, v83
	v_pk_fma_f32 v[106:107], v[118:119], 2.0, 1.0 op_sel_hi:[1,0,0] neg_lo:[1,0,0] neg_hi:[1,0,0]
	v_rcp_f32_e32 v117, v81
	v_pk_add_f32 v[106:107], v[106:107], 1.0 op_sel_hi:[1,0]
	v_pk_mul_f32 v[102:103], v[102:103], 0.5 op_sel_hi:[1,0]
	v_pk_mul_f32 v[106:107], v[112:113], v[106:107]
	v_and_b32_e32 v113, 0xffff0000, v65
	v_and_b32_e32 v112, 0xffff0000, v64
	v_lshlrev_b32_e32 v65, 16, v65
	v_lshlrev_b32_e32 v64, 16, v64
	v_pk_fma_f32 v[64:65], v[88:89], v[64:65], v[112:113]
	v_pk_mul_f32 v[70:71], v[2:3], v[70:71]
	v_pk_mul_f32 v[64:65], v[64:65], v[106:107]
	v_pk_fma_f32 v[106:107], v[116:117], 2.0, 1.0 op_sel_hi:[1,0,0] neg_lo:[1,0,0] neg_hi:[1,0,0]
	v_pk_mul_f32 v[114:115], v[0:1], v[114:115]
	v_pk_add_f32 v[106:107], v[106:107], 1.0 op_sel_hi:[1,0]
	s_nop 0
	v_pk_mul_f32 v[102:103], v[102:103], v[106:107]
	v_and_b32_e32 v107, 0xffff0000, v67
	v_and_b32_e32 v106, 0xffff0000, v66
	v_lshlrev_b32_e32 v67, 16, v67
	v_lshlrev_b32_e32 v66, 16, v66
	v_pk_fma_f32 v[66:67], v[86:87], v[66:67], v[106:107]
	v_mov_b32_e32 v106, v65
	v_pk_mul_f32 v[66:67], v[66:67], v[102:103]
	v_mov_b32_e32 v102, v64
	v_mov_b32_e32 v107, v67
	v_mov_b32_e32 v103, v66
	v_pk_mul_f32 v[106:107], v[106:107], v[106:107]
	s_nop 0
	v_pk_fma_f32 v[102:103], v[102:103], v[102:103], v[106:107]
	v_cvt_pk_bf16_f32 v106, v114, v115
	v_cvt_pk_bf16_f32 v107, v70, v71
	global_store_dwordx4 v[84:85], v[104:107], off offset:512
	v_add_f32_e32 v81, v102, v103
	s_nop 0
	v_lshlrev_b32_e32 v105, 16, v63
	v_add_f32_dpp v81, v81, v81 quad_perm:[1,0,3,2] row_mask:0xf bank_mask:0xf bound_ctrl:1
	v_and_b32_e32 v63, 0xffff0000, v63
	v_lshlrev_b32_e32 v104, 16, v61
	v_add_f32_dpp v81, v81, v81 quad_perm:[2,3,0,1] row_mask:0xf bank_mask:0xf bound_ctrl:1
	s_nop 1
	v_add_f32_dpp v81, v81, v81 row_half_mirror row_mask:0xf bank_mask:0xf bound_ctrl:1
	s_nop 1
	v_add_f32_dpp v81, v81, v81 row_mirror row_mask:0xf bank_mask:0xf bound_ctrl:1
	s_nop 0
	v_readlane_b32 s18, v81, 16
	v_readlane_b32 s19, v81, 48
	v_readlane_b32 s8, v81, 0
	v_readlane_b32 s9, v81, 32
	v_mov_b32_e32 v102, s18
	v_mov_b32_e32 v103, s19
	v_pk_add_f32 v[102:103], s[8:9], v[102:103]
	s_nop 0
	v_add_f32_e32 v81, v102, v103
	v_fmamk_f32 v81, v81, 0x3b800000, v109
	v_mul_f32_e32 v83, 0x4b800000, v81
	v_cmp_gt_f32_e32 vcc, s38, v81
	v_and_b32_e32 v103, 0xffff0000, v62
	v_and_b32_e32 v102, 0xffff0000, v60
	v_cndmask_b32_e32 v81, v81, v83, vcc
	v_rsq_f32_e32 v81, v81
	s_nop 0
	v_mul_f32_e32 v70, 0x45800000, v81
	v_cndmask_b32_e32 v70, v81, v70, vcc
	v_pk_mul_f32 v[64:65], v[64:65], v[70:71] op_sel_hi:[1,0]
	v_pk_mul_f32 v[66:67], v[66:67], v[70:71] op_sel_hi:[1,0]
	v_lshlrev_b32_e32 v71, 16, v62
	v_and_b32_e32 v62, 0xffff0000, v61
	v_lshlrev_b32_e32 v70, 16, v60
	v_pk_mul_f32 v[60:61], v[102:103], v[102:103]
	v_pk_mul_f32 v[106:107], v[62:63], v[62:63]
	v_pk_fma_f32 v[60:61], v[70:71], v[70:71], v[60:61]
	v_pk_fma_f32 v[106:107], v[104:105], v[104:105], v[106:107]
	v_pk_mul_f32 v[64:65], v[8:9], v[64:65]
	v_pk_add_f32 v[60:61], v[60:61], v[106:107]
	v_pk_mul_f32 v[66:67], v[10:11], v[66:67]
	v_add_f32_e32 v60, v60, v61
	s_nop 1
	v_add_f32_dpp v60, v60, v60 quad_perm:[1,0,3,2] row_mask:0xf bank_mask:0xf bound_ctrl:1
	s_nop 1
	v_add_f32_dpp v60, v60, v60 quad_perm:[2,3,0,1] row_mask:0xf bank_mask:0xf bound_ctrl:1
	s_nop 1
	v_add_f32_dpp v60, v60, v60 row_half_mirror row_mask:0xf bank_mask:0xf bound_ctrl:1
	s_nop 1
	v_add_f32_dpp v60, v60, v60 row_mirror row_mask:0xf bank_mask:0xf bound_ctrl:1
	s_nop 0
	v_readlane_b32 s18, v60, 16
	v_readlane_b32 s19, v60, 48
	v_readlane_b32 s8, v60, 0
	v_readlane_b32 s9, v60, 32
	v_mov_b32_e32 v60, s18
	v_mov_b32_e32 v61, s19
	v_pk_add_f32 v[60:61], s[8:9], v[60:61]
	s_nop 0
	v_add_f32_e32 v60, v60, v61
	v_fmamk_f32 v60, v60, 0x3b000000, v109
	v_mul_f32_e32 v61, 0x4b800000, v60
	v_cmp_gt_f32_e32 vcc, s38, v60
	s_nop 1
	v_cndmask_b32_e32 v60, v60, v61, vcc
	v_rsq_f32_e32 v81, v60
	v_cvt_pk_bf16_f32 v60, v64, v65
	v_cvt_pk_bf16_f32 v61, v66, v67
	global_store_dwordx2 v[68:69], v[60:61], off offset:2048
	v_mul_f32_e32 v60, 0x45800000, v81
	v_cndmask_b32_e32 v60, v81, v60, vcc
	v_mov_b32_e32 v64, v70
	v_mov_b32_e32 v65, v102
	v_mov_b32_e32 v66, v104
	v_mov_b32_e32 v67, v62
	v_mov_b32_e32 v102, v71
	v_mov_b32_e32 v62, v105
	v_pk_mul_f32 v[64:65], v[64:65], v[60:61] op_sel_hi:[1,0]
	v_pk_mul_f32 v[66:67], v[66:67], v[60:61] op_sel_hi:[1,0]
	v_pk_mul_f32 v[70:71], v[102:103], v[60:61] op_sel_hi:[1,0]
	v_pk_mul_f32 v[60:61], v[62:63], v[60:61] op_sel_hi:[1,0]
	s_waitcnt vmcnt(19)
	v_lshlrev_b32_e32 v62, 16, v100
	v_mul_f32_e32 v81, 0x3d372713, v62
	v_mul_f32_e32 v81, v81, v62
	v_mov_b32_e32 v83, v62
	v_and_b32_e32 v63, 0xffff0000, v100
	v_fmac_f32_e32 v83, v81, v83
	v_mul_f32_e32 v81, 0x3f4c422a, v83
	v_mul_f32_e32 v83, 0x3d372713, v63
	v_mul_f32_e32 v83, v83, v63
	v_mov_b32_e32 v100, v63
	v_fmac_f32_e32 v100, v83, v100
	v_add_f32_e32 v81, v81, v81
	v_mul_f32_e32 v83, 0x3f4c422a, v100
	v_mul_f32_e32 v81, 0x3fb8aa3b, v81
	v_add_f32_e32 v83, v83, v83
	v_exp_f32_e32 v81, v81
	v_mul_f32_e32 v83, 0x3fb8aa3b, v83
	v_exp_f32_e32 v83, v83
	v_pk_mul_f32 v[102:103], v[2:3], v[60:61]
	v_add_f32_e32 v60, 1.0, v81
	v_pk_mul_f32 v[66:67], v[6:7], v[66:67]
	v_rcp_f32_e32 v104, v60
	v_add_f32_e32 v60, 1.0, v83
	v_pk_mul_f32 v[64:65], v[4:5], v[64:65]
	v_rcp_f32_e32 v105, v60
	v_cvt_pk_bf16_f32 v60, v64, v65
	v_cvt_pk_bf16_f32 v61, v66, v67
	v_lshlrev_b32_e32 v66, 16, v101
	v_mul_f32_e32 v81, 0x3d372713, v66
	v_mul_f32_e32 v81, v81, v66
	v_mov_b32_e32 v83, v66
	v_and_b32_e32 v67, 0xffff0000, v101
	v_fmac_f32_e32 v83, v81, v83
	v_mul_f32_e32 v81, 0x3f4c422a, v83
	v_mul_f32_e32 v83, 0x3d372713, v67
	v_mul_f32_e32 v83, v83, v67
	v_mov_b32_e32 v100, v67
	v_fmac_f32_e32 v100, v83, v100
	v_add_f32_e32 v81, v81, v81
	v_mul_f32_e32 v83, 0x3f4c422a, v100
	v_mul_f32_e32 v81, 0x3fb8aa3b, v81
	v_add_f32_e32 v83, v83, v83
	v_exp_f32_e32 v81, v81
	v_mul_f32_e32 v83, 0x3fb8aa3b, v83
	v_exp_f32_e32 v83, v83
	v_pk_fma_f32 v[64:65], v[104:105], 2.0, 1.0 op_sel_hi:[1,0,0] neg_lo:[1,0,0] neg_hi:[1,0,0]
	v_add_f32_e32 v81, 1.0, v81
	v_rcp_f32_e32 v100, v81
	v_add_f32_e32 v81, 1.0, v83
	v_rcp_f32_e32 v101, v81
	v_pk_mul_f32 v[62:63], v[62:63], 0.5 op_sel_hi:[1,0]
	v_pk_add_f32 v[64:65], v[64:65], 1.0 op_sel_hi:[1,0]
	v_pk_mul_f32 v[70:71], v[0:1], v[70:71]
	v_pk_mul_f32 v[62:63], v[62:63], v[64:65]
	v_and_b32_e32 v65, 0xffff0000, v57
	v_and_b32_e32 v64, 0xffff0000, v56
	v_lshlrev_b32_e32 v57, 16, v57
	v_lshlrev_b32_e32 v56, 16, v56
	v_pk_fma_f32 v[56:57], v[88:89], v[56:57], v[64:65]
	v_pk_mul_f32 v[64:65], v[66:67], 0.5 op_sel_hi:[1,0]
	v_pk_mul_f32 v[56:57], v[56:57], v[62:63]
	v_pk_fma_f32 v[62:63], v[100:101], 2.0, 1.0 op_sel_hi:[1,0,0] neg_lo:[1,0,0] neg_hi:[1,0,0]
	s_nop 0
	v_pk_add_f32 v[62:63], v[62:63], 1.0 op_sel_hi:[1,0]
	s_nop 0
	v_pk_mul_f32 v[62:63], v[64:65], v[62:63]
	v_and_b32_e32 v65, 0xffff0000, v59
	v_and_b32_e32 v64, 0xffff0000, v58
	v_lshlrev_b32_e32 v59, 16, v59
	v_lshlrev_b32_e32 v58, 16, v58
	v_pk_fma_f32 v[58:59], v[86:87], v[58:59], v[64:65]
	v_mov_b32_e32 v64, v57
	v_pk_mul_f32 v[58:59], v[58:59], v[62:63]
	v_mov_b32_e32 v62, v56
	v_mov_b32_e32 v65, v59
	v_mov_b32_e32 v63, v58
	v_pk_mul_f32 v[64:65], v[64:65], v[64:65]
	s_nop 0
	v_pk_fma_f32 v[62:63], v[62:63], v[62:63], v[64:65]
	s_waitcnt vmcnt(18)
	v_lshlrev_b32_e32 v65, 16, v55
	v_add_f32_e32 v62, v62, v63
	v_and_b32_e32 v55, 0xffff0000, v55
	s_nop 0
	v_add_f32_dpp v62, v62, v62 quad_perm:[1,0,3,2] row_mask:0xf bank_mask:0xf bound_ctrl:1
	s_nop 1
	v_add_f32_dpp v62, v62, v62 quad_perm:[2,3,0,1] row_mask:0xf bank_mask:0xf bound_ctrl:1
	s_nop 1
	v_add_f32_dpp v62, v62, v62 row_half_mirror row_mask:0xf bank_mask:0xf bound_ctrl:1
	s_nop 1
	v_add_f32_dpp v62, v62, v62 row_mirror row_mask:0xf bank_mask:0xf bound_ctrl:1
	s_nop 0
	v_readlane_b32 s18, v62, 16
	v_readlane_b32 s19, v62, 48
	v_readlane_b32 s8, v62, 0
	v_readlane_b32 s9, v62, 32
	v_mov_b32_e32 v62, s18
	v_mov_b32_e32 v63, s19
	v_pk_add_f32 v[62:63], s[8:9], v[62:63]
	s_nop 0
	v_add_f32_e32 v62, v62, v63
	v_fmamk_f32 v62, v62, 0x3b800000, v109
	v_mul_f32_e32 v63, 0x4b800000, v62
	v_cmp_gt_f32_e32 vcc, s38, v62
	s_nop 1
	v_cndmask_b32_e32 v62, v62, v63, vcc
	v_rsq_f32_e32 v64, v62
	v_cvt_pk_bf16_f32 v62, v70, v71
	v_cvt_pk_bf16_f32 v63, v102, v103
	global_store_dwordx4 v[84:85], v[60:63], off offset:2560
	s_nop 1
	v_mul_f32_e32 v60, 0x45800000, v64
	v_cndmask_b32_e32 v60, v64, v60, vcc
	v_pk_mul_f32 v[58:59], v[58:59], v[60:61] op_sel_hi:[1,0]
	v_pk_mul_f32 v[56:57], v[56:57], v[60:61] op_sel_hi:[1,0]
	v_pk_mul_f32 v[58:59], v[10:11], v[58:59]
	v_pk_mul_f32 v[56:57], v[8:9], v[56:57]
	v_and_b32_e32 v63, 0xffff0000, v54
	v_cvt_pk_bf16_f32 v60, v56, v57
	v_cvt_pk_bf16_f32 v61, v58, v59
	v_lshlrev_b32_e32 v59, 16, v54
	v_and_b32_e32 v62, 0xffff0000, v52
	v_and_b32_e32 v54, 0xffff0000, v53
	v_lshlrev_b32_e32 v58, 16, v52
	v_lshlrev_b32_e32 v64, 16, v53
	v_pk_mul_f32 v[52:53], v[62:63], v[62:63]
	v_pk_mul_f32 v[66:67], v[54:55], v[54:55]
	v_pk_fma_f32 v[52:53], v[58:59], v[58:59], v[52:53]
	v_pk_fma_f32 v[66:67], v[64:65], v[64:65], v[66:67]
	v_add_co_u32_e32 v56, vcc, s28, v68
	v_pk_add_f32 v[52:53], v[52:53], v[66:67]
	s_nop 0
	v_addc_co_u32_e32 v57, vcc, 0, v69, vcc
	v_add_f32_e32 v52, v52, v53
	v_mov_b32_e32 v67, v62
	v_mov_b32_e32 v62, v59
	v_add_f32_dpp v52, v52, v52 quad_perm:[1,0,3,2] row_mask:0xf bank_mask:0xf bound_ctrl:1
	v_mov_b32_e32 v70, v64
	v_mov_b32_e32 v71, v54
	v_add_f32_dpp v52, v52, v52 quad_perm:[2,3,0,1] row_mask:0xf bank_mask:0xf bound_ctrl:1
	v_mov_b32_e32 v54, v65
	s_nop 0
	v_add_f32_dpp v52, v52, v52 row_half_mirror row_mask:0xf bank_mask:0xf bound_ctrl:1
	s_nop 1
	v_add_f32_dpp v52, v52, v52 row_mirror row_mask:0xf bank_mask:0xf bound_ctrl:1
	s_nop 0
	v_readlane_b32 s18, v52, 16
	v_readlane_b32 s19, v52, 48
	v_readlane_b32 s8, v52, 0
	v_readlane_b32 s9, v52, 32
	v_mov_b32_e32 v52, s18
	v_mov_b32_e32 v53, s19
	v_pk_add_f32 v[52:53], s[8:9], v[52:53]
	s_nop 0
	v_add_f32_e32 v52, v52, v53
	v_fmamk_f32 v52, v52, 0x3b000000, v109
	v_mul_f32_e32 v53, 0x4b800000, v52
	v_cmp_gt_f32_e32 vcc, s38, v52
	s_nop 1
	v_cndmask_b32_e32 v52, v52, v53, vcc
	v_rsq_f32_e32 v66, v52
	v_add_co_u32_e64 v52, s[8:9], s39, v68
	s_nop 1
	v_addc_co_u32_e64 v53, s[8:9], 0, v69, s[8:9]
	global_store_dwordx2 v[52:53], v[60:61], off offset:-4096
	v_mul_f32_e32 v60, 0x45800000, v66
	v_cndmask_b32_e32 v60, v66, v60, vcc
	v_mov_b32_e32 v66, v58
	v_pk_mul_f32 v[58:59], v[62:63], v[60:61] op_sel_hi:[1,0]
	s_waitcnt vmcnt(18)
	v_lshlrev_b32_e32 v62, 16, v98
	v_pk_mul_f32 v[66:67], v[66:67], v[60:61] op_sel_hi:[1,0]
	v_pk_mul_f32 v[70:71], v[70:71], v[60:61] op_sel_hi:[1,0]
	v_pk_mul_f32 v[54:55], v[54:55], v[60:61] op_sel_hi:[1,0]
	v_pk_mul_f32 v[60:61], v[0:1], v[58:59]
	v_mul_f32_e32 v58, 0x3d372713, v62
	v_mul_f32_e32 v58, v58, v62
	v_mov_b32_e32 v59, v62
	v_fmac_f32_e32 v59, v58, v59
	v_mul_f32_e32 v58, 0x3f4c422a, v59
	v_add_f32_e32 v58, v58, v58
	v_and_b32_e32 v63, 0xffff0000, v98
	v_mul_f32_e32 v58, 0x3fb8aa3b, v58
	v_exp_f32_e32 v59, v58
	v_mul_f32_e32 v58, 0x3d372713, v63
	v_mul_f32_e32 v58, v58, v63
	v_mov_b32_e32 v64, v63
	v_fmac_f32_e32 v64, v58, v64
	v_mul_f32_e32 v58, 0x3f4c422a, v64
	v_add_f32_e32 v58, v58, v58
	v_mul_f32_e32 v58, 0x3fb8aa3b, v58
	v_exp_f32_e32 v65, v58
	v_add_f32_e32 v59, 1.0, v59
	v_rcp_f32_e32 v64, v59
	v_pk_mul_f32 v[54:55], v[2:3], v[54:55]
	v_add_f32_e32 v59, 1.0, v65
	v_rcp_f32_e32 v65, v59
	v_pk_mul_f32 v[70:71], v[6:7], v[70:71]
	v_pk_mul_f32 v[66:67], v[4:5], v[66:67]
	v_pk_mul_f32 v[62:63], v[62:63], 0.5 op_sel_hi:[1,0]
	v_cvt_pk_bf16_f32 v58, v66, v67
	v_cvt_pk_bf16_f32 v59, v70, v71
	v_cvt_pk_bf16_f32 v60, v60, v61
	v_cvt_pk_bf16_f32 v61, v54, v55
	v_pk_fma_f32 v[54:55], v[64:65], 2.0, 1.0 op_sel_hi:[1,0,0] neg_lo:[1,0,0] neg_hi:[1,0,0]
	v_lshlrev_b32_e32 v64, 16, v99
	v_mul_f32_e32 v66, 0x3d372713, v64
	v_mul_f32_e32 v66, v66, v64
	v_mov_b32_e32 v67, v64
	v_and_b32_e32 v65, 0xffff0000, v99
	v_fmac_f32_e32 v67, v66, v67
	v_mul_f32_e32 v66, 0x3f4c422a, v67
	v_mul_f32_e32 v67, 0x3d372713, v65
	v_mul_f32_e32 v67, v67, v65
	v_mov_b32_e32 v70, v65
	v_fmac_f32_e32 v70, v67, v70
	v_mul_f32_e32 v67, 0x3f4c422a, v70
	v_add_f32_e32 v66, v66, v66
	v_add_f32_e32 v67, v67, v67
	v_mul_f32_e32 v66, 0x3fb8aa3b, v66
	v_mul_f32_e32 v67, 0x3fb8aa3b, v67
	v_exp_f32_e32 v66, v66
	v_exp_f32_e32 v67, v67
	v_pk_add_f32 v[54:55], v[54:55], 1.0 op_sel_hi:[1,0]
	v_add_f32_e32 v66, 1.0, v66
	v_add_f32_e32 v67, 1.0, v67
	v_rcp_f32_e32 v66, v66
	v_rcp_f32_e32 v67, v67
	v_pk_mul_f32 v[54:55], v[62:63], v[54:55]
	v_and_b32_e32 v63, 0xffff0000, v49
	v_and_b32_e32 v62, 0xffff0000, v48
	v_lshlrev_b32_e32 v49, 16, v49
	v_lshlrev_b32_e32 v48, 16, v48
	v_pk_fma_f32 v[48:49], v[88:89], v[48:49], v[62:63]
	v_pk_mul_f32 v[62:63], v[64:65], 0.5 op_sel_hi:[1,0]
	v_pk_mul_f32 v[48:49], v[48:49], v[54:55]
	v_pk_fma_f32 v[54:55], v[66:67], 2.0, 1.0 op_sel_hi:[1,0,0] neg_lo:[1,0,0] neg_hi:[1,0,0]
	s_nop 0
	v_pk_add_f32 v[54:55], v[54:55], 1.0 op_sel_hi:[1,0]
	s_nop 0
	v_pk_mul_f32 v[54:55], v[62:63], v[54:55]
	v_and_b32_e32 v63, 0xffff0000, v51
	v_and_b32_e32 v62, 0xffff0000, v50
	v_lshlrev_b32_e32 v51, 16, v51
	v_lshlrev_b32_e32 v50, 16, v50
	v_pk_fma_f32 v[50:51], v[86:87], v[50:51], v[62:63]
	v_mov_b32_e32 v62, v49
	v_pk_mul_f32 v[50:51], v[50:51], v[54:55]
	v_mov_b32_e32 v54, v48
	v_mov_b32_e32 v63, v51
	v_mov_b32_e32 v55, v50
	v_pk_mul_f32 v[62:63], v[62:63], v[62:63]
	s_nop 0
	v_pk_fma_f32 v[54:55], v[54:55], v[54:55], v[62:63]
	s_waitcnt vmcnt(17)
	v_lshlrev_b32_e32 v63, 16, v47
	v_add_f32_e32 v54, v54, v55
	v_and_b32_e32 v47, 0xffff0000, v47
	s_nop 0
	v_add_f32_dpp v54, v54, v54 quad_perm:[1,0,3,2] row_mask:0xf bank_mask:0xf bound_ctrl:1
	s_nop 1
	v_add_f32_dpp v54, v54, v54 quad_perm:[2,3,0,1] row_mask:0xf bank_mask:0xf bound_ctrl:1
	s_nop 1
	v_add_f32_dpp v54, v54, v54 row_half_mirror row_mask:0xf bank_mask:0xf bound_ctrl:1
	s_nop 1
	v_add_f32_dpp v54, v54, v54 row_mirror row_mask:0xf bank_mask:0xf bound_ctrl:1
	s_nop 0
	v_readlane_b32 s18, v54, 16
	v_readlane_b32 s19, v54, 48
	v_readlane_b32 s8, v54, 0
	v_readlane_b32 s9, v54, 32
	v_mov_b32_e32 v54, s18
	v_mov_b32_e32 v55, s19
	v_pk_add_f32 v[54:55], s[8:9], v[54:55]
	s_nop 0
	v_add_f32_e32 v54, v54, v55
	v_fmamk_f32 v54, v54, 0x3b800000, v109
	v_mul_f32_e32 v55, 0x4b800000, v54
	v_cmp_gt_f32_e32 vcc, s38, v54
	s_nop 1
	v_cndmask_b32_e32 v54, v54, v55, vcc
	v_rsq_f32_e32 v62, v54
	v_add_co_u32_e64 v54, s[8:9], s28, v84
	s_nop 1
	v_addc_co_u32_e64 v55, s[8:9], 0, v85, s[8:9]
	global_store_dwordx4 v[54:55], v[58:61], off offset:512
	s_nop 1
	v_mul_f32_e32 v58, 0x45800000, v62
	v_cndmask_b32_e32 v58, v62, v58, vcc
	v_pk_mul_f32 v[48:49], v[48:49], v[58:59] op_sel_hi:[1,0]
	v_pk_mul_f32 v[50:51], v[50:51], v[58:59] op_sel_hi:[1,0]
	v_lshlrev_b32_e32 v59, 16, v46
	v_and_b32_e32 v61, 0xffff0000, v46
	v_and_b32_e32 v60, 0xffff0000, v44
	v_and_b32_e32 v46, 0xffff0000, v45
	v_lshlrev_b32_e32 v58, 16, v44
	v_lshlrev_b32_e32 v62, 16, v45
	v_pk_mul_f32 v[44:45], v[60:61], v[60:61]
	v_pk_mul_f32 v[64:65], v[46:47], v[46:47]
	v_pk_fma_f32 v[44:45], v[58:59], v[58:59], v[44:45]
	v_pk_fma_f32 v[64:65], v[62:63], v[62:63], v[64:65]
	v_pk_mul_f32 v[48:49], v[8:9], v[48:49]
	v_pk_add_f32 v[44:45], v[44:45], v[64:65]
	v_pk_mul_f32 v[50:51], v[10:11], v[50:51]
	v_add_f32_e32 v44, v44, v45
	s_nop 1
	v_add_f32_dpp v44, v44, v44 quad_perm:[1,0,3,2] row_mask:0xf bank_mask:0xf bound_ctrl:1
	s_nop 1
	v_add_f32_dpp v44, v44, v44 quad_perm:[2,3,0,1] row_mask:0xf bank_mask:0xf bound_ctrl:1
	s_nop 1
	v_add_f32_dpp v44, v44, v44 row_half_mirror row_mask:0xf bank_mask:0xf bound_ctrl:1
	s_nop 1
	v_add_f32_dpp v44, v44, v44 row_mirror row_mask:0xf bank_mask:0xf bound_ctrl:1
	s_nop 0
	v_readlane_b32 s18, v44, 16
	v_readlane_b32 s19, v44, 48
	v_readlane_b32 s8, v44, 0
	v_readlane_b32 s9, v44, 32
	v_mov_b32_e32 v44, s18
	v_mov_b32_e32 v45, s19
	v_pk_add_f32 v[44:45], s[8:9], v[44:45]
	s_nop 0
	v_add_f32_e32 v44, v44, v45
	v_fmamk_f32 v44, v44, 0x3b000000, v109
	v_mul_f32_e32 v45, 0x4b800000, v44
	v_cmp_gt_f32_e32 vcc, s38, v44
	s_nop 1
	v_cndmask_b32_e32 v44, v44, v45, vcc
	v_rsq_f32_e32 v64, v44
	v_cvt_pk_bf16_f32 v44, v48, v49
	v_cvt_pk_bf16_f32 v45, v50, v51
	global_store_dwordx2 v[56:57], v[44:45], off offset:2048
	v_mul_f32_e32 v44, 0x45800000, v64
	v_cndmask_b32_e32 v44, v64, v44, vcc
	v_mov_b32_e32 v48, v58
	v_mov_b32_e32 v49, v60
	v_mov_b32_e32 v50, v62
	v_mov_b32_e32 v51, v46
	v_mov_b32_e32 v60, v59
	v_mov_b32_e32 v46, v63
	v_pk_mul_f32 v[48:49], v[48:49], v[44:45] op_sel_hi:[1,0]
	v_pk_mul_f32 v[50:51], v[50:51], v[44:45] op_sel_hi:[1,0]
	v_pk_mul_f32 v[56:57], v[60:61], v[44:45] op_sel_hi:[1,0]
	v_pk_mul_f32 v[44:45], v[46:47], v[44:45] op_sel_hi:[1,0]
	s_waitcnt vmcnt(17)
	v_lshlrev_b32_e32 v46, 16, v96
	v_mul_f32_e32 v58, 0x3d372713, v46
	v_mul_f32_e32 v58, v58, v46
	v_mov_b32_e32 v59, v46
	v_fmac_f32_e32 v59, v58, v59
	v_mul_f32_e32 v58, 0x3f4c422a, v59
	v_add_f32_e32 v58, v58, v58
	v_and_b32_e32 v47, 0xffff0000, v96
	v_mul_f32_e32 v58, 0x3fb8aa3b, v58
	v_exp_f32_e32 v60, v58
	v_mul_f32_e32 v58, 0x3d372713, v47
	v_mul_f32_e32 v58, v58, v47
	v_mov_b32_e32 v59, v47
	v_fmac_f32_e32 v59, v58, v59
	v_mul_f32_e32 v58, 0x3f4c422a, v59
	v_add_f32_e32 v58, v58, v58
	v_mul_f32_e32 v58, 0x3fb8aa3b, v58
	v_exp_f32_e32 v61, v58
	v_pk_mul_f32 v[58:59], v[2:3], v[44:45]
	v_add_f32_e32 v44, 1.0, v60
	v_rcp_f32_e32 v60, v44
	v_add_f32_e32 v44, 1.0, v61
	v_rcp_f32_e32 v61, v44
	v_pk_mul_f32 v[50:51], v[6:7], v[50:51]
	v_pk_mul_f32 v[48:49], v[4:5], v[48:49]
	v_pk_mul_f32 v[46:47], v[46:47], 0.5 op_sel_hi:[1,0]
	v_cvt_pk_bf16_f32 v44, v48, v49
	v_cvt_pk_bf16_f32 v45, v50, v51
	v_lshlrev_b32_e32 v50, 16, v97
	v_pk_fma_f32 v[48:49], v[60:61], 2.0, 1.0 op_sel_hi:[1,0,0] neg_lo:[1,0,0] neg_hi:[1,0,0]
	v_mul_f32_e32 v60, 0x3d372713, v50
	v_mul_f32_e32 v60, v60, v50
	v_mov_b32_e32 v61, v50
	v_and_b32_e32 v51, 0xffff0000, v97
	v_fmac_f32_e32 v61, v60, v61
	v_mul_f32_e32 v60, 0x3f4c422a, v61
	v_mul_f32_e32 v61, 0x3d372713, v51
	v_mul_f32_e32 v61, v61, v51
	v_mov_b32_e32 v62, v51
	v_fmac_f32_e32 v62, v61, v62
	v_mul_f32_e32 v61, 0x3f4c422a, v62
	v_add_f32_e32 v60, v60, v60
	v_add_f32_e32 v61, v61, v61
	v_mul_f32_e32 v60, 0x3fb8aa3b, v60
	v_mul_f32_e32 v61, 0x3fb8aa3b, v61
	v_exp_f32_e32 v60, v60
	v_exp_f32_e32 v61, v61
	v_pk_add_f32 v[48:49], v[48:49], 1.0 op_sel_hi:[1,0]
	v_pk_mul_f32 v[56:57], v[0:1], v[56:57]
	v_add_f32_e32 v60, 1.0, v60
	v_add_f32_e32 v61, 1.0, v61
	v_rcp_f32_e32 v60, v60
	v_rcp_f32_e32 v61, v61
	v_pk_mul_f32 v[46:47], v[46:47], v[48:49]
	v_and_b32_e32 v49, 0xffff0000, v41
	v_and_b32_e32 v48, 0xffff0000, v40
	v_lshlrev_b32_e32 v41, 16, v41
	v_lshlrev_b32_e32 v40, 16, v40
	v_pk_fma_f32 v[40:41], v[88:89], v[40:41], v[48:49]
	v_pk_mul_f32 v[48:49], v[50:51], 0.5 op_sel_hi:[1,0]
	v_pk_mul_f32 v[40:41], v[40:41], v[46:47]
	v_pk_fma_f32 v[46:47], v[60:61], 2.0, 1.0 op_sel_hi:[1,0,0] neg_lo:[1,0,0] neg_hi:[1,0,0]
	s_nop 0
	v_pk_add_f32 v[46:47], v[46:47], 1.0 op_sel_hi:[1,0]
	s_nop 0
	v_pk_mul_f32 v[46:47], v[48:49], v[46:47]
	v_and_b32_e32 v49, 0xffff0000, v43
	v_and_b32_e32 v48, 0xffff0000, v42
	v_lshlrev_b32_e32 v43, 16, v43
	v_lshlrev_b32_e32 v42, 16, v42
	v_pk_fma_f32 v[42:43], v[86:87], v[42:43], v[48:49]
	v_mov_b32_e32 v48, v41
	v_pk_mul_f32 v[42:43], v[42:43], v[46:47]
	v_mov_b32_e32 v46, v40
	v_mov_b32_e32 v49, v43
	v_mov_b32_e32 v47, v42
	v_pk_mul_f32 v[48:49], v[48:49], v[48:49]
	s_nop 0
	v_pk_fma_f32 v[46:47], v[46:47], v[46:47], v[48:49]
	s_waitcnt vmcnt(16)
	v_lshlrev_b32_e32 v49, 16, v39
	v_add_f32_e32 v46, v46, v47
	v_and_b32_e32 v39, 0xffff0000, v39
	s_nop 0
	v_add_f32_dpp v46, v46, v46 quad_perm:[1,0,3,2] row_mask:0xf bank_mask:0xf bound_ctrl:1
	s_nop 1
	v_add_f32_dpp v46, v46, v46 quad_perm:[2,3,0,1] row_mask:0xf bank_mask:0xf bound_ctrl:1
	s_nop 1
	v_add_f32_dpp v46, v46, v46 row_half_mirror row_mask:0xf bank_mask:0xf bound_ctrl:1
	s_nop 1
	v_add_f32_dpp v46, v46, v46 row_mirror row_mask:0xf bank_mask:0xf bound_ctrl:1
	s_nop 0
	v_readlane_b32 s18, v46, 16
	v_readlane_b32 s19, v46, 48
	v_readlane_b32 s8, v46, 0
	v_readlane_b32 s9, v46, 32
	v_mov_b32_e32 v46, s18
	v_mov_b32_e32 v47, s19
	v_pk_add_f32 v[46:47], s[8:9], v[46:47]
	s_nop 0
	v_add_f32_e32 v46, v46, v47
	v_fmamk_f32 v46, v46, 0x3b800000, v109
	v_mul_f32_e32 v47, 0x4b800000, v46
	v_cmp_gt_f32_e32 vcc, s38, v46
	s_nop 1
	v_cndmask_b32_e32 v46, v46, v47, vcc
	v_rsq_f32_e32 v48, v46
	v_cvt_pk_bf16_f32 v46, v56, v57
	v_cvt_pk_bf16_f32 v47, v58, v59
	global_store_dwordx4 v[54:55], v[44:47], off offset:2560
	s_nop 1
	v_mul_f32_e32 v44, 0x45800000, v48
	v_cndmask_b32_e32 v44, v48, v44, vcc
	v_pk_mul_f32 v[40:41], v[40:41], v[44:45] op_sel_hi:[1,0]
	v_pk_mul_f32 v[42:43], v[42:43], v[44:45] op_sel_hi:[1,0]
	v_lshlrev_b32_e32 v45, 16, v38
	v_and_b32_e32 v47, 0xffff0000, v38
	v_and_b32_e32 v46, 0xffff0000, v36
	v_and_b32_e32 v38, 0xffff0000, v37
	v_lshlrev_b32_e32 v44, 16, v36
	v_lshlrev_b32_e32 v48, 16, v37
	v_pk_mul_f32 v[36:37], v[46:47], v[46:47]
	v_pk_mul_f32 v[50:51], v[38:39], v[38:39]
	v_pk_fma_f32 v[36:37], v[44:45], v[44:45], v[36:37]
	v_pk_fma_f32 v[50:51], v[48:49], v[48:49], v[50:51]
	v_pk_mul_f32 v[40:41], v[8:9], v[40:41]
	v_pk_add_f32 v[36:37], v[36:37], v[50:51]
	v_pk_mul_f32 v[42:43], v[10:11], v[42:43]
	v_add_f32_e32 v36, v36, v37
	s_nop 1
	v_add_f32_dpp v36, v36, v36 quad_perm:[1,0,3,2] row_mask:0xf bank_mask:0xf bound_ctrl:1
	s_nop 1
	v_add_f32_dpp v36, v36, v36 quad_perm:[2,3,0,1] row_mask:0xf bank_mask:0xf bound_ctrl:1
	s_nop 1
	v_add_f32_dpp v36, v36, v36 row_half_mirror row_mask:0xf bank_mask:0xf bound_ctrl:1
	s_nop 1
	v_add_f32_dpp v36, v36, v36 row_mirror row_mask:0xf bank_mask:0xf bound_ctrl:1
	s_nop 0
	v_readlane_b32 s18, v36, 16
	v_readlane_b32 s19, v36, 48
	v_readlane_b32 s8, v36, 0
	v_readlane_b32 s9, v36, 32
	v_mov_b32_e32 v36, s18
	v_mov_b32_e32 v37, s19
	v_pk_add_f32 v[36:37], s[8:9], v[36:37]
	s_nop 0
	v_add_f32_e32 v36, v36, v37
	v_fmamk_f32 v36, v36, 0x3b000000, v109
	v_mul_f32_e32 v37, 0x4b800000, v36
	v_cmp_gt_f32_e32 vcc, s38, v36
	s_nop 1
	v_cndmask_b32_e32 v36, v36, v37, vcc
	v_rsq_f32_e32 v50, v36
	v_cvt_pk_bf16_f32 v36, v40, v41
	v_cvt_pk_bf16_f32 v37, v42, v43
	global_store_dwordx2 v[52:53], v[36:37], off
	v_mul_f32_e32 v36, 0x45800000, v50
	v_cndmask_b32_e32 v36, v50, v36, vcc
	v_mov_b32_e32 v41, v46
	v_mov_b32_e32 v46, v45
	v_mov_b32_e32 v40, v44
	v_mov_b32_e32 v42, v48
	v_mov_b32_e32 v43, v38
	v_pk_mul_f32 v[44:45], v[46:47], v[36:37] op_sel_hi:[1,0]
	v_mov_b32_e32 v38, v49
	v_pk_mul_f32 v[40:41], v[40:41], v[36:37] op_sel_hi:[1,0]
	v_pk_mul_f32 v[42:43], v[42:43], v[36:37] op_sel_hi:[1,0]
	v_pk_mul_f32 v[36:37], v[38:39], v[36:37] op_sel_hi:[1,0]
	v_pk_mul_f32 v[38:39], v[0:1], v[44:45]
	s_waitcnt vmcnt(16)
	v_lshlrev_b32_e32 v44, 16, v94
	v_pk_mul_f32 v[46:47], v[2:3], v[36:37]
	v_mul_f32_e32 v36, 0x3d372713, v44
	v_mul_f32_e32 v36, v36, v44
	v_mov_b32_e32 v37, v44
	v_fmac_f32_e32 v37, v36, v37
	v_mul_f32_e32 v36, 0x3f4c422a, v37
	v_add_f32_e32 v36, v36, v36
	v_and_b32_e32 v45, 0xffff0000, v94
	v_mul_f32_e32 v36, 0x3fb8aa3b, v36
	v_exp_f32_e32 v37, v36
	v_mul_f32_e32 v36, 0x3d372713, v45
	v_mul_f32_e32 v36, v36, v45
	v_mov_b32_e32 v48, v45
	v_fmac_f32_e32 v48, v36, v48
	v_mul_f32_e32 v36, 0x3f4c422a, v48
	v_add_f32_e32 v36, v36, v36
	v_mul_f32_e32 v36, 0x3fb8aa3b, v36
	v_exp_f32_e32 v48, v36
	v_pk_mul_f32 v[40:41], v[4:5], v[40:41]
	v_add_f32_e32 v37, 1.0, v37
	v_pk_mul_f32 v[42:43], v[6:7], v[42:43]
	v_cvt_pk_bf16_f32 v36, v40, v41
	v_rcp_f32_e32 v40, v37
	v_add_f32_e32 v37, 1.0, v48
	v_rcp_f32_e32 v41, v37
	v_cvt_pk_bf16_f32 v37, v42, v43
	v_pk_mul_f32 v[42:43], v[44:45], 0.5 op_sel_hi:[1,0]
	v_lshlrev_b32_e32 v44, 16, v95
	v_cvt_pk_bf16_f32 v38, v38, v39
	v_cvt_pk_bf16_f32 v39, v46, v47
	v_mul_f32_e32 v46, 0x3d372713, v44
	v_mul_f32_e32 v46, v46, v44
	v_mov_b32_e32 v47, v44
	v_and_b32_e32 v45, 0xffff0000, v95
	v_fmac_f32_e32 v47, v46, v47
	v_mul_f32_e32 v46, 0x3f4c422a, v47
	v_mul_f32_e32 v47, 0x3d372713, v45
	v_mul_f32_e32 v47, v47, v45
	v_mov_b32_e32 v48, v45
	v_fmac_f32_e32 v48, v47, v48
	v_mul_f32_e32 v47, 0x3f4c422a, v48
	v_add_f32_e32 v46, v46, v46
	v_add_f32_e32 v47, v47, v47
	v_mul_f32_e32 v46, 0x3fb8aa3b, v46
	v_mul_f32_e32 v47, 0x3fb8aa3b, v47
	v_exp_f32_e32 v46, v46
	v_exp_f32_e32 v47, v47
	v_pk_fma_f32 v[40:41], v[40:41], 2.0, 1.0 op_sel_hi:[1,0,0] neg_lo:[1,0,0] neg_hi:[1,0,0]
	v_add_f32_e32 v46, 1.0, v46
	v_add_f32_e32 v47, 1.0, v47
	v_rcp_f32_e32 v46, v46
	v_rcp_f32_e32 v47, v47
	v_pk_add_f32 v[40:41], v[40:41], 1.0 op_sel_hi:[1,0]
	s_nop 0
	v_pk_mul_f32 v[40:41], v[42:43], v[40:41]
	v_and_b32_e32 v43, 0xffff0000, v33
	v_and_b32_e32 v42, 0xffff0000, v32
	v_lshlrev_b32_e32 v33, 16, v33
	v_lshlrev_b32_e32 v32, 16, v32
	v_pk_fma_f32 v[32:33], v[88:89], v[32:33], v[42:43]
	v_pk_mul_f32 v[42:43], v[44:45], 0.5 op_sel_hi:[1,0]
	v_pk_mul_f32 v[32:33], v[32:33], v[40:41]
	v_pk_fma_f32 v[40:41], v[46:47], 2.0, 1.0 op_sel_hi:[1,0,0] neg_lo:[1,0,0] neg_hi:[1,0,0]
	s_nop 0
	v_pk_add_f32 v[40:41], v[40:41], 1.0 op_sel_hi:[1,0]
	s_nop 0
	v_pk_mul_f32 v[40:41], v[42:43], v[40:41]
	v_and_b32_e32 v43, 0xffff0000, v35
	v_and_b32_e32 v42, 0xffff0000, v34
	v_lshlrev_b32_e32 v35, 16, v35
	v_lshlrev_b32_e32 v34, 16, v34
	v_pk_fma_f32 v[34:35], v[86:87], v[34:35], v[42:43]
	v_mov_b32_e32 v42, v33
	v_pk_mul_f32 v[34:35], v[34:35], v[40:41]
	v_mov_b32_e32 v40, v32
	v_mov_b32_e32 v43, v35
	v_mov_b32_e32 v41, v34
	v_pk_mul_f32 v[42:43], v[42:43], v[42:43]
	s_nop 0
	v_pk_fma_f32 v[40:41], v[40:41], v[40:41], v[42:43]
	s_waitcnt vmcnt(15)
	v_lshlrev_b32_e32 v43, 16, v31
	v_add_f32_e32 v40, v40, v41
	v_and_b32_e32 v31, 0xffff0000, v31
	s_nop 0
	v_add_f32_dpp v40, v40, v40 quad_perm:[1,0,3,2] row_mask:0xf bank_mask:0xf bound_ctrl:1
	s_nop 1
	v_add_f32_dpp v40, v40, v40 quad_perm:[2,3,0,1] row_mask:0xf bank_mask:0xf bound_ctrl:1
	s_nop 1
	v_add_f32_dpp v40, v40, v40 row_half_mirror row_mask:0xf bank_mask:0xf bound_ctrl:1
	s_nop 1
	v_add_f32_dpp v40, v40, v40 row_mirror row_mask:0xf bank_mask:0xf bound_ctrl:1
	s_nop 0
	v_readlane_b32 s18, v40, 16
	v_readlane_b32 s19, v40, 48
	v_readlane_b32 s8, v40, 0
	v_readlane_b32 s9, v40, 32
	v_mov_b32_e32 v40, s18
	v_mov_b32_e32 v41, s19
	v_pk_add_f32 v[40:41], s[8:9], v[40:41]
	s_nop 0
	v_add_f32_e32 v40, v40, v41
	v_fmamk_f32 v40, v40, 0x3b800000, v109
	v_mul_f32_e32 v41, 0x4b800000, v40
	v_cmp_gt_f32_e32 vcc, s38, v40
	s_nop 1
	v_cndmask_b32_e32 v40, v40, v41, vcc
	v_rsq_f32_e32 v42, v40
	v_add_co_u32_e64 v40, s[8:9], s39, v84
	s_nop 1
	v_addc_co_u32_e64 v41, s[8:9], 0, v85, s[8:9]
	global_store_dwordx4 v[40:41], v[36:39], off offset:512
	s_nop 1
	v_mul_f32_e32 v36, 0x45800000, v42
	v_cndmask_b32_e32 v36, v42, v36, vcc
	v_pk_mul_f32 v[32:33], v[32:33], v[36:37] op_sel_hi:[1,0]
	v_pk_mul_f32 v[34:35], v[34:35], v[36:37] op_sel_hi:[1,0]
	v_lshlrev_b32_e32 v37, 16, v30
	v_and_b32_e32 v39, 0xffff0000, v30
	v_and_b32_e32 v38, 0xffff0000, v28
	v_and_b32_e32 v30, 0xffff0000, v29
	v_lshlrev_b32_e32 v36, 16, v28
	v_lshlrev_b32_e32 v42, 16, v29
	v_pk_mul_f32 v[28:29], v[38:39], v[38:39]
	v_pk_mul_f32 v[44:45], v[30:31], v[30:31]
	v_pk_fma_f32 v[28:29], v[36:37], v[36:37], v[28:29]
	v_pk_fma_f32 v[44:45], v[42:43], v[42:43], v[44:45]
	v_pk_mul_f32 v[32:33], v[8:9], v[32:33]
	v_pk_add_f32 v[28:29], v[28:29], v[44:45]
	v_pk_mul_f32 v[34:35], v[10:11], v[34:35]
	v_add_f32_e32 v28, v28, v29
	s_nop 1
	v_add_f32_dpp v28, v28, v28 quad_perm:[1,0,3,2] row_mask:0xf bank_mask:0xf bound_ctrl:1
	s_nop 1
	v_add_f32_dpp v28, v28, v28 quad_perm:[2,3,0,1] row_mask:0xf bank_mask:0xf bound_ctrl:1
	s_nop 1
	v_add_f32_dpp v28, v28, v28 row_half_mirror row_mask:0xf bank_mask:0xf bound_ctrl:1
	s_nop 1
	v_add_f32_dpp v28, v28, v28 row_mirror row_mask:0xf bank_mask:0xf bound_ctrl:1
	s_nop 0
	v_readlane_b32 s18, v28, 16
	v_readlane_b32 s19, v28, 48
	v_readlane_b32 s8, v28, 0
	v_readlane_b32 s9, v28, 32
	v_mov_b32_e32 v28, s18
	v_mov_b32_e32 v29, s19
	v_pk_add_f32 v[28:29], s[8:9], v[28:29]
	s_nop 0
	v_add_f32_e32 v28, v28, v29
	v_fmamk_f32 v28, v28, 0x3b000000, v109
	v_mul_f32_e32 v29, 0x4b800000, v28
	v_cmp_gt_f32_e32 vcc, s38, v28
	s_nop 1
	v_cndmask_b32_e32 v28, v28, v29, vcc
	v_rsq_f32_e32 v44, v28
	v_cvt_pk_bf16_f32 v28, v32, v33
	v_cvt_pk_bf16_f32 v29, v34, v35
	global_store_dwordx2 v[52:53], v[28:29], off offset:2048
	v_mul_f32_e32 v28, 0x45800000, v44
	v_cndmask_b32_e32 v28, v44, v28, vcc
	v_mov_b32_e32 v32, v36
	v_mov_b32_e32 v33, v38
	v_mov_b32_e32 v34, v42
	v_mov_b32_e32 v35, v30
	v_mov_b32_e32 v38, v37
	v_mov_b32_e32 v30, v43
	v_pk_mul_f32 v[32:33], v[32:33], v[28:29] op_sel_hi:[1,0]
	v_pk_mul_f32 v[34:35], v[34:35], v[28:29] op_sel_hi:[1,0]
	v_pk_mul_f32 v[36:37], v[38:39], v[28:29] op_sel_hi:[1,0]
	v_pk_mul_f32 v[28:29], v[30:31], v[28:29] op_sel_hi:[1,0]
	s_waitcnt vmcnt(15)
	v_lshlrev_b32_e32 v30, 16, v92
	v_mul_f32_e32 v38, 0x3d372713, v30
	v_mul_f32_e32 v38, v38, v30
	v_mov_b32_e32 v39, v30
	v_fmac_f32_e32 v39, v38, v39
	v_mul_f32_e32 v38, 0x3f4c422a, v39
	v_add_f32_e32 v38, v38, v38
	v_and_b32_e32 v31, 0xffff0000, v92
	v_mul_f32_e32 v38, 0x3fb8aa3b, v38
	v_exp_f32_e32 v42, v38
	v_mul_f32_e32 v38, 0x3d372713, v31
	v_mul_f32_e32 v38, v38, v31
	v_mov_b32_e32 v39, v31
	v_fmac_f32_e32 v39, v38, v39
	v_mul_f32_e32 v38, 0x3f4c422a, v39
	v_add_f32_e32 v38, v38, v38
	v_mul_f32_e32 v38, 0x3fb8aa3b, v38
	v_exp_f32_e32 v43, v38
	v_pk_mul_f32 v[38:39], v[2:3], v[28:29]
	v_add_f32_e32 v28, 1.0, v42
	v_rcp_f32_e32 v42, v28
	v_add_f32_e32 v28, 1.0, v43
	v_rcp_f32_e32 v43, v28
	v_pk_mul_f32 v[34:35], v[6:7], v[34:35]
	v_pk_mul_f32 v[32:33], v[4:5], v[32:33]
	v_pk_mul_f32 v[30:31], v[30:31], 0.5 op_sel_hi:[1,0]
	v_cvt_pk_bf16_f32 v28, v32, v33
	v_cvt_pk_bf16_f32 v29, v34, v35
	v_lshlrev_b32_e32 v34, 16, v93
	v_pk_fma_f32 v[32:33], v[42:43], 2.0, 1.0 op_sel_hi:[1,0,0] neg_lo:[1,0,0] neg_hi:[1,0,0]
	v_mul_f32_e32 v42, 0x3d372713, v34
	v_mul_f32_e32 v42, v42, v34
	v_mov_b32_e32 v43, v34
	v_and_b32_e32 v35, 0xffff0000, v93
	v_fmac_f32_e32 v43, v42, v43
	v_mul_f32_e32 v42, 0x3f4c422a, v43
	v_mul_f32_e32 v43, 0x3d372713, v35
	v_mul_f32_e32 v43, v43, v35
	v_mov_b32_e32 v44, v35
	v_fmac_f32_e32 v44, v43, v44
	v_mul_f32_e32 v43, 0x3f4c422a, v44
	v_add_f32_e32 v42, v42, v42
	v_add_f32_e32 v43, v43, v43
	v_mul_f32_e32 v42, 0x3fb8aa3b, v42
	v_mul_f32_e32 v43, 0x3fb8aa3b, v43
	v_exp_f32_e32 v42, v42
	v_exp_f32_e32 v43, v43
	v_pk_add_f32 v[32:33], v[32:33], 1.0 op_sel_hi:[1,0]
	v_pk_mul_f32 v[36:37], v[0:1], v[36:37]
	v_add_f32_e32 v42, 1.0, v42
	v_add_f32_e32 v43, 1.0, v43
	v_rcp_f32_e32 v42, v42
	v_rcp_f32_e32 v43, v43
	v_pk_mul_f32 v[30:31], v[30:31], v[32:33]
	v_and_b32_e32 v33, 0xffff0000, v25
	v_and_b32_e32 v32, 0xffff0000, v24
	v_lshlrev_b32_e32 v25, 16, v25
	v_lshlrev_b32_e32 v24, 16, v24
	v_pk_fma_f32 v[24:25], v[88:89], v[24:25], v[32:33]
	v_pk_mul_f32 v[32:33], v[34:35], 0.5 op_sel_hi:[1,0]
	v_pk_mul_f32 v[24:25], v[24:25], v[30:31]
	v_pk_fma_f32 v[30:31], v[42:43], 2.0, 1.0 op_sel_hi:[1,0,0] neg_lo:[1,0,0] neg_hi:[1,0,0]
	s_nop 0
	v_pk_add_f32 v[30:31], v[30:31], 1.0 op_sel_hi:[1,0]
	s_nop 0
	v_pk_mul_f32 v[30:31], v[32:33], v[30:31]
	v_and_b32_e32 v33, 0xffff0000, v27
	v_and_b32_e32 v32, 0xffff0000, v26
	v_lshlrev_b32_e32 v27, 16, v27
	v_lshlrev_b32_e32 v26, 16, v26
	v_pk_fma_f32 v[26:27], v[86:87], v[26:27], v[32:33]
	v_mov_b32_e32 v32, v25
	v_pk_mul_f32 v[26:27], v[26:27], v[30:31]
	v_mov_b32_e32 v30, v24
	v_mov_b32_e32 v33, v27
	v_mov_b32_e32 v31, v26
	v_pk_mul_f32 v[32:33], v[32:33], v[32:33]
	s_nop 0
	v_pk_fma_f32 v[30:31], v[30:31], v[30:31], v[32:33]
	s_nop 0
	v_add_f32_e32 v30, v30, v31
	s_nop 1
	v_add_f32_dpp v30, v30, v30 quad_perm:[1,0,3,2] row_mask:0xf bank_mask:0xf bound_ctrl:1
	s_nop 1
	v_add_f32_dpp v30, v30, v30 quad_perm:[2,3,0,1] row_mask:0xf bank_mask:0xf bound_ctrl:1
	s_nop 1
	v_add_f32_dpp v30, v30, v30 row_half_mirror row_mask:0xf bank_mask:0xf bound_ctrl:1
	s_nop 1
	v_add_f32_dpp v30, v30, v30 row_mirror row_mask:0xf bank_mask:0xf bound_ctrl:1
	s_nop 0
	v_readlane_b32 s18, v30, 16
	v_readlane_b32 s19, v30, 48
	v_readlane_b32 s8, v30, 0
	v_readlane_b32 s9, v30, 32
	v_mov_b32_e32 v30, s18
	v_mov_b32_e32 v31, s19
	v_pk_add_f32 v[30:31], s[8:9], v[30:31]
	s_nop 0
	v_add_f32_e32 v30, v30, v31
	v_fmamk_f32 v30, v30, 0x3b800000, v109
	v_mul_f32_e32 v31, 0x4b800000, v30
	v_cmp_gt_f32_e32 vcc, s38, v30
	s_nop 1
	v_cndmask_b32_e32 v30, v30, v31, vcc
	v_rsq_f32_e32 v32, v30
	v_cvt_pk_bf16_f32 v30, v36, v37
	v_cvt_pk_bf16_f32 v31, v38, v39
	global_store_dwordx4 v[40:41], v[28:31], off offset:2560
	s_nop 1
	v_mul_f32_e32 v28, 0x45800000, v32
	v_cndmask_b32_e32 v28, v32, v28, vcc
	v_pk_mul_f32 v[24:25], v[24:25], v[28:29] op_sel_hi:[1,0]
	v_pk_mul_f32 v[26:27], v[26:27], v[28:29] op_sel_hi:[1,0]
	v_pk_mul_f32 v[24:25], v[8:9], v[24:25]
	v_pk_mul_f32 v[26:27], v[10:11], v[26:27]
	v_cvt_pk_bf16_f32 v24, v24, v25
	s_waitcnt vmcnt(15)
	v_and_b32_e32 v29, 0xffff0000, v22
	v_cvt_pk_bf16_f32 v25, v26, v27
	v_lshlrev_b32_e32 v27, 16, v22
	v_and_b32_e32 v28, 0xffff0000, v20
	v_lshlrev_b32_e32 v31, 16, v23
	v_and_b32_e32 v23, 0xffff0000, v23
	v_and_b32_e32 v22, 0xffff0000, v21
	v_lshlrev_b32_e32 v26, 16, v20
	v_lshlrev_b32_e32 v30, 16, v21
	v_pk_mul_f32 v[20:21], v[28:29], v[28:29]
	v_pk_mul_f32 v[32:33], v[22:23], v[22:23]
	v_pk_fma_f32 v[20:21], v[26:27], v[26:27], v[20:21]
	v_pk_fma_f32 v[32:33], v[30:31], v[30:31], v[32:33]
	v_mov_b32_e32 v34, v30
	v_pk_add_f32 v[20:21], v[20:21], v[32:33]
	v_mov_b32_e32 v35, v22
	v_add_f32_e32 v20, v20, v21
	v_mov_b32_e32 v22, v31
	s_nop 0
	v_add_f32_dpp v20, v20, v20 quad_perm:[1,0,3,2] row_mask:0xf bank_mask:0xf bound_ctrl:1
	s_nop 1
	v_add_f32_dpp v20, v20, v20 quad_perm:[2,3,0,1] row_mask:0xf bank_mask:0xf bound_ctrl:1
	s_nop 1
	v_add_f32_dpp v20, v20, v20 row_half_mirror row_mask:0xf bank_mask:0xf bound_ctrl:1
	s_nop 1
	v_add_f32_dpp v20, v20, v20 row_mirror row_mask:0xf bank_mask:0xf bound_ctrl:1
	s_nop 0
	v_readlane_b32 s18, v20, 16
	v_readlane_b32 s19, v20, 48
	v_readlane_b32 s8, v20, 0
	v_readlane_b32 s9, v20, 32
	v_mov_b32_e32 v20, s18
	v_mov_b32_e32 v21, s19
	v_pk_add_f32 v[20:21], s[8:9], v[20:21]
	v_add_co_u32_e64 v32, s[8:9], s40, v68
	v_add_f32_e32 v20, v20, v21
	v_fmamk_f32 v20, v20, 0x3b000000, v109
	v_mul_f32_e32 v21, 0x4b800000, v20
	v_cmp_gt_f32_e32 vcc, s38, v20
	v_addc_co_u32_e64 v33, s[8:9], 0, v69, s[8:9]
	s_nop 0
	v_cndmask_b32_e32 v20, v20, v21, vcc
	v_rsq_f32_e32 v20, v20
	global_store_dwordx2 v[32:33], v[24:25], off
	v_mov_b32_e32 v25, v28
	v_mov_b32_e32 v28, v27
	v_mul_f32_e32 v21, 0x45800000, v20
	v_cndmask_b32_e32 v20, v20, v21, vcc
	v_mov_b32_e32 v24, v26
	v_pk_mul_f32 v[26:27], v[28:29], v[20:21] op_sel_hi:[1,0]
	v_pk_mul_f32 v[24:25], v[24:25], v[20:21] op_sel_hi:[1,0]
	v_pk_mul_f32 v[34:35], v[34:35], v[20:21] op_sel_hi:[1,0]
	v_pk_mul_f32 v[20:21], v[22:23], v[20:21] op_sel_hi:[1,0]
	v_pk_mul_f32 v[22:23], v[0:1], v[26:27]
	s_waitcnt vmcnt(14)
	v_lshlrev_b32_e32 v26, 16, v90
	v_pk_mul_f32 v[28:29], v[2:3], v[20:21]
	v_mul_f32_e32 v20, 0x3d372713, v26
	v_mul_f32_e32 v20, v20, v26
	v_mov_b32_e32 v21, v26
	v_fmac_f32_e32 v21, v20, v21
	v_mul_f32_e32 v20, 0x3f4c422a, v21
	v_add_f32_e32 v20, v20, v20
	v_and_b32_e32 v27, 0xffff0000, v90
	v_mul_f32_e32 v20, 0x3fb8aa3b, v20
	v_exp_f32_e32 v21, v20
	v_mul_f32_e32 v20, 0x3d372713, v27
	v_mul_f32_e32 v20, v20, v27
	v_mov_b32_e32 v30, v27
	v_fmac_f32_e32 v30, v20, v30
	v_mul_f32_e32 v20, 0x3f4c422a, v30
	v_add_f32_e32 v20, v20, v20
	v_mul_f32_e32 v20, 0x3fb8aa3b, v20
	v_exp_f32_e32 v30, v20
	v_pk_mul_f32 v[24:25], v[4:5], v[24:25]
	v_add_f32_e32 v21, 1.0, v21
	v_cvt_pk_bf16_f32 v20, v24, v25
	v_rcp_f32_e32 v24, v21
	v_add_f32_e32 v21, 1.0, v30
	v_pk_mul_f32 v[34:35], v[6:7], v[34:35]
	v_rcp_f32_e32 v25, v21
	v_cvt_pk_bf16_f32 v21, v34, v35
	v_cvt_pk_bf16_f32 v22, v22, v23
	v_cvt_pk_bf16_f32 v23, v28, v29
	v_lshlrev_b32_e32 v28, 16, v91
	v_mul_f32_e32 v30, 0x3d372713, v28
	v_mul_f32_e32 v30, v30, v28
	v_mov_b32_e32 v31, v28
	v_and_b32_e32 v29, 0xffff0000, v91
	v_fmac_f32_e32 v31, v30, v31
	v_mul_f32_e32 v30, 0x3f4c422a, v31
	v_mul_f32_e32 v31, 0x3d372713, v29
	v_mul_f32_e32 v31, v31, v29
	v_mov_b32_e32 v34, v29
	v_fmac_f32_e32 v34, v31, v34
	v_mul_f32_e32 v31, 0x3f4c422a, v34
	v_add_f32_e32 v30, v30, v30
	v_add_f32_e32 v31, v31, v31
	v_mul_f32_e32 v30, 0x3fb8aa3b, v30
	v_mul_f32_e32 v31, 0x3fb8aa3b, v31
	v_exp_f32_e32 v30, v30
	v_exp_f32_e32 v31, v31
	v_pk_fma_f32 v[24:25], v[24:25], 2.0, 1.0 op_sel_hi:[1,0,0] neg_lo:[1,0,0] neg_hi:[1,0,0]
	v_pk_mul_f32 v[26:27], v[26:27], 0.5 op_sel_hi:[1,0]
	v_add_f32_e32 v30, 1.0, v30
	v_add_f32_e32 v31, 1.0, v31
	v_rcp_f32_e32 v30, v30
	v_rcp_f32_e32 v31, v31
	v_pk_add_f32 v[24:25], v[24:25], 1.0 op_sel_hi:[1,0]
	s_nop 0
	v_pk_mul_f32 v[24:25], v[26:27], v[24:25]
	v_and_b32_e32 v27, 0xffff0000, v13
	v_and_b32_e32 v26, 0xffff0000, v12
	v_lshlrev_b32_e32 v13, 16, v13
	v_lshlrev_b32_e32 v12, 16, v12
	v_pk_fma_f32 v[12:13], v[88:89], v[12:13], v[26:27]
	v_pk_mul_f32 v[26:27], v[28:29], 0.5 op_sel_hi:[1,0]
	v_pk_mul_f32 v[12:13], v[12:13], v[24:25]
	v_pk_fma_f32 v[24:25], v[30:31], 2.0, 1.0 op_sel_hi:[1,0,0] neg_lo:[1,0,0] neg_hi:[1,0,0]
	s_nop 0
	v_pk_add_f32 v[24:25], v[24:25], 1.0 op_sel_hi:[1,0]
	s_nop 0
	v_pk_mul_f32 v[24:25], v[26:27], v[24:25]
	v_and_b32_e32 v27, 0xffff0000, v15
	v_and_b32_e32 v26, 0xffff0000, v14
	v_lshlrev_b32_e32 v15, 16, v15
	v_lshlrev_b32_e32 v14, 16, v14
	v_pk_fma_f32 v[14:15], v[86:87], v[14:15], v[26:27]
	v_mov_b32_e32 v26, v13
	v_pk_mul_f32 v[14:15], v[14:15], v[24:25]
	v_mov_b32_e32 v24, v12
	v_mov_b32_e32 v27, v15
	v_mov_b32_e32 v25, v14
	v_pk_mul_f32 v[26:27], v[26:27], v[26:27]
	s_nop 0
	v_pk_fma_f32 v[24:25], v[24:25], v[24:25], v[26:27]
	s_nop 0
	v_add_f32_e32 v24, v24, v25
	s_nop 1
	v_add_f32_dpp v24, v24, v24 quad_perm:[1,0,3,2] row_mask:0xf bank_mask:0xf bound_ctrl:1
	s_nop 1
	v_add_f32_dpp v24, v24, v24 quad_perm:[2,3,0,1] row_mask:0xf bank_mask:0xf bound_ctrl:1
	s_nop 1
	v_add_f32_dpp v24, v24, v24 row_half_mirror row_mask:0xf bank_mask:0xf bound_ctrl:1
	s_nop 1
	v_add_f32_dpp v24, v24, v24 row_mirror row_mask:0xf bank_mask:0xf bound_ctrl:1
	s_nop 0
	v_readlane_b32 s18, v24, 16
	v_readlane_b32 s19, v24, 48
	v_readlane_b32 s8, v24, 0
	v_readlane_b32 s9, v24, 32
	v_mov_b32_e32 v24, s18
	v_mov_b32_e32 v25, s19
	v_pk_add_f32 v[24:25], s[8:9], v[24:25]
	s_nop 0
	v_add_f32_e32 v24, v24, v25
	v_fmamk_f32 v24, v24, 0x3b800000, v109
	v_mul_f32_e32 v25, 0x4b800000, v24
	v_cmp_gt_f32_e32 vcc, s38, v24
	s_nop 1
	v_cndmask_b32_e32 v24, v24, v25, vcc
	v_rsq_f32_e32 v26, v24
	v_add_co_u32_e64 v24, s[8:9], s40, v84
	s_nop 1
	v_addc_co_u32_e64 v25, s[8:9], 0, v85, s[8:9]
	global_store_dwordx4 v[24:25], v[20:23], off offset:512
	s_nop 1
	v_mul_f32_e32 v20, 0x45800000, v26
	v_cndmask_b32_e32 v20, v26, v20, vcc
	v_pk_mul_f32 v[12:13], v[12:13], v[20:21] op_sel_hi:[1,0]
	v_pk_mul_f32 v[14:15], v[14:15], v[20:21] op_sel_hi:[1,0]
	v_pk_mul_f32 v[8:9], v[8:9], v[12:13]
	v_pk_mul_f32 v[10:11], v[10:11], v[14:15]
	s_waitcnt vmcnt(14)
	v_lshlrev_b32_e32 v13, 16, v18
	v_and_b32_e32 v15, 0xffff0000, v18
	v_and_b32_e32 v14, 0xffff0000, v16
	v_lshlrev_b32_e32 v21, 16, v19
	v_and_b32_e32 v19, 0xffff0000, v19
	v_and_b32_e32 v18, 0xffff0000, v17
	v_lshlrev_b32_e32 v12, 16, v16
	v_lshlrev_b32_e32 v20, 16, v17
	v_pk_mul_f32 v[16:17], v[14:15], v[14:15]
	v_pk_mul_f32 v[22:23], v[18:19], v[18:19]
	v_pk_fma_f32 v[16:17], v[12:13], v[12:13], v[16:17]
	v_pk_fma_f32 v[22:23], v[20:21], v[20:21], v[22:23]
	v_cvt_pk_bf16_f32 v8, v8, v9
	v_cvt_pk_bf16_f32 v9, v10, v11
	global_store_dwordx2 v[32:33], v[8:9], off offset:2048
	v_pk_add_f32 v[16:17], v[16:17], v[22:23]
	v_mov_b32_e32 v10, v12
	v_add_f32_e32 v16, v16, v17
	v_mov_b32_e32 v11, v14
	v_mov_b32_e32 v14, v13
	v_add_f32_dpp v16, v16, v16 quad_perm:[1,0,3,2] row_mask:0xf bank_mask:0xf bound_ctrl:1
	s_nop 1
	v_add_f32_dpp v16, v16, v16 quad_perm:[2,3,0,1] row_mask:0xf bank_mask:0xf bound_ctrl:1
	s_nop 1
	v_add_f32_dpp v16, v16, v16 row_half_mirror row_mask:0xf bank_mask:0xf bound_ctrl:1
	s_nop 1
	v_add_f32_dpp v16, v16, v16 row_mirror row_mask:0xf bank_mask:0xf bound_ctrl:1
	s_nop 0
	v_readlane_b32 s18, v16, 16
	v_readlane_b32 s19, v16, 48
	v_readlane_b32 s8, v16, 0
	v_readlane_b32 s9, v16, 32
	v_mov_b32_e32 v16, s18
	v_mov_b32_e32 v17, s19
	v_pk_add_f32 v[16:17], s[8:9], v[16:17]
	s_nop 0
	v_add_f32_e32 v16, v16, v17
	v_fmamk_f32 v16, v16, 0x3b000000, v109
	v_mul_f32_e32 v17, 0x4b800000, v16
	v_cmp_gt_f32_e32 vcc, s38, v16
	s_nop 1
	v_cndmask_b32_e32 v16, v16, v17, vcc
	v_rsq_f32_e32 v16, v16
	v_mov_b32_e32 v17, v18
	v_mov_b32_e32 v18, v21
	v_mul_f32_e32 v8, 0x45800000, v16
	v_cndmask_b32_e32 v8, v16, v8, vcc
	v_pk_mul_f32 v[10:11], v[10:11], v[8:9] op_sel_hi:[1,0]
	v_mov_b32_e32 v16, v20
	v_pk_mul_f32 v[16:17], v[16:17], v[8:9] op_sel_hi:[1,0]
	v_pk_mul_f32 v[4:5], v[4:5], v[10:11]
	v_pk_mul_f32 v[10:11], v[14:15], v[8:9] op_sel_hi:[1,0]
	v_pk_mul_f32 v[8:9], v[18:19], v[8:9] op_sel_hi:[1,0]
	v_pk_mul_f32 v[6:7], v[6:7], v[16:17]
	v_pk_mul_f32 v[8:9], v[2:3], v[8:9]
	v_pk_mul_f32 v[2:3], v[0:1], v[10:11]
	v_cvt_pk_bf16_f32 v0, v4, v5
	v_cvt_pk_bf16_f32 v1, v6, v7
	s_nop 0
	v_cvt_pk_bf16_f32 v2, v2, v3
	v_cvt_pk_bf16_f32 v3, v8, v9
	global_store_dwordx4 v[24:25], v[0:3], off offset:2560
	s_barrier
	s_cbranch_scc1 .LBB0_1182

.Llb_fast_12:
	v_add_co_u32_e32 v0, vcc, 0x2000, v2
	v_mov_b32_e32 v2, 1
	s_nop 0
	v_addc_co_u32_e32 v1, vcc, 0, v3, vcc
	s_waitcnt vmcnt(0)
	buffer_inv sc1
	global_atomic_add v[0:1], v2, off offset:1024
	s_waitcnt vmcnt(0)
.LBB0_1226:
	s_or_b64 exec, exec, s[48:49]
	s_mov_b64 s[8:9], s[0:1]
	s_waitcnt lgkmcnt(0)
	s_barrier
	v_mov_b32_e32 v12, v176
	s_waitcnt vmcnt(0)
	v_mov_b64_e32 v[0:1], s[8:9]
	flat_load_dwordx2 v[0:1], v[0:1] offset:216
	s_and_b64 vcc, exec, s[46:47]
	v_readfirstlane_b32 s10, v12
	s_cbranch_vccz .LBB0_1232
	s_lshr_b32 s3, s33, 29
	s_add_i32 s3, s2, s3
	s_and_b32 s8, s3, -8
	s_sub_i32 s11, s2, s8
	s_cmp_gt_i32 s11, -1
	s_cbranch_scc0 .LBB0_1229
	s_lshl_b32 s12, s11, 6
	s_cbranch_execz .LBB0_1230
	s_branch .LBB0_1231

.LBB0_1232:
	s_and_b64 vcc, exec, s[4:5]
	s_cbranch_vccnz .LBB0_1301
	s_mov_b64 s[8:9], 0x9000000
	s_waitcnt vmcnt(0) lgkmcnt(0)
	v_lshl_add_u64 v[178:179], v[0:1], 0, s[8:9]
	s_mov_b64 s[8:9], 0x3b80000
	v_lshl_add_u64 v[180:181], v[0:1], 0, s[8:9]
	v_ashrrev_i32_e32 v1, 31, v12
	v_lshrrev_b32_e32 v1, 26, v1
	v_add_u32_e32 v1, v12, v1
	v_ashrrev_i32_e32 v13, 6, v1
	v_bfe_i32 v1, v12, 27, 1
	v_lshlrev_b32_e32 v0, 4, v12
	v_lshrrev_b32_e32 v1, 22, v1
	v_add_u32_e32 v1, v0, v1
	v_and_b32_e32 v1, 0xfffffc00, v1
	v_sub_u32_e32 v1, v0, v1
	v_lshrrev_b32_e32 v2, 4, v1
	v_bitop3_b32 v1, v2, v1, 32 bitop3:0x6c
	v_ashrrev_i32_e32 v3, 31, v1
	v_lshrrev_b32_e32 v3, 26, v3
	v_add_u32_e32 v3, v1, v3
	v_lshlrev_b32_e32 v2, 3, v13
	v_ashrrev_i32_e32 v14, 6, v3
	v_and_b32_e32 v3, 0xc0, v3
	v_and_b32_e32 v2, -16, v2
	v_sub_u32_e32 v1, v1, v3
	v_mov_b32_e32 v217, 1
	v_add_u32_e32 v2, v14, v2
	v_ashrrev_i16_sdwa v1, v217, sext(v1) dst_sel:DWORD dst_unused:UNUSED_PAD src0_sel:DWORD src1_sel:BYTE_0
	v_lshlrev_b32_e32 v4, 5, v13
	v_bfe_i32 v15, v1, 0, 16
	v_lshlrev_b32_e32 v1, 1, v2
	v_lshrrev_b32_e32 v3, 2, v2
	v_and_b32_e32 v5, 3, v14
	s_mov_b32 s3, 0x1fffe0
	v_and_b32_e32 v4, 32, v4
	v_and_b32_e32 v1, 24, v1
	v_and_b32_e32 v3, 4, v3
	v_and_or_b32 v5, v2, s3, v5
	v_or3_b32 v1, v5, v3, v1
	v_add_lshl_u32 v3, v4, v15, 1
	v_add_u32_e32 v0, 0x2000, v0
	v_lshl_add_u32 v184, v1, 11, v3
	v_ashrrev_i32_e32 v1, 31, v0
	v_lshrrev_b32_e32 v1, 22, v1
	v_add_u32_e32 v1, v0, v1
	v_ashrrev_i32_e32 v16, 10, v1
	v_mul_i32_i24_e32 v1, 0x400, v16
	v_sub_u32_e32 v0, v0, v1
	v_lshrrev_b32_e32 v1, 4, v0
	v_bitop3_b32 v0, v1, v0, 32 bitop3:0x6c
	v_lshl_add_u32 v182, v2, 11, v3
	v_ashrrev_i32_e32 v2, 31, v0
	v_lshrrev_b32_e32 v2, 26, v2
	v_add_u32_e32 v2, v0, v2
	v_lshlrev_b32_e32 v1, 3, v16
	v_ashrrev_i32_e32 v17, 6, v2
	v_and_b32_e32 v2, 0xc0, v2
	v_and_b32_e32 v1, -16, v1
	v_sub_u32_e32 v0, v0, v2
	v_add_u32_e32 v1, v17, v1
	v_ashrrev_i16_sdwa v0, v217, sext(v0) dst_sel:DWORD dst_unused:UNUSED_PAD src0_sel:DWORD src1_sel:BYTE_0
	v_lshlrev_b32_e32 v3, 5, v16
	v_bfe_i32 v18, v0, 0, 16
	v_lshlrev_b32_e32 v0, 1, v1
	v_lshrrev_b32_e32 v2, 2, v1
	v_and_b32_e32 v4, 3, v17
	s_ashr_i32 s8, s10, 6
	v_and_b32_e32 v3, 32, v3
	v_and_b32_e32 v0, 24, v0
	v_and_b32_e32 v2, 4, v2
	v_and_or_b32 v4, v1, s3, v4
	s_ashr_i32 s15, s14, 31
	v_or3_b32 v0, v4, v2, v0
	v_add_lshl_u32 v2, v3, v18, 1
	s_lshl_b32 s3, s8, 10
	s_lshl_b64 s[16:17], s[14:15], 19
	v_lshl_add_u32 v186, v1, 11, v2
	v_lshl_add_u32 v188, v0, 11, v2
	v_lshl_add_u64 v[0:1], v[180:181], 0, s[16:17]
	s_add_i32 s42, s3, 0
	v_mov_b32_e32 v185, 0
	s_add_i32 m0, s42, 0x10000
	v_lshl_add_u64 v[4:5], v[0:1], 0, v[184:185]
	v_mov_b32_e32 v189, v185
	s_mov_b64 s[16:17], 0x40000
	global_load_lds_dwordx4 v[4:5], off
	v_lshl_add_u64 v[6:7], v[0:1], 0, v[188:189]
	s_add_i32 m0, s42, 0x12000
	v_lshl_add_u64 v[2:3], v[0:1], 0, s[16:17]
	s_ashr_i32 s13, s12, 31
	global_load_lds_dwordx4 v[6:7], off
	s_add_i32 m0, s42, 0x14000
	v_lshl_add_u64 v[8:9], v[2:3], 0, v[184:185]
	s_lshl_b64 s[18:19], s[12:13], 19
	global_load_lds_dwordx4 v[8:9], off
	v_lshl_add_u64 v[2:3], v[2:3], 0, v[188:189]
	s_add_i32 m0, s42, 0x16000
	v_mov_b32_e32 v183, v185
	global_load_lds_dwordx4 v[2:3], off
	v_lshl_add_u64 v[2:3], v[178:179], 0, s[18:19]
	v_lshl_add_u64 v[8:9], v[2:3], 0, v[182:183]
	s_mov_b32 m0, s42
	v_mov_b32_e32 v187, v185
	s_add_i32 s43, s42, 0x2000
	global_load_lds_dwordx4 v[8:9], off
	v_lshl_add_u64 v[10:11], v[2:3], 0, v[186:187]
	s_mov_b32 m0, s43
	v_lshl_add_u64 v[20:21], v[2:3], 0, s[16:17]
	s_add_i32 s44, s42, 0x4000
	global_load_lds_dwordx4 v[10:11], off
	v_lshl_add_u64 v[22:23], v[20:21], 0, v[182:183]
	s_mov_b32 m0, s44
	s_add_i32 s45, s42, 0x6000
	global_load_lds_dwordx4 v[22:23], off
	v_lshl_add_u64 v[20:21], v[20:21], 0, v[186:187]
	s_mov_b32 m0, s45
	s_ashr_i32 s70, s10, 8
	global_load_lds_dwordx4 v[20:21], off
	s_cmp_eq_u32 s70, 1
	s_cselect_b64 s[18:19], -1, 0
	s_cmp_lg_u32 s70, 1
	s_mov_b32 s20, 0
	s_cbranch_scc1 .LBB0_1235
	s_barrier
